# GEMM K-loops: LDS-DMA takes its offset VGPR directly (v_mov to v0 per DMA removed) in 9 loops + peeled copies
# speedup vs baseline: 1.0141x; 1.0030x over previous
.LBB0_444:
	s_add_u32 s48, s46, 0x20080
	s_addc_u32 s49, s47, 0
	s_add_u32 s25, s50, 0x100
	s_addc_u32 s64, s51, 0
	s_mov_b32 s65, -2
	s_add_u32 s46, s48, 0xfffe0080
	s_addc_u32 s47, s49, -1
	s_add_i32 s84, 0, 0x10000
	s_cmp_eq_u32 s65, 4
	s_cselect_b32 s47, s15, s47
	s_cselect_b32 s46, s14, s46
	v_add_u32_e32 v0, s84, v147
	s_cselect_b32 s51, s17, s64
	s_cselect_b32 s50, s16, s25
	s_add_i32 s86, 0, 0x14000
	ds_read_b128 v[150:153], v0
	ds_read_b128 v[154:157], v0 offset:1024
	ds_read_b128 v[158:161], v0 offset:2048
	ds_read_b128 v[162:165], v0 offset:3072
	v_add_u32_e32 v0, s86, v147
	ds_read_b128 v[166:169], v0
	ds_read_b128 v[170:173], v0 offset:1024
	ds_read_b128 v[174:177], v0 offset:2048
	ds_read_b128 v[178:181], v0 offset:3072
	ds_read_b128 v[182:185], v148
	ds_read_b128 v[186:189], v148 offset:1024
	ds_read_b128 v[190:193], v148 offset:2048
	ds_read_b128 v[194:197], v148 offset:3072
	ds_read_b128 v[198:201], v148 offset:4096
	ds_read_b128 v[202:205], v148 offset:5120
	ds_read_b128 v[206:209], v148 offset:6144
	ds_read_b128 v[210:213], v148 offset:7168
	s_add_i32 m0, s59, 0xc000
	s_nop 0
	global_load_lds_dwordx4 v132, s[48:49]
	s_add_i32 m0, s59, 0xe000
	s_nop 0
	global_load_lds_dwordx4 v133, s[48:49]
	s_waitcnt vmcnt(8)
	s_waitcnt lgkmcnt(0)
	s_barrier
	s_setprio 1
	s_waitcnt lgkmcnt(0)
	v_mfma_i32_16x16x64_i8 v[126:129], v[150:153], v[182:185], 0
	v_mfma_i32_16x16x64_i8 v[122:125], v[158:161], v[182:185], 0
	v_mfma_i32_16x16x64_i8 v[110:113], v[150:153], v[190:193], 0
	v_mfma_i32_16x16x64_i8 v[106:109], v[158:161], v[190:193], 0
	v_mfma_i32_16x16x64_i8 v[94:97], v[150:153], v[198:201], 0
	v_mfma_i32_16x16x64_i8 v[90:93], v[158:161], v[198:201], 0
	v_mfma_i32_16x16x64_i8 v[78:81], v[150:153], v[206:209], 0
	v_mfma_i32_16x16x64_i8 v[74:77], v[158:161], v[206:209], 0
	v_mfma_i32_16x16x64_i8 v[126:129], v[154:157], v[186:189], v[126:129]
	v_mfma_i32_16x16x64_i8 v[122:125], v[162:165], v[186:189], v[122:125]
	v_mfma_i32_16x16x64_i8 v[110:113], v[154:157], v[194:197], v[110:113]
	v_mfma_i32_16x16x64_i8 v[106:109], v[162:165], v[194:197], v[106:109]
	v_mfma_i32_16x16x64_i8 v[94:97], v[154:157], v[202:205], v[94:97]
	v_mfma_i32_16x16x64_i8 v[90:93], v[162:165], v[202:205], v[90:93]
	v_mfma_i32_16x16x64_i8 v[78:81], v[154:157], v[210:213], v[78:81]
	v_mfma_i32_16x16x64_i8 v[74:77], v[162:165], v[210:213], v[74:77]
	s_setprio 0
	s_setprio 1
	v_mfma_i32_16x16x64_i8 v[118:121], v[166:169], v[182:185], 0
	v_mfma_i32_16x16x64_i8 v[114:117], v[174:177], v[182:185], 0
	v_mfma_i32_16x16x64_i8 v[102:105], v[166:169], v[190:193], 0
	v_mfma_i32_16x16x64_i8 v[98:101], v[174:177], v[190:193], 0
	v_mfma_i32_16x16x64_i8 v[86:89], v[166:169], v[198:201], 0
	v_mfma_i32_16x16x64_i8 v[82:85], v[174:177], v[198:201], 0
	v_mfma_i32_16x16x64_i8 v[70:73], v[166:169], v[206:209], 0
	v_mfma_i32_16x16x64_i8 v[66:69], v[174:177], v[206:209], 0
	v_mfma_i32_16x16x64_i8 v[118:121], v[170:173], v[186:189], v[118:121]
	v_mfma_i32_16x16x64_i8 v[114:117], v[178:181], v[186:189], v[114:117]
	v_mfma_i32_16x16x64_i8 v[102:105], v[170:173], v[194:197], v[102:105]
	v_mfma_i32_16x16x64_i8 v[98:101], v[178:181], v[194:197], v[98:101]
	v_mfma_i32_16x16x64_i8 v[86:89], v[170:173], v[202:205], v[86:89]
	v_mfma_i32_16x16x64_i8 v[82:85], v[178:181], v[202:205], v[82:85]
	v_mfma_i32_16x16x64_i8 v[70:73], v[170:173], v[210:213], v[70:73]
	v_mfma_i32_16x16x64_i8 v[66:69], v[178:181], v[210:213], v[66:69]
	s_setprio 0
	s_barrier
	s_add_i32 s84, s84, s40
	ds_read_b128 v[182:185], v148 offset:16384
	ds_read_b128 v[186:189], v148 offset:17408
	ds_read_b128 v[190:193], v148 offset:18432
	ds_read_b128 v[194:197], v148 offset:19456
	ds_read_b128 v[198:201], v148 offset:20480
	ds_read_b128 v[202:205], v148 offset:21504
	ds_read_b128 v[206:209], v148 offset:22528
	ds_read_b128 v[210:213], v148 offset:23552
	s_mov_b32 m0, s84
	s_nop 0
	global_load_lds_dwordx4 v143, s[50:51]
	s_add_i32 m0, s84, 0x2000
	s_add_u32 s84, s50, 0x20000
	global_load_lds_dwordx4 v144, s[50:51]
	s_addc_u32 s85, s51, 0
	s_add_i32 s86, s86, s40
	s_mov_b32 m0, s86
	s_nop 0
	global_load_lds_dwordx4 v143, s[84:85]
	s_add_i32 m0, s86, 0x2000
	s_nop 0
	global_load_lds_dwordx4 v144, s[84:85]
	s_mov_b32 m0, s59
	s_nop 0
	global_load_lds_dwordx4 v132, s[46:47]
	s_mov_b32 m0, s60
	s_nop 0
	global_load_lds_dwordx4 v133, s[46:47]
	s_waitcnt vmcnt(8)
	s_waitcnt lgkmcnt(0)
	s_barrier
	s_setprio 1
	s_waitcnt lgkmcnt(0)
	v_mfma_i32_16x16x64_i8 v[62:65], v[150:153], v[182:185], 0
	v_mfma_i32_16x16x64_i8 v[58:61], v[158:161], v[182:185], 0
	v_mfma_i32_16x16x64_i8 v[46:49], v[150:153], v[190:193], 0
	v_mfma_i32_16x16x64_i8 v[42:45], v[158:161], v[190:193], 0
	v_mfma_i32_16x16x64_i8 v[30:33], v[150:153], v[198:201], 0
	v_mfma_i32_16x16x64_i8 v[26:29], v[158:161], v[198:201], 0
	v_mfma_i32_16x16x64_i8 v[14:17], v[150:153], v[206:209], 0
	v_mfma_i32_16x16x64_i8 v[10:13], v[158:161], v[206:209], 0
	v_mfma_i32_16x16x64_i8 v[62:65], v[154:157], v[186:189], v[62:65]
	v_mfma_i32_16x16x64_i8 v[58:61], v[162:165], v[186:189], v[58:61]
	v_mfma_i32_16x16x64_i8 v[46:49], v[154:157], v[194:197], v[46:49]
	v_mfma_i32_16x16x64_i8 v[42:45], v[162:165], v[194:197], v[42:45]
	v_mfma_i32_16x16x64_i8 v[30:33], v[154:157], v[202:205], v[30:33]
	v_mfma_i32_16x16x64_i8 v[26:29], v[162:165], v[202:205], v[26:29]
	v_mfma_i32_16x16x64_i8 v[14:17], v[154:157], v[210:213], v[14:17]
	v_mfma_i32_16x16x64_i8 v[10:13], v[162:165], v[210:213], v[10:13]
	s_setprio 0
	s_setprio 1
	v_mfma_i32_16x16x64_i8 v[54:57], v[166:169], v[182:185], 0
	v_mfma_i32_16x16x64_i8 v[50:53], v[174:177], v[182:185], 0
	v_mfma_i32_16x16x64_i8 v[38:41], v[166:169], v[190:193], 0
	v_mfma_i32_16x16x64_i8 v[34:37], v[174:177], v[190:193], 0
	v_mfma_i32_16x16x64_i8 v[22:25], v[166:169], v[198:201], 0
	v_mfma_i32_16x16x64_i8 v[18:21], v[174:177], v[198:201], 0
	v_mfma_i32_16x16x64_i8 v[6:9], v[166:169], v[206:209], 0
	v_mfma_i32_16x16x64_i8 v[2:5], v[174:177], v[206:209], 0
	v_mfma_i32_16x16x64_i8 v[54:57], v[170:173], v[186:189], v[54:57]
	v_mfma_i32_16x16x64_i8 v[50:53], v[178:181], v[186:189], v[50:53]
	v_mfma_i32_16x16x64_i8 v[38:41], v[170:173], v[194:197], v[38:41]
	v_mfma_i32_16x16x64_i8 v[34:37], v[178:181], v[194:197], v[34:37]
	v_mfma_i32_16x16x64_i8 v[22:25], v[170:173], v[202:205], v[22:25]
	v_mfma_i32_16x16x64_i8 v[18:21], v[178:181], v[202:205], v[18:21]
	v_mfma_i32_16x16x64_i8 v[6:9], v[170:173], v[210:213], v[6:9]
	v_mfma_i32_16x16x64_i8 v[2:5], v[178:181], v[210:213], v[2:5]
	s_setprio 0
	s_barrier
	s_add_i32 s86, 0, 0x18000
	v_add_u32_e32 v0, s86, v147
	s_add_i32 s87, 0, 0x1c000
	ds_read_b128 v[150:153], v0
	ds_read_b128 v[154:157], v0 offset:1024
	ds_read_b128 v[158:161], v0 offset:2048
	ds_read_b128 v[162:165], v0 offset:3072
	v_add_u32_e32 v0, s87, v147
	ds_read_b128 v[166:169], v0
	ds_read_b128 v[170:173], v0 offset:1024
	ds_read_b128 v[174:177], v0 offset:2048
	ds_read_b128 v[178:181], v0 offset:3072
	s_add_u32 s84, s46, 0x20000
	s_mov_b32 m0, s61
	ds_read_b128 v[182:185], v148 offset:32768
	ds_read_b128 v[186:189], v148 offset:33792
	ds_read_b128 v[190:193], v148 offset:34816
	ds_read_b128 v[194:197], v148 offset:35840
	ds_read_b128 v[198:201], v148 offset:36864
	ds_read_b128 v[202:205], v148 offset:37888
	ds_read_b128 v[206:209], v148 offset:38912
	ds_read_b128 v[210:213], v148 offset:39936
	s_addc_u32 s85, s47, 0
	s_nop 0
	global_load_lds_dwordx4 v132, s[84:85]
	s_mov_b32 m0, s66
	s_nop 0
	global_load_lds_dwordx4 v133, s[84:85]
	s_waitcnt vmcnt(8)
	s_waitcnt lgkmcnt(0)
	s_barrier
	s_setprio 1
	s_waitcnt lgkmcnt(0)
	v_mfma_i32_16x16x64_i8 v[126:129], v[150:153], v[182:185], v[126:129]
	v_mfma_i32_16x16x64_i8 v[122:125], v[158:161], v[182:185], v[122:125]
	v_mfma_i32_16x16x64_i8 v[110:113], v[150:153], v[190:193], v[110:113]
	v_mfma_i32_16x16x64_i8 v[106:109], v[158:161], v[190:193], v[106:109]
	v_mfma_i32_16x16x64_i8 v[94:97], v[150:153], v[198:201], v[94:97]
	v_mfma_i32_16x16x64_i8 v[90:93], v[158:161], v[198:201], v[90:93]
	v_mfma_i32_16x16x64_i8 v[78:81], v[150:153], v[206:209], v[78:81]
	v_mfma_i32_16x16x64_i8 v[74:77], v[158:161], v[206:209], v[74:77]
	v_mfma_i32_16x16x64_i8 v[126:129], v[154:157], v[186:189], v[126:129]
	v_mfma_i32_16x16x64_i8 v[122:125], v[162:165], v[186:189], v[122:125]
	v_mfma_i32_16x16x64_i8 v[110:113], v[154:157], v[194:197], v[110:113]
	v_mfma_i32_16x16x64_i8 v[106:109], v[162:165], v[194:197], v[106:109]
	v_mfma_i32_16x16x64_i8 v[94:97], v[154:157], v[202:205], v[94:97]
	v_mfma_i32_16x16x64_i8 v[90:93], v[162:165], v[202:205], v[90:93]
	v_mfma_i32_16x16x64_i8 v[78:81], v[154:157], v[210:213], v[78:81]
	v_mfma_i32_16x16x64_i8 v[74:77], v[162:165], v[210:213], v[74:77]
	s_setprio 0
	s_setprio 1
	v_mfma_i32_16x16x64_i8 v[118:121], v[166:169], v[182:185], v[118:121]
	v_mfma_i32_16x16x64_i8 v[114:117], v[174:177], v[182:185], v[114:117]
	v_mfma_i32_16x16x64_i8 v[102:105], v[166:169], v[190:193], v[102:105]
	v_mfma_i32_16x16x64_i8 v[98:101], v[174:177], v[190:193], v[98:101]
	v_mfma_i32_16x16x64_i8 v[86:89], v[166:169], v[198:201], v[86:89]
	v_mfma_i32_16x16x64_i8 v[82:85], v[174:177], v[198:201], v[82:85]
	v_mfma_i32_16x16x64_i8 v[70:73], v[166:169], v[206:209], v[70:73]
	v_mfma_i32_16x16x64_i8 v[66:69], v[174:177], v[206:209], v[66:69]
	v_mfma_i32_16x16x64_i8 v[118:121], v[170:173], v[186:189], v[118:121]
	v_mfma_i32_16x16x64_i8 v[114:117], v[178:181], v[186:189], v[114:117]
	v_mfma_i32_16x16x64_i8 v[102:105], v[170:173], v[194:197], v[102:105]
	v_mfma_i32_16x16x64_i8 v[98:101], v[178:181], v[194:197], v[98:101]
	v_mfma_i32_16x16x64_i8 v[86:89], v[170:173], v[202:205], v[86:89]
	v_mfma_i32_16x16x64_i8 v[82:85], v[178:181], v[202:205], v[82:85]
	v_mfma_i32_16x16x64_i8 v[70:73], v[170:173], v[210:213], v[70:73]
	v_mfma_i32_16x16x64_i8 v[66:69], v[178:181], v[210:213], v[66:69]
	s_setprio 0
	s_barrier
	v_mov_b32_e32 v0, v143
	ds_read_b128 v[182:185], v148 offset:49152
	ds_read_b128 v[186:189], v148 offset:50176
	ds_read_b128 v[190:193], v148 offset:51200
	ds_read_b128 v[194:197], v148 offset:52224
	ds_read_b128 v[198:201], v148 offset:53248
	ds_read_b128 v[202:205], v148 offset:54272
	ds_read_b128 v[206:209], v148 offset:55296
	ds_read_b128 v[210:213], v148 offset:56320
	s_add_i32 s84, s86, s40
	v_lshl_add_u64 v[130:131], s[50:51], 0, v[0:1]
	v_lshl_add_u64 v[130:131], v[130:131], 0, s[38:39]
	s_mov_b32 m0, s84
	v_mov_b32_e32 v0, v144
	global_load_lds_dwordx4 v[130:131], off
	s_add_i32 m0, s84, 0x2000
	s_nop 0
	v_lshl_add_u64 v[130:131], s[50:51], 0, v[0:1]
	s_add_u32 s50, s50, 0x20080
	v_lshl_add_u64 v[130:131], v[130:131], 0, s[38:39]
	s_addc_u32 s51, s51, 0
	s_add_i32 s84, s87, s40
	global_load_lds_dwordx4 v[130:131], off
	s_mov_b32 m0, s84
	s_nop 0
	global_load_lds_dwordx4 v143, s[50:51]
	s_add_i32 m0, s84, 0x2000
	s_nop 0
	global_load_lds_dwordx4 v144, s[50:51]
	v_mov_b32_e32 v0, v132
	s_mov_b32 m0, s75
	v_lshl_add_u64 v[130:131], s[46:47], 0, v[0:1]
	v_lshl_add_u64 v[130:131], v[130:131], 0, s[38:39]
	v_mov_b32_e32 v0, v133
	global_load_lds_dwordx4 v[130:131], off
	s_mov_b32 m0, s78
	v_lshl_add_u64 v[130:131], s[46:47], 0, v[0:1]
	v_lshl_add_u64 v[130:131], v[130:131], 0, s[38:39]
	global_load_lds_dwordx4 v[130:131], off
	s_waitcnt vmcnt(8)
	s_waitcnt lgkmcnt(0)
	s_barrier
	s_setprio 1
	s_waitcnt lgkmcnt(0)
	v_mfma_i32_16x16x64_i8 v[62:65], v[150:153], v[182:185], v[62:65]
	v_mfma_i32_16x16x64_i8 v[58:61], v[158:161], v[182:185], v[58:61]
	v_mfma_i32_16x16x64_i8 v[46:49], v[150:153], v[190:193], v[46:49]
	v_mfma_i32_16x16x64_i8 v[42:45], v[158:161], v[190:193], v[42:45]
	v_mfma_i32_16x16x64_i8 v[30:33], v[150:153], v[198:201], v[30:33]
	v_mfma_i32_16x16x64_i8 v[26:29], v[158:161], v[198:201], v[26:29]
	v_mfma_i32_16x16x64_i8 v[14:17], v[150:153], v[206:209], v[14:17]
	v_mfma_i32_16x16x64_i8 v[10:13], v[158:161], v[206:209], v[10:13]
	v_mfma_i32_16x16x64_i8 v[62:65], v[154:157], v[186:189], v[62:65]
	v_mfma_i32_16x16x64_i8 v[58:61], v[162:165], v[186:189], v[58:61]
	v_mfma_i32_16x16x64_i8 v[46:49], v[154:157], v[194:197], v[46:49]
	v_mfma_i32_16x16x64_i8 v[42:45], v[162:165], v[194:197], v[42:45]
	v_mfma_i32_16x16x64_i8 v[30:33], v[154:157], v[202:205], v[30:33]
	v_mfma_i32_16x16x64_i8 v[26:29], v[162:165], v[202:205], v[26:29]
	v_mfma_i32_16x16x64_i8 v[14:17], v[154:157], v[210:213], v[14:17]
	v_mfma_i32_16x16x64_i8 v[10:13], v[162:165], v[210:213], v[10:13]
	s_setprio 0
	s_setprio 1
	v_mfma_i32_16x16x64_i8 v[54:57], v[166:169], v[182:185], v[54:57]
	v_mfma_i32_16x16x64_i8 v[50:53], v[174:177], v[182:185], v[50:53]
	v_mfma_i32_16x16x64_i8 v[38:41], v[166:169], v[190:193], v[38:41]
	v_mfma_i32_16x16x64_i8 v[34:37], v[174:177], v[190:193], v[34:37]
	v_mfma_i32_16x16x64_i8 v[22:25], v[166:169], v[198:201], v[22:25]
	v_mfma_i32_16x16x64_i8 v[18:21], v[174:177], v[198:201], v[18:21]
	v_mfma_i32_16x16x64_i8 v[6:9], v[166:169], v[206:209], v[6:9]
	v_mfma_i32_16x16x64_i8 v[2:5], v[174:177], v[206:209], v[2:5]
	v_mfma_i32_16x16x64_i8 v[54:57], v[170:173], v[186:189], v[54:57]
	v_mfma_i32_16x16x64_i8 v[50:53], v[178:181], v[186:189], v[50:53]
	v_mfma_i32_16x16x64_i8 v[38:41], v[170:173], v[194:197], v[38:41]
	v_mfma_i32_16x16x64_i8 v[34:37], v[178:181], v[194:197], v[34:37]
	v_mfma_i32_16x16x64_i8 v[22:25], v[170:173], v[202:205], v[22:25]
	v_mfma_i32_16x16x64_i8 v[18:21], v[178:181], v[202:205], v[18:21]
	v_mfma_i32_16x16x64_i8 v[6:9], v[170:173], v[210:213], v[6:9]
	v_mfma_i32_16x16x64_i8 v[2:5], v[178:181], v[210:213], v[2:5]
	s_setprio 0
	s_barrier
	s_add_i32 s65, s65, 2
	s_add_u32 s48, s48, 0x100
	s_addc_u32 s49, s49, 0
	s_add_u32 s25, s25, 0x100
	s_addc_u32 s64, s64, 0
	s_cmp_gt_u32 s65, 5
	s_cbranch_scc0 .LBB0_445
	s_branch .Lpeel_exit_445
.LBB0_445:
	s_add_u32 s46, s48, 0xfffe0080
	s_addc_u32 s47, s49, -1
	s_add_i32 s84, 0, 0x10000
	s_cmp_eq_u32 s65, 4
	s_cselect_b32 s47, s15, s47
	s_cselect_b32 s46, s14, s46
	v_add_u32_e32 v0, s84, v147
	s_cselect_b32 s51, s17, s64
	s_cselect_b32 s50, s16, s25
	s_add_i32 s86, 0, 0x14000
	ds_read_b128 v[150:153], v0
	ds_read_b128 v[154:157], v0 offset:1024
	ds_read_b128 v[158:161], v0 offset:2048
	ds_read_b128 v[162:165], v0 offset:3072
	v_add_u32_e32 v0, s86, v147
	ds_read_b128 v[166:169], v0
	ds_read_b128 v[170:173], v0 offset:1024
	ds_read_b128 v[174:177], v0 offset:2048
	ds_read_b128 v[178:181], v0 offset:3072
	ds_read_b128 v[182:185], v148
	ds_read_b128 v[186:189], v148 offset:1024
	ds_read_b128 v[190:193], v148 offset:2048
	ds_read_b128 v[194:197], v148 offset:3072
	ds_read_b128 v[198:201], v148 offset:4096
	ds_read_b128 v[202:205], v148 offset:5120
	ds_read_b128 v[206:209], v148 offset:6144
	ds_read_b128 v[210:213], v148 offset:7168
	s_add_i32 m0, s59, 0xc000
	s_nop 0
	global_load_lds_dwordx4 v132, s[48:49]
	s_add_i32 m0, s59, 0xe000
	s_nop 0
	global_load_lds_dwordx4 v133, s[48:49]
	s_waitcnt vmcnt(8)
	s_waitcnt lgkmcnt(0)
	s_barrier
	s_setprio 1
	s_waitcnt lgkmcnt(0)
	v_mfma_i32_16x16x64_i8 v[126:129], v[150:153], v[182:185], v[126:129]
	v_mfma_i32_16x16x64_i8 v[122:125], v[158:161], v[182:185], v[122:125]
	v_mfma_i32_16x16x64_i8 v[110:113], v[150:153], v[190:193], v[110:113]
	v_mfma_i32_16x16x64_i8 v[106:109], v[158:161], v[190:193], v[106:109]
	v_mfma_i32_16x16x64_i8 v[94:97], v[150:153], v[198:201], v[94:97]
	v_mfma_i32_16x16x64_i8 v[90:93], v[158:161], v[198:201], v[90:93]
	v_mfma_i32_16x16x64_i8 v[78:81], v[150:153], v[206:209], v[78:81]
	v_mfma_i32_16x16x64_i8 v[74:77], v[158:161], v[206:209], v[74:77]
	v_mfma_i32_16x16x64_i8 v[126:129], v[154:157], v[186:189], v[126:129]
	v_mfma_i32_16x16x64_i8 v[122:125], v[162:165], v[186:189], v[122:125]
	v_mfma_i32_16x16x64_i8 v[110:113], v[154:157], v[194:197], v[110:113]
	v_mfma_i32_16x16x64_i8 v[106:109], v[162:165], v[194:197], v[106:109]
	v_mfma_i32_16x16x64_i8 v[94:97], v[154:157], v[202:205], v[94:97]
	v_mfma_i32_16x16x64_i8 v[90:93], v[162:165], v[202:205], v[90:93]
	v_mfma_i32_16x16x64_i8 v[78:81], v[154:157], v[210:213], v[78:81]
	v_mfma_i32_16x16x64_i8 v[74:77], v[162:165], v[210:213], v[74:77]
	s_setprio 0
	s_setprio 1
	v_mfma_i32_16x16x64_i8 v[118:121], v[166:169], v[182:185], v[118:121]
	v_mfma_i32_16x16x64_i8 v[114:117], v[174:177], v[182:185], v[114:117]
	v_mfma_i32_16x16x64_i8 v[102:105], v[166:169], v[190:193], v[102:105]
	v_mfma_i32_16x16x64_i8 v[98:101], v[174:177], v[190:193], v[98:101]
	v_mfma_i32_16x16x64_i8 v[86:89], v[166:169], v[198:201], v[86:89]
	v_mfma_i32_16x16x64_i8 v[82:85], v[174:177], v[198:201], v[82:85]
	v_mfma_i32_16x16x64_i8 v[70:73], v[166:169], v[206:209], v[70:73]
	v_mfma_i32_16x16x64_i8 v[66:69], v[174:177], v[206:209], v[66:69]
	v_mfma_i32_16x16x64_i8 v[118:121], v[170:173], v[186:189], v[118:121]
	v_mfma_i32_16x16x64_i8 v[114:117], v[178:181], v[186:189], v[114:117]
	v_mfma_i32_16x16x64_i8 v[102:105], v[170:173], v[194:197], v[102:105]
	v_mfma_i32_16x16x64_i8 v[98:101], v[178:181], v[194:197], v[98:101]
	v_mfma_i32_16x16x64_i8 v[86:89], v[170:173], v[202:205], v[86:89]
	v_mfma_i32_16x16x64_i8 v[82:85], v[178:181], v[202:205], v[82:85]
	v_mfma_i32_16x16x64_i8 v[70:73], v[170:173], v[210:213], v[70:73]
	v_mfma_i32_16x16x64_i8 v[66:69], v[178:181], v[210:213], v[66:69]
	s_setprio 0
	s_barrier
	s_add_i32 s84, s84, s40
	ds_read_b128 v[182:185], v148 offset:16384
	ds_read_b128 v[186:189], v148 offset:17408
	ds_read_b128 v[190:193], v148 offset:18432
	ds_read_b128 v[194:197], v148 offset:19456
	ds_read_b128 v[198:201], v148 offset:20480
	ds_read_b128 v[202:205], v148 offset:21504
	ds_read_b128 v[206:209], v148 offset:22528
	ds_read_b128 v[210:213], v148 offset:23552
	s_mov_b32 m0, s84
	s_nop 0
	global_load_lds_dwordx4 v143, s[50:51]
	s_add_i32 m0, s84, 0x2000
	s_add_u32 s84, s50, 0x20000
	global_load_lds_dwordx4 v144, s[50:51]
	s_addc_u32 s85, s51, 0
	s_add_i32 s86, s86, s40
	s_mov_b32 m0, s86
	s_nop 0
	global_load_lds_dwordx4 v143, s[84:85]
	s_add_i32 m0, s86, 0x2000
	s_nop 0
	global_load_lds_dwordx4 v144, s[84:85]
	s_mov_b32 m0, s59
	s_nop 0
	global_load_lds_dwordx4 v132, s[46:47]
	s_mov_b32 m0, s60
	s_nop 0
	global_load_lds_dwordx4 v133, s[46:47]
	s_waitcnt vmcnt(8)
	s_waitcnt lgkmcnt(0)
	s_barrier
	s_setprio 1
	s_waitcnt lgkmcnt(0)
	v_mfma_i32_16x16x64_i8 v[62:65], v[150:153], v[182:185], v[62:65]
	v_mfma_i32_16x16x64_i8 v[58:61], v[158:161], v[182:185], v[58:61]
	v_mfma_i32_16x16x64_i8 v[46:49], v[150:153], v[190:193], v[46:49]
	v_mfma_i32_16x16x64_i8 v[42:45], v[158:161], v[190:193], v[42:45]
	v_mfma_i32_16x16x64_i8 v[30:33], v[150:153], v[198:201], v[30:33]
	v_mfma_i32_16x16x64_i8 v[26:29], v[158:161], v[198:201], v[26:29]
	v_mfma_i32_16x16x64_i8 v[14:17], v[150:153], v[206:209], v[14:17]
	v_mfma_i32_16x16x64_i8 v[10:13], v[158:161], v[206:209], v[10:13]
	v_mfma_i32_16x16x64_i8 v[62:65], v[154:157], v[186:189], v[62:65]
	v_mfma_i32_16x16x64_i8 v[58:61], v[162:165], v[186:189], v[58:61]
	v_mfma_i32_16x16x64_i8 v[46:49], v[154:157], v[194:197], v[46:49]
	v_mfma_i32_16x16x64_i8 v[42:45], v[162:165], v[194:197], v[42:45]
	v_mfma_i32_16x16x64_i8 v[30:33], v[154:157], v[202:205], v[30:33]
	v_mfma_i32_16x16x64_i8 v[26:29], v[162:165], v[202:205], v[26:29]
	v_mfma_i32_16x16x64_i8 v[14:17], v[154:157], v[210:213], v[14:17]
	v_mfma_i32_16x16x64_i8 v[10:13], v[162:165], v[210:213], v[10:13]
	s_setprio 0
	s_setprio 1
	v_mfma_i32_16x16x64_i8 v[54:57], v[166:169], v[182:185], v[54:57]
	v_mfma_i32_16x16x64_i8 v[50:53], v[174:177], v[182:185], v[50:53]
	v_mfma_i32_16x16x64_i8 v[38:41], v[166:169], v[190:193], v[38:41]
	v_mfma_i32_16x16x64_i8 v[34:37], v[174:177], v[190:193], v[34:37]
	v_mfma_i32_16x16x64_i8 v[22:25], v[166:169], v[198:201], v[22:25]
	v_mfma_i32_16x16x64_i8 v[18:21], v[174:177], v[198:201], v[18:21]
	v_mfma_i32_16x16x64_i8 v[6:9], v[166:169], v[206:209], v[6:9]
	v_mfma_i32_16x16x64_i8 v[2:5], v[174:177], v[206:209], v[2:5]
	v_mfma_i32_16x16x64_i8 v[54:57], v[170:173], v[186:189], v[54:57]
	v_mfma_i32_16x16x64_i8 v[50:53], v[178:181], v[186:189], v[50:53]
	v_mfma_i32_16x16x64_i8 v[38:41], v[170:173], v[194:197], v[38:41]
	v_mfma_i32_16x16x64_i8 v[34:37], v[178:181], v[194:197], v[34:37]
	v_mfma_i32_16x16x64_i8 v[22:25], v[170:173], v[202:205], v[22:25]
	v_mfma_i32_16x16x64_i8 v[18:21], v[178:181], v[202:205], v[18:21]
	v_mfma_i32_16x16x64_i8 v[6:9], v[170:173], v[210:213], v[6:9]
	v_mfma_i32_16x16x64_i8 v[2:5], v[178:181], v[210:213], v[2:5]
	s_setprio 0
	s_barrier
	s_add_i32 s86, 0, 0x18000
	v_add_u32_e32 v0, s86, v147
	s_add_i32 s87, 0, 0x1c000
	ds_read_b128 v[150:153], v0
	ds_read_b128 v[154:157], v0 offset:1024
	ds_read_b128 v[158:161], v0 offset:2048
	ds_read_b128 v[162:165], v0 offset:3072
	v_add_u32_e32 v0, s87, v147
	ds_read_b128 v[166:169], v0
	ds_read_b128 v[170:173], v0 offset:1024
	ds_read_b128 v[174:177], v0 offset:2048
	ds_read_b128 v[178:181], v0 offset:3072
	s_add_u32 s84, s46, 0x20000
	s_mov_b32 m0, s61
	ds_read_b128 v[182:185], v148 offset:32768
	ds_read_b128 v[186:189], v148 offset:33792
	ds_read_b128 v[190:193], v148 offset:34816
	ds_read_b128 v[194:197], v148 offset:35840
	ds_read_b128 v[198:201], v148 offset:36864
	ds_read_b128 v[202:205], v148 offset:37888
	ds_read_b128 v[206:209], v148 offset:38912
	ds_read_b128 v[210:213], v148 offset:39936
	s_addc_u32 s85, s47, 0
	s_nop 0
	global_load_lds_dwordx4 v132, s[84:85]
	s_mov_b32 m0, s66
	s_nop 0
	global_load_lds_dwordx4 v133, s[84:85]
	s_waitcnt vmcnt(8)
	s_waitcnt lgkmcnt(0)
	s_barrier
	s_setprio 1
	s_waitcnt lgkmcnt(0)
	v_mfma_i32_16x16x64_i8 v[126:129], v[150:153], v[182:185], v[126:129]
	v_mfma_i32_16x16x64_i8 v[122:125], v[158:161], v[182:185], v[122:125]
	v_mfma_i32_16x16x64_i8 v[110:113], v[150:153], v[190:193], v[110:113]
	v_mfma_i32_16x16x64_i8 v[106:109], v[158:161], v[190:193], v[106:109]
	v_mfma_i32_16x16x64_i8 v[94:97], v[150:153], v[198:201], v[94:97]
	v_mfma_i32_16x16x64_i8 v[90:93], v[158:161], v[198:201], v[90:93]
	v_mfma_i32_16x16x64_i8 v[78:81], v[150:153], v[206:209], v[78:81]
	v_mfma_i32_16x16x64_i8 v[74:77], v[158:161], v[206:209], v[74:77]
	v_mfma_i32_16x16x64_i8 v[126:129], v[154:157], v[186:189], v[126:129]
	v_mfma_i32_16x16x64_i8 v[122:125], v[162:165], v[186:189], v[122:125]
	v_mfma_i32_16x16x64_i8 v[110:113], v[154:157], v[194:197], v[110:113]
	v_mfma_i32_16x16x64_i8 v[106:109], v[162:165], v[194:197], v[106:109]
	v_mfma_i32_16x16x64_i8 v[94:97], v[154:157], v[202:205], v[94:97]
	v_mfma_i32_16x16x64_i8 v[90:93], v[162:165], v[202:205], v[90:93]
	v_mfma_i32_16x16x64_i8 v[78:81], v[154:157], v[210:213], v[78:81]
	v_mfma_i32_16x16x64_i8 v[74:77], v[162:165], v[210:213], v[74:77]
	s_setprio 0
	s_setprio 1
	v_mfma_i32_16x16x64_i8 v[118:121], v[166:169], v[182:185], v[118:121]
	v_mfma_i32_16x16x64_i8 v[114:117], v[174:177], v[182:185], v[114:117]
	v_mfma_i32_16x16x64_i8 v[102:105], v[166:169], v[190:193], v[102:105]
	v_mfma_i32_16x16x64_i8 v[98:101], v[174:177], v[190:193], v[98:101]
	v_mfma_i32_16x16x64_i8 v[86:89], v[166:169], v[198:201], v[86:89]
	v_mfma_i32_16x16x64_i8 v[82:85], v[174:177], v[198:201], v[82:85]
	v_mfma_i32_16x16x64_i8 v[70:73], v[166:169], v[206:209], v[70:73]
	v_mfma_i32_16x16x64_i8 v[66:69], v[174:177], v[206:209], v[66:69]
	v_mfma_i32_16x16x64_i8 v[118:121], v[170:173], v[186:189], v[118:121]
	v_mfma_i32_16x16x64_i8 v[114:117], v[178:181], v[186:189], v[114:117]
	v_mfma_i32_16x16x64_i8 v[102:105], v[170:173], v[194:197], v[102:105]
	v_mfma_i32_16x16x64_i8 v[98:101], v[178:181], v[194:197], v[98:101]
	v_mfma_i32_16x16x64_i8 v[86:89], v[170:173], v[202:205], v[86:89]
	v_mfma_i32_16x16x64_i8 v[82:85], v[178:181], v[202:205], v[82:85]
	v_mfma_i32_16x16x64_i8 v[70:73], v[170:173], v[210:213], v[70:73]
	v_mfma_i32_16x16x64_i8 v[66:69], v[178:181], v[210:213], v[66:69]
	s_setprio 0
	s_barrier
	v_mov_b32_e32 v0, v143
	ds_read_b128 v[182:185], v148 offset:49152
	ds_read_b128 v[186:189], v148 offset:50176
	ds_read_b128 v[190:193], v148 offset:51200
	ds_read_b128 v[194:197], v148 offset:52224
	ds_read_b128 v[198:201], v148 offset:53248
	ds_read_b128 v[202:205], v148 offset:54272
	ds_read_b128 v[206:209], v148 offset:55296
	ds_read_b128 v[210:213], v148 offset:56320
	s_add_i32 s84, s86, s40
	v_lshl_add_u64 v[130:131], s[50:51], 0, v[0:1]
	v_lshl_add_u64 v[130:131], v[130:131], 0, s[38:39]
	s_mov_b32 m0, s84
	v_mov_b32_e32 v0, v144
	global_load_lds_dwordx4 v[130:131], off
	s_add_i32 m0, s84, 0x2000
	s_nop 0
	v_lshl_add_u64 v[130:131], s[50:51], 0, v[0:1]
	s_add_u32 s50, s50, 0x20080
	v_lshl_add_u64 v[130:131], v[130:131], 0, s[38:39]
	s_addc_u32 s51, s51, 0
	s_add_i32 s84, s87, s40
	global_load_lds_dwordx4 v[130:131], off
	s_mov_b32 m0, s84
	s_nop 0
	global_load_lds_dwordx4 v143, s[50:51]
	s_add_i32 m0, s84, 0x2000
	s_nop 0
	global_load_lds_dwordx4 v144, s[50:51]
	v_mov_b32_e32 v0, v132
	s_mov_b32 m0, s75
	v_lshl_add_u64 v[130:131], s[46:47], 0, v[0:1]
	v_lshl_add_u64 v[130:131], v[130:131], 0, s[38:39]
	v_mov_b32_e32 v0, v133
	global_load_lds_dwordx4 v[130:131], off
	s_mov_b32 m0, s78
	v_lshl_add_u64 v[130:131], s[46:47], 0, v[0:1]
	v_lshl_add_u64 v[130:131], v[130:131], 0, s[38:39]
	global_load_lds_dwordx4 v[130:131], off
	s_waitcnt vmcnt(8)
	s_waitcnt lgkmcnt(0)
	s_barrier
	s_setprio 1
	s_waitcnt lgkmcnt(0)
	v_mfma_i32_16x16x64_i8 v[62:65], v[150:153], v[182:185], v[62:65]
	v_mfma_i32_16x16x64_i8 v[58:61], v[158:161], v[182:185], v[58:61]
	v_mfma_i32_16x16x64_i8 v[46:49], v[150:153], v[190:193], v[46:49]
	v_mfma_i32_16x16x64_i8 v[42:45], v[158:161], v[190:193], v[42:45]
	v_mfma_i32_16x16x64_i8 v[30:33], v[150:153], v[198:201], v[30:33]
	v_mfma_i32_16x16x64_i8 v[26:29], v[158:161], v[198:201], v[26:29]
	v_mfma_i32_16x16x64_i8 v[14:17], v[150:153], v[206:209], v[14:17]
	v_mfma_i32_16x16x64_i8 v[10:13], v[158:161], v[206:209], v[10:13]
	v_mfma_i32_16x16x64_i8 v[62:65], v[154:157], v[186:189], v[62:65]
	v_mfma_i32_16x16x64_i8 v[58:61], v[162:165], v[186:189], v[58:61]
	v_mfma_i32_16x16x64_i8 v[46:49], v[154:157], v[194:197], v[46:49]
	v_mfma_i32_16x16x64_i8 v[42:45], v[162:165], v[194:197], v[42:45]
	v_mfma_i32_16x16x64_i8 v[30:33], v[154:157], v[202:205], v[30:33]
	v_mfma_i32_16x16x64_i8 v[26:29], v[162:165], v[202:205], v[26:29]
	v_mfma_i32_16x16x64_i8 v[14:17], v[154:157], v[210:213], v[14:17]
	v_mfma_i32_16x16x64_i8 v[10:13], v[162:165], v[210:213], v[10:13]
	s_setprio 0
	s_setprio 1
	v_mfma_i32_16x16x64_i8 v[54:57], v[166:169], v[182:185], v[54:57]
	v_mfma_i32_16x16x64_i8 v[50:53], v[174:177], v[182:185], v[50:53]
	v_mfma_i32_16x16x64_i8 v[38:41], v[166:169], v[190:193], v[38:41]
	v_mfma_i32_16x16x64_i8 v[34:37], v[174:177], v[190:193], v[34:37]
	v_mfma_i32_16x16x64_i8 v[22:25], v[166:169], v[198:201], v[22:25]
	v_mfma_i32_16x16x64_i8 v[18:21], v[174:177], v[198:201], v[18:21]
	v_mfma_i32_16x16x64_i8 v[6:9], v[166:169], v[206:209], v[6:9]
	v_mfma_i32_16x16x64_i8 v[2:5], v[174:177], v[206:209], v[2:5]
	v_mfma_i32_16x16x64_i8 v[54:57], v[170:173], v[186:189], v[54:57]
	v_mfma_i32_16x16x64_i8 v[50:53], v[178:181], v[186:189], v[50:53]
	v_mfma_i32_16x16x64_i8 v[38:41], v[170:173], v[194:197], v[38:41]
	v_mfma_i32_16x16x64_i8 v[34:37], v[178:181], v[194:197], v[34:37]
	v_mfma_i32_16x16x64_i8 v[22:25], v[170:173], v[202:205], v[22:25]
	v_mfma_i32_16x16x64_i8 v[18:21], v[178:181], v[202:205], v[18:21]
	v_mfma_i32_16x16x64_i8 v[6:9], v[170:173], v[210:213], v[6:9]
	v_mfma_i32_16x16x64_i8 v[2:5], v[178:181], v[210:213], v[2:5]
	s_setprio 0
	s_barrier
	s_add_i32 s65, s65, 2
	s_add_u32 s48, s48, 0x100
	s_addc_u32 s49, s49, 0
	s_add_u32 s25, s25, 0x100
	s_addc_u32 s64, s64, 0
	s_cmp_gt_u32 s65, 5
	s_cbranch_scc0 .LBB0_445

.LBB0_667:
	s_add_u32 s4, s70, s50
	s_addc_u32 s5, s71, s51
	s_add_u32 s46, s4, 0x9400100
	s_addc_u32 s47, s5, 0
	s_add_u32 s58, s74, s50
	s_addc_u32 s59, s75, s51
	s_add_i32 s77, 0, 0x10000
	s_cmpk_eq_i32 s50, 0x300
	s_cselect_b32 s47, s23, s47
	s_cselect_b32 s46, s22, s46
	v_add_u32_e32 v0, s77, v144
	s_cselect_b32 s59, s49, s59
	s_cselect_b32 s58, s48, s58
	s_add_i32 s78, 0, 0x14000
	ds_read_b128 v[146:149], v0
	ds_read_b128 v[150:153], v0 offset:1024
	ds_read_b128 v[154:157], v0 offset:2048
	ds_read_b128 v[158:161], v0 offset:3072
	v_add_u32_e32 v0, s78, v144
	ds_read_b128 v[162:165], v0
	ds_read_b128 v[166:169], v0 offset:1024
	ds_read_b128 v[170:173], v0 offset:2048
	ds_read_b128 v[174:177], v0 offset:3072
	v_mov_b32_e32 v0, v130
	ds_read_b128 v[178:181], v145
	ds_read_b128 v[182:185], v145 offset:1024
	ds_read_b128 v[186:189], v145 offset:2048
	ds_read_b128 v[190:193], v145 offset:3072
	ds_read_b128 v[194:197], v145 offset:4096
	ds_read_b128 v[198:201], v145 offset:5120
	ds_read_b128 v[202:205], v145 offset:6144
	ds_read_b128 v[206:209], v145 offset:7168
	s_add_i32 m0, s61, 0xc000
	v_lshl_add_u64 v[210:211], s[4:5], 0, v[0:1]
	v_lshl_add_u64 v[210:211], v[210:211], 0, s[54:55]
	v_mov_b32_e32 v0, v141
	global_load_lds_dwordx4 v[210:211], off
	s_add_i32 m0, s61, 0xe000
	v_lshl_add_u64 v[210:211], s[4:5], 0, v[0:1]
	v_lshl_add_u64 v[210:211], v[210:211], 0, s[54:55]
	global_load_lds_dwordx4 v[210:211], off
	s_waitcnt vmcnt(8)
	s_waitcnt lgkmcnt(0)
	s_barrier
	s_setprio 1
	s_waitcnt lgkmcnt(0)
	v_mfma_i32_16x16x64_i8 v[126:129], v[146:149], v[178:181], v[126:129]
	v_mfma_i32_16x16x64_i8 v[122:125], v[154:157], v[178:181], v[122:125]
	v_mfma_i32_16x16x64_i8 v[110:113], v[146:149], v[186:189], v[110:113]
	v_mfma_i32_16x16x64_i8 v[106:109], v[154:157], v[186:189], v[106:109]
	v_mfma_i32_16x16x64_i8 v[94:97], v[146:149], v[194:197], v[94:97]
	v_mfma_i32_16x16x64_i8 v[90:93], v[154:157], v[194:197], v[90:93]
	v_mfma_i32_16x16x64_i8 v[78:81], v[146:149], v[202:205], v[78:81]
	v_mfma_i32_16x16x64_i8 v[74:77], v[154:157], v[202:205], v[74:77]
	v_mfma_i32_16x16x64_i8 v[126:129], v[150:153], v[182:185], v[126:129]
	v_mfma_i32_16x16x64_i8 v[122:125], v[158:161], v[182:185], v[122:125]
	v_mfma_i32_16x16x64_i8 v[110:113], v[150:153], v[190:193], v[110:113]
	v_mfma_i32_16x16x64_i8 v[106:109], v[158:161], v[190:193], v[106:109]
	v_mfma_i32_16x16x64_i8 v[94:97], v[150:153], v[198:201], v[94:97]
	v_mfma_i32_16x16x64_i8 v[90:93], v[158:161], v[198:201], v[90:93]
	v_mfma_i32_16x16x64_i8 v[78:81], v[150:153], v[206:209], v[78:81]
	v_mfma_i32_16x16x64_i8 v[74:77], v[158:161], v[206:209], v[74:77]
	s_setprio 0
	s_setprio 1
	v_mfma_i32_16x16x64_i8 v[118:121], v[162:165], v[178:181], v[118:121]
	v_mfma_i32_16x16x64_i8 v[114:117], v[170:173], v[178:181], v[114:117]
	v_mfma_i32_16x16x64_i8 v[102:105], v[162:165], v[186:189], v[102:105]
	v_mfma_i32_16x16x64_i8 v[98:101], v[170:173], v[186:189], v[98:101]
	v_mfma_i32_16x16x64_i8 v[86:89], v[162:165], v[194:197], v[86:89]
	v_mfma_i32_16x16x64_i8 v[82:85], v[170:173], v[194:197], v[82:85]
	v_mfma_i32_16x16x64_i8 v[70:73], v[162:165], v[202:205], v[70:73]
	v_mfma_i32_16x16x64_i8 v[66:69], v[170:173], v[202:205], v[66:69]
	v_mfma_i32_16x16x64_i8 v[118:121], v[166:169], v[182:185], v[118:121]
	v_mfma_i32_16x16x64_i8 v[114:117], v[174:177], v[182:185], v[114:117]
	v_mfma_i32_16x16x64_i8 v[102:105], v[166:169], v[190:193], v[102:105]
	v_mfma_i32_16x16x64_i8 v[98:101], v[174:177], v[190:193], v[98:101]
	v_mfma_i32_16x16x64_i8 v[86:89], v[166:169], v[198:201], v[86:89]
	v_mfma_i32_16x16x64_i8 v[82:85], v[174:177], v[198:201], v[82:85]
	v_mfma_i32_16x16x64_i8 v[70:73], v[166:169], v[206:209], v[70:73]
	v_mfma_i32_16x16x64_i8 v[66:69], v[174:177], v[206:209], v[66:69]
	s_setprio 0
	s_barrier
	s_add_i32 s4, s77, s60
	ds_read_b128 v[178:181], v145 offset:16384
	ds_read_b128 v[182:185], v145 offset:17408
	ds_read_b128 v[186:189], v145 offset:18432
	ds_read_b128 v[190:193], v145 offset:19456
	ds_read_b128 v[194:197], v145 offset:20480
	ds_read_b128 v[198:201], v145 offset:21504
	ds_read_b128 v[202:205], v145 offset:22528
	ds_read_b128 v[206:209], v145 offset:23552
	s_mov_b32 m0, s4
	s_nop 0
	global_load_lds_dwordx4 v131, s[58:59]
	s_add_i32 m0, s4, 0x2000
	s_add_u32 s4, s58, 0x20000
	global_load_lds_dwordx4 v142, s[58:59]
	s_addc_u32 s5, s59, 0
	s_add_i32 s77, s78, s60
	s_mov_b32 m0, s77
	s_nop 0
	global_load_lds_dwordx4 v131, s[4:5]
	s_add_i32 m0, s77, 0x2000
	s_nop 0
	global_load_lds_dwordx4 v142, s[4:5]
	s_mov_b32 m0, s61
	s_nop 0
	global_load_lds_dwordx4 v130, s[46:47]
	s_mov_b32 m0, s65
	s_nop 0
	global_load_lds_dwordx4 v141, s[46:47]
	s_waitcnt vmcnt(8)
	s_waitcnt lgkmcnt(0)
	s_barrier
	s_setprio 1
	s_waitcnt lgkmcnt(0)
	v_mfma_i32_16x16x64_i8 v[62:65], v[146:149], v[178:181], v[62:65]
	v_mfma_i32_16x16x64_i8 v[58:61], v[154:157], v[178:181], v[58:61]
	v_mfma_i32_16x16x64_i8 v[46:49], v[146:149], v[186:189], v[46:49]
	v_mfma_i32_16x16x64_i8 v[42:45], v[154:157], v[186:189], v[42:45]
	v_mfma_i32_16x16x64_i8 v[30:33], v[146:149], v[194:197], v[30:33]
	v_mfma_i32_16x16x64_i8 v[26:29], v[154:157], v[194:197], v[26:29]
	v_mfma_i32_16x16x64_i8 v[14:17], v[146:149], v[202:205], v[14:17]
	v_mfma_i32_16x16x64_i8 v[10:13], v[154:157], v[202:205], v[10:13]
	v_mfma_i32_16x16x64_i8 v[62:65], v[150:153], v[182:185], v[62:65]
	v_mfma_i32_16x16x64_i8 v[58:61], v[158:161], v[182:185], v[58:61]
	v_mfma_i32_16x16x64_i8 v[46:49], v[150:153], v[190:193], v[46:49]
	v_mfma_i32_16x16x64_i8 v[42:45], v[158:161], v[190:193], v[42:45]
	v_mfma_i32_16x16x64_i8 v[30:33], v[150:153], v[198:201], v[30:33]
	v_mfma_i32_16x16x64_i8 v[26:29], v[158:161], v[198:201], v[26:29]
	v_mfma_i32_16x16x64_i8 v[14:17], v[150:153], v[206:209], v[14:17]
	v_mfma_i32_16x16x64_i8 v[10:13], v[158:161], v[206:209], v[10:13]
	s_setprio 0
	s_setprio 1
	v_mfma_i32_16x16x64_i8 v[54:57], v[162:165], v[178:181], v[54:57]
	v_mfma_i32_16x16x64_i8 v[50:53], v[170:173], v[178:181], v[50:53]
	v_mfma_i32_16x16x64_i8 v[38:41], v[162:165], v[186:189], v[38:41]
	v_mfma_i32_16x16x64_i8 v[34:37], v[170:173], v[186:189], v[34:37]
	v_mfma_i32_16x16x64_i8 v[22:25], v[162:165], v[194:197], v[22:25]
	v_mfma_i32_16x16x64_i8 v[18:21], v[170:173], v[194:197], v[18:21]
	v_mfma_i32_16x16x64_i8 v[6:9], v[162:165], v[202:205], v[6:9]
	v_mfma_i32_16x16x64_i8 v[2:5], v[170:173], v[202:205], v[2:5]
	v_mfma_i32_16x16x64_i8 v[54:57], v[166:169], v[182:185], v[54:57]
	v_mfma_i32_16x16x64_i8 v[50:53], v[174:177], v[182:185], v[50:53]
	v_mfma_i32_16x16x64_i8 v[38:41], v[166:169], v[190:193], v[38:41]
	v_mfma_i32_16x16x64_i8 v[34:37], v[174:177], v[190:193], v[34:37]
	v_mfma_i32_16x16x64_i8 v[22:25], v[166:169], v[198:201], v[22:25]
	v_mfma_i32_16x16x64_i8 v[18:21], v[174:177], v[198:201], v[18:21]
	v_mfma_i32_16x16x64_i8 v[6:9], v[166:169], v[206:209], v[6:9]
	v_mfma_i32_16x16x64_i8 v[2:5], v[174:177], v[206:209], v[2:5]
	s_setprio 0
	s_barrier
	s_add_i32 s77, 0, 0x18000
	v_add_u32_e32 v0, s77, v144
	s_add_i32 s78, 0, 0x1c000
	ds_read_b128 v[146:149], v0
	ds_read_b128 v[150:153], v0 offset:1024
	ds_read_b128 v[154:157], v0 offset:2048
	ds_read_b128 v[158:161], v0 offset:3072
	v_add_u32_e32 v0, s78, v144
	ds_read_b128 v[162:165], v0
	ds_read_b128 v[166:169], v0 offset:1024
	ds_read_b128 v[170:173], v0 offset:2048
	ds_read_b128 v[174:177], v0 offset:3072
	s_add_u32 s4, s46, 0x20000
	s_mov_b32 m0, s66
	ds_read_b128 v[178:181], v145 offset:32768
	ds_read_b128 v[182:185], v145 offset:33792
	ds_read_b128 v[186:189], v145 offset:34816
	ds_read_b128 v[190:193], v145 offset:35840
	ds_read_b128 v[194:197], v145 offset:36864
	ds_read_b128 v[198:201], v145 offset:37888
	ds_read_b128 v[202:205], v145 offset:38912
	ds_read_b128 v[206:209], v145 offset:39936
	s_addc_u32 s5, s47, 0
	s_nop 0
	global_load_lds_dwordx4 v130, s[4:5]
	s_mov_b32 m0, s67
	s_nop 0
	global_load_lds_dwordx4 v141, s[4:5]
	s_waitcnt vmcnt(8)
	s_waitcnt lgkmcnt(0)
	s_barrier
	s_setprio 1
	s_waitcnt lgkmcnt(0)
	v_mfma_i32_16x16x64_i8 v[126:129], v[146:149], v[178:181], v[126:129]
	v_mfma_i32_16x16x64_i8 v[122:125], v[154:157], v[178:181], v[122:125]
	v_mfma_i32_16x16x64_i8 v[110:113], v[146:149], v[186:189], v[110:113]
	v_mfma_i32_16x16x64_i8 v[106:109], v[154:157], v[186:189], v[106:109]
	v_mfma_i32_16x16x64_i8 v[94:97], v[146:149], v[194:197], v[94:97]
	v_mfma_i32_16x16x64_i8 v[90:93], v[154:157], v[194:197], v[90:93]
	v_mfma_i32_16x16x64_i8 v[78:81], v[146:149], v[202:205], v[78:81]
	v_mfma_i32_16x16x64_i8 v[74:77], v[154:157], v[202:205], v[74:77]
	v_mfma_i32_16x16x64_i8 v[126:129], v[150:153], v[182:185], v[126:129]
	v_mfma_i32_16x16x64_i8 v[122:125], v[158:161], v[182:185], v[122:125]
	v_mfma_i32_16x16x64_i8 v[110:113], v[150:153], v[190:193], v[110:113]
	v_mfma_i32_16x16x64_i8 v[106:109], v[158:161], v[190:193], v[106:109]
	v_mfma_i32_16x16x64_i8 v[94:97], v[150:153], v[198:201], v[94:97]
	v_mfma_i32_16x16x64_i8 v[90:93], v[158:161], v[198:201], v[90:93]
	v_mfma_i32_16x16x64_i8 v[78:81], v[150:153], v[206:209], v[78:81]
	v_mfma_i32_16x16x64_i8 v[74:77], v[158:161], v[206:209], v[74:77]
	s_setprio 0
	s_setprio 1
	v_mfma_i32_16x16x64_i8 v[118:121], v[162:165], v[178:181], v[118:121]
	v_mfma_i32_16x16x64_i8 v[114:117], v[170:173], v[178:181], v[114:117]
	v_mfma_i32_16x16x64_i8 v[102:105], v[162:165], v[186:189], v[102:105]
	v_mfma_i32_16x16x64_i8 v[98:101], v[170:173], v[186:189], v[98:101]
	v_mfma_i32_16x16x64_i8 v[86:89], v[162:165], v[194:197], v[86:89]
	v_mfma_i32_16x16x64_i8 v[82:85], v[170:173], v[194:197], v[82:85]
	v_mfma_i32_16x16x64_i8 v[70:73], v[162:165], v[202:205], v[70:73]
	v_mfma_i32_16x16x64_i8 v[66:69], v[170:173], v[202:205], v[66:69]
	v_mfma_i32_16x16x64_i8 v[118:121], v[166:169], v[182:185], v[118:121]
	v_mfma_i32_16x16x64_i8 v[114:117], v[174:177], v[182:185], v[114:117]
	v_mfma_i32_16x16x64_i8 v[102:105], v[166:169], v[190:193], v[102:105]
	v_mfma_i32_16x16x64_i8 v[98:101], v[174:177], v[190:193], v[98:101]
	v_mfma_i32_16x16x64_i8 v[86:89], v[166:169], v[198:201], v[86:89]
	v_mfma_i32_16x16x64_i8 v[82:85], v[174:177], v[198:201], v[82:85]
	v_mfma_i32_16x16x64_i8 v[70:73], v[166:169], v[206:209], v[70:73]
	v_mfma_i32_16x16x64_i8 v[66:69], v[174:177], v[206:209], v[66:69]
	s_setprio 0
	s_barrier
	v_mov_b32_e32 v0, v131
	ds_read_b128 v[178:181], v145 offset:49152
	ds_read_b128 v[182:185], v145 offset:50176
	ds_read_b128 v[186:189], v145 offset:51200
	ds_read_b128 v[190:193], v145 offset:52224
	ds_read_b128 v[194:197], v145 offset:53248
	ds_read_b128 v[198:201], v145 offset:54272
	ds_read_b128 v[202:205], v145 offset:55296
	ds_read_b128 v[206:209], v145 offset:56320
	s_add_i32 s4, s77, s60
	v_lshl_add_u64 v[210:211], s[58:59], 0, v[0:1]
	v_lshl_add_u64 v[210:211], v[210:211], 0, s[38:39]
	s_mov_b32 m0, s4
	v_mov_b32_e32 v0, v142
	global_load_lds_dwordx4 v[210:211], off
	s_add_i32 m0, s4, 0x2000
	s_add_u32 s4, s58, 0x20080
	v_lshl_add_u64 v[210:211], s[58:59], 0, v[0:1]
	v_lshl_add_u64 v[210:211], v[210:211], 0, s[38:39]
	s_addc_u32 s5, s59, 0
	s_add_i32 s58, s78, s60
	global_load_lds_dwordx4 v[210:211], off
	s_mov_b32 m0, s58
	s_nop 0
	global_load_lds_dwordx4 v131, s[4:5]
	s_add_i32 m0, s58, 0x2000
	s_nop 0
	global_load_lds_dwordx4 v142, s[4:5]
	v_mov_b32_e32 v0, v130
	s_mov_b32 m0, s68
	v_lshl_add_u64 v[210:211], s[46:47], 0, v[0:1]
	v_lshl_add_u64 v[210:211], v[210:211], 0, s[38:39]
	v_mov_b32_e32 v0, v141
	global_load_lds_dwordx4 v[210:211], off
	s_mov_b32 m0, s69
	v_lshl_add_u64 v[210:211], s[46:47], 0, v[0:1]
	v_lshl_add_u64 v[210:211], v[210:211], 0, s[38:39]
	global_load_lds_dwordx4 v[210:211], off
	s_waitcnt vmcnt(8)
	s_waitcnt lgkmcnt(0)
	s_barrier
	s_setprio 1
	s_waitcnt lgkmcnt(0)
	v_mfma_i32_16x16x64_i8 v[62:65], v[146:149], v[178:181], v[62:65]
	v_mfma_i32_16x16x64_i8 v[58:61], v[154:157], v[178:181], v[58:61]
	v_mfma_i32_16x16x64_i8 v[46:49], v[146:149], v[186:189], v[46:49]
	v_mfma_i32_16x16x64_i8 v[42:45], v[154:157], v[186:189], v[42:45]
	v_mfma_i32_16x16x64_i8 v[30:33], v[146:149], v[194:197], v[30:33]
	v_mfma_i32_16x16x64_i8 v[26:29], v[154:157], v[194:197], v[26:29]
	v_mfma_i32_16x16x64_i8 v[14:17], v[146:149], v[202:205], v[14:17]
	v_mfma_i32_16x16x64_i8 v[10:13], v[154:157], v[202:205], v[10:13]
	v_mfma_i32_16x16x64_i8 v[62:65], v[150:153], v[182:185], v[62:65]
	v_mfma_i32_16x16x64_i8 v[58:61], v[158:161], v[182:185], v[58:61]
	v_mfma_i32_16x16x64_i8 v[46:49], v[150:153], v[190:193], v[46:49]
	v_mfma_i32_16x16x64_i8 v[42:45], v[158:161], v[190:193], v[42:45]
	v_mfma_i32_16x16x64_i8 v[30:33], v[150:153], v[198:201], v[30:33]
	v_mfma_i32_16x16x64_i8 v[26:29], v[158:161], v[198:201], v[26:29]
	v_mfma_i32_16x16x64_i8 v[14:17], v[150:153], v[206:209], v[14:17]
	v_mfma_i32_16x16x64_i8 v[10:13], v[158:161], v[206:209], v[10:13]
	s_setprio 0
	s_setprio 1
	v_mfma_i32_16x16x64_i8 v[54:57], v[162:165], v[178:181], v[54:57]
	v_mfma_i32_16x16x64_i8 v[50:53], v[170:173], v[178:181], v[50:53]
	v_mfma_i32_16x16x64_i8 v[38:41], v[162:165], v[186:189], v[38:41]
	v_mfma_i32_16x16x64_i8 v[34:37], v[170:173], v[186:189], v[34:37]
	v_mfma_i32_16x16x64_i8 v[22:25], v[162:165], v[194:197], v[22:25]
	v_mfma_i32_16x16x64_i8 v[18:21], v[170:173], v[194:197], v[18:21]
	v_mfma_i32_16x16x64_i8 v[6:9], v[162:165], v[202:205], v[6:9]
	v_mfma_i32_16x16x64_i8 v[2:5], v[170:173], v[202:205], v[2:5]
	v_mfma_i32_16x16x64_i8 v[54:57], v[166:169], v[182:185], v[54:57]
	v_mfma_i32_16x16x64_i8 v[50:53], v[174:177], v[182:185], v[50:53]
	v_mfma_i32_16x16x64_i8 v[38:41], v[166:169], v[190:193], v[38:41]
	v_mfma_i32_16x16x64_i8 v[34:37], v[174:177], v[190:193], v[34:37]
	v_mfma_i32_16x16x64_i8 v[22:25], v[166:169], v[198:201], v[22:25]
	v_mfma_i32_16x16x64_i8 v[18:21], v[174:177], v[198:201], v[18:21]
	v_mfma_i32_16x16x64_i8 v[6:9], v[166:169], v[206:209], v[6:9]
	v_mfma_i32_16x16x64_i8 v[2:5], v[174:177], v[206:209], v[2:5]
	s_setprio 0
	s_barrier
	s_add_i32 s76, s76, 2
	s_add_u32 s50, s50, 0x100
	s_addc_u32 s51, s51, 0
	s_cmp_gt_u32 s76, 5
	s_cbranch_scc0 .LBB0_667
	s_cmpk_lt_u32 s17, 0x100
	s_cbranch_scc0 .LBB0_661
	s_barrier
	s_branch .LBB0_661

.LBB0_821:
	s_add_u32 s4, s79, s50
	s_addc_u32 s5, s82, s51
	s_add_u32 s46, s4, 0x9800100
	s_addc_u32 s47, s5, 0
	s_add_u32 s58, s64, s50
	s_addc_u32 s59, s83, s51
	s_add_i32 s85, 0, 0x10000
	s_cmpk_eq_i32 s50, 0x1500
	s_cselect_b32 s47, s49, s47
	s_cselect_b32 s46, s48, s46
	v_add_u32_e32 v0, s85, v134
	s_cselect_b32 s59, s71, s59
	s_cselect_b32 s58, s70, s58
	s_add_i32 s86, 0, 0x14000
	ds_read_b128 v[136:139], v0
	ds_read_b128 v[140:143], v0 offset:1024
	ds_read_b128 v[144:147], v0 offset:2048
	ds_read_b128 v[148:151], v0 offset:3072
	v_add_u32_e32 v0, s86, v134
	ds_read_b128 v[152:155], v0
	ds_read_b128 v[156:159], v0 offset:1024
	ds_read_b128 v[160:163], v0 offset:2048
	ds_read_b128 v[164:167], v0 offset:3072
	v_mov_b32_e32 v0, v130
	ds_read_b128 v[168:171], v135
	ds_read_b128 v[172:175], v135 offset:1024
	ds_read_b128 v[176:179], v135 offset:2048
	ds_read_b128 v[180:183], v135 offset:3072
	ds_read_b128 v[184:187], v135 offset:4096
	ds_read_b128 v[188:191], v135 offset:5120
	ds_read_b128 v[192:195], v135 offset:6144
	ds_read_b128 v[198:201], v135 offset:7168
	s_add_i32 m0, s60, 0xc000
	v_lshl_add_u64 v[202:203], s[4:5], 0, v[0:1]
	v_lshl_add_u64 v[202:203], v[202:203], 0, s[88:89]
	v_mov_b32_e32 v0, v131
	global_load_lds_dwordx4 v[202:203], off
	s_add_i32 m0, s60, 0xe000
	v_lshl_add_u64 v[202:203], s[4:5], 0, v[0:1]
	v_lshl_add_u64 v[202:203], v[202:203], 0, s[88:89]
	global_load_lds_dwordx4 v[202:203], off
	s_waitcnt vmcnt(8)
	s_waitcnt lgkmcnt(0)
	s_barrier
	s_setprio 1
	s_waitcnt lgkmcnt(0)
	v_mfma_f32_16x16x32_bf16 v[126:129], v[136:139], v[168:171], v[126:129]
	v_mfma_f32_16x16x32_bf16 v[122:125], v[144:147], v[168:171], v[122:125]
	v_mfma_f32_16x16x32_bf16 v[110:113], v[136:139], v[176:179], v[110:113]
	v_mfma_f32_16x16x32_bf16 v[106:109], v[144:147], v[176:179], v[106:109]
	v_mfma_f32_16x16x32_bf16 v[94:97], v[136:139], v[184:187], v[94:97]
	v_mfma_f32_16x16x32_bf16 v[90:93], v[144:147], v[184:187], v[90:93]
	v_mfma_f32_16x16x32_bf16 v[78:81], v[136:139], v[192:195], v[78:81]
	v_mfma_f32_16x16x32_bf16 v[74:77], v[144:147], v[192:195], v[74:77]
	v_mfma_f32_16x16x32_bf16 v[126:129], v[140:143], v[172:175], v[126:129]
	v_mfma_f32_16x16x32_bf16 v[122:125], v[148:151], v[172:175], v[122:125]
	v_mfma_f32_16x16x32_bf16 v[110:113], v[140:143], v[180:183], v[110:113]
	v_mfma_f32_16x16x32_bf16 v[106:109], v[148:151], v[180:183], v[106:109]
	v_mfma_f32_16x16x32_bf16 v[94:97], v[140:143], v[188:191], v[94:97]
	v_mfma_f32_16x16x32_bf16 v[90:93], v[148:151], v[188:191], v[90:93]
	v_mfma_f32_16x16x32_bf16 v[78:81], v[140:143], v[198:201], v[78:81]
	v_mfma_f32_16x16x32_bf16 v[74:77], v[148:151], v[198:201], v[74:77]
	s_setprio 0
	s_setprio 1
	v_mfma_f32_16x16x32_bf16 v[118:121], v[152:155], v[168:171], v[118:121]
	v_mfma_f32_16x16x32_bf16 v[114:117], v[160:163], v[168:171], v[114:117]
	v_mfma_f32_16x16x32_bf16 v[102:105], v[152:155], v[176:179], v[102:105]
	v_mfma_f32_16x16x32_bf16 v[98:101], v[160:163], v[176:179], v[98:101]
	v_mfma_f32_16x16x32_bf16 v[86:89], v[152:155], v[184:187], v[86:89]
	v_mfma_f32_16x16x32_bf16 v[82:85], v[160:163], v[184:187], v[82:85]
	v_mfma_f32_16x16x32_bf16 v[70:73], v[152:155], v[192:195], v[70:73]
	v_mfma_f32_16x16x32_bf16 v[66:69], v[160:163], v[192:195], v[66:69]
	v_mfma_f32_16x16x32_bf16 v[118:121], v[156:159], v[172:175], v[118:121]
	v_mfma_f32_16x16x32_bf16 v[114:117], v[164:167], v[172:175], v[114:117]
	v_mfma_f32_16x16x32_bf16 v[102:105], v[156:159], v[180:183], v[102:105]
	v_mfma_f32_16x16x32_bf16 v[98:101], v[164:167], v[180:183], v[98:101]
	v_mfma_f32_16x16x32_bf16 v[86:89], v[156:159], v[188:191], v[86:89]
	v_mfma_f32_16x16x32_bf16 v[82:85], v[164:167], v[188:191], v[82:85]
	v_mfma_f32_16x16x32_bf16 v[70:73], v[156:159], v[198:201], v[70:73]
	v_mfma_f32_16x16x32_bf16 v[66:69], v[164:167], v[198:201], v[66:69]
	s_setprio 0
	s_barrier
	s_add_i32 s4, s85, s26
	ds_read_b128 v[168:171], v135 offset:16384
	ds_read_b128 v[172:175], v135 offset:17408
	ds_read_b128 v[176:179], v135 offset:18432
	ds_read_b128 v[180:183], v135 offset:19456
	ds_read_b128 v[184:187], v135 offset:20480
	ds_read_b128 v[188:191], v135 offset:21504
	ds_read_b128 v[192:195], v135 offset:22528
	ds_read_b128 v[198:201], v135 offset:23552
	s_mov_b32 m0, s4
	s_nop 0
	global_load_lds_dwordx4 v132, s[58:59]
	s_add_i32 m0, s4, 0x2000
	s_add_u32 s4, s58, 0xb0000
	global_load_lds_dwordx4 v133, s[58:59]
	s_addc_u32 s5, s59, 0
	s_add_i32 s85, s86, s26
	s_mov_b32 m0, s85
	s_nop 0
	global_load_lds_dwordx4 v132, s[4:5]
	s_add_i32 m0, s85, 0x2000
	s_nop 0
	global_load_lds_dwordx4 v133, s[4:5]
	s_mov_b32 m0, s60
	s_nop 0
	global_load_lds_dwordx4 v130, s[46:47]
	s_mov_b32 m0, s65
	s_nop 0
	global_load_lds_dwordx4 v131, s[46:47]
	s_waitcnt vmcnt(8)
	s_waitcnt lgkmcnt(0)
	s_barrier
	s_setprio 1
	s_waitcnt lgkmcnt(0)
	v_mfma_f32_16x16x32_bf16 v[62:65], v[136:139], v[168:171], v[62:65]
	v_mfma_f32_16x16x32_bf16 v[58:61], v[144:147], v[168:171], v[58:61]
	v_mfma_f32_16x16x32_bf16 v[46:49], v[136:139], v[176:179], v[46:49]
	v_mfma_f32_16x16x32_bf16 v[42:45], v[144:147], v[176:179], v[42:45]
	v_mfma_f32_16x16x32_bf16 v[30:33], v[136:139], v[184:187], v[30:33]
	v_mfma_f32_16x16x32_bf16 v[26:29], v[144:147], v[184:187], v[26:29]
	v_mfma_f32_16x16x32_bf16 v[14:17], v[136:139], v[192:195], v[14:17]
	v_mfma_f32_16x16x32_bf16 v[10:13], v[144:147], v[192:195], v[10:13]
	v_mfma_f32_16x16x32_bf16 v[62:65], v[140:143], v[172:175], v[62:65]
	v_mfma_f32_16x16x32_bf16 v[58:61], v[148:151], v[172:175], v[58:61]
	v_mfma_f32_16x16x32_bf16 v[46:49], v[140:143], v[180:183], v[46:49]
	v_mfma_f32_16x16x32_bf16 v[42:45], v[148:151], v[180:183], v[42:45]
	v_mfma_f32_16x16x32_bf16 v[30:33], v[140:143], v[188:191], v[30:33]
	v_mfma_f32_16x16x32_bf16 v[26:29], v[148:151], v[188:191], v[26:29]
	v_mfma_f32_16x16x32_bf16 v[14:17], v[140:143], v[198:201], v[14:17]
	v_mfma_f32_16x16x32_bf16 v[10:13], v[148:151], v[198:201], v[10:13]
	s_setprio 0
	s_setprio 1
	v_mfma_f32_16x16x32_bf16 v[54:57], v[152:155], v[168:171], v[54:57]
	v_mfma_f32_16x16x32_bf16 v[50:53], v[160:163], v[168:171], v[50:53]
	v_mfma_f32_16x16x32_bf16 v[38:41], v[152:155], v[176:179], v[38:41]
	v_mfma_f32_16x16x32_bf16 v[34:37], v[160:163], v[176:179], v[34:37]
	v_mfma_f32_16x16x32_bf16 v[22:25], v[152:155], v[184:187], v[22:25]
	v_mfma_f32_16x16x32_bf16 v[18:21], v[160:163], v[184:187], v[18:21]
	v_mfma_f32_16x16x32_bf16 v[6:9], v[152:155], v[192:195], v[6:9]
	v_mfma_f32_16x16x32_bf16 v[2:5], v[160:163], v[192:195], v[2:5]
	v_mfma_f32_16x16x32_bf16 v[54:57], v[156:159], v[172:175], v[54:57]
	v_mfma_f32_16x16x32_bf16 v[50:53], v[164:167], v[172:175], v[50:53]
	v_mfma_f32_16x16x32_bf16 v[38:41], v[156:159], v[180:183], v[38:41]
	v_mfma_f32_16x16x32_bf16 v[34:37], v[164:167], v[180:183], v[34:37]
	v_mfma_f32_16x16x32_bf16 v[22:25], v[156:159], v[188:191], v[22:25]
	v_mfma_f32_16x16x32_bf16 v[18:21], v[164:167], v[188:191], v[18:21]
	v_mfma_f32_16x16x32_bf16 v[6:9], v[156:159], v[198:201], v[6:9]
	v_mfma_f32_16x16x32_bf16 v[2:5], v[164:167], v[198:201], v[2:5]
	s_setprio 0
	s_barrier
	s_add_i32 s85, 0, 0x18000
	v_add_u32_e32 v0, s85, v134
	s_add_i32 s86, 0, 0x1c000
	ds_read_b128 v[136:139], v0
	ds_read_b128 v[140:143], v0 offset:1024
	ds_read_b128 v[144:147], v0 offset:2048
	ds_read_b128 v[148:151], v0 offset:3072
	v_add_u32_e32 v0, s86, v134
	ds_read_b128 v[152:155], v0
	ds_read_b128 v[156:159], v0 offset:1024
	ds_read_b128 v[160:163], v0 offset:2048
	ds_read_b128 v[164:167], v0 offset:3072
	s_add_u32 s4, s46, 0xb0000
	s_mov_b32 m0, s68
	ds_read_b128 v[168:171], v135 offset:32768
	ds_read_b128 v[172:175], v135 offset:33792
	ds_read_b128 v[176:179], v135 offset:34816
	ds_read_b128 v[180:183], v135 offset:35840
	ds_read_b128 v[184:187], v135 offset:36864
	ds_read_b128 v[188:191], v135 offset:37888
	ds_read_b128 v[192:195], v135 offset:38912
	ds_read_b128 v[198:201], v135 offset:39936
	s_addc_u32 s5, s47, 0
	s_nop 0
	global_load_lds_dwordx4 v130, s[4:5]
	s_mov_b32 m0, s69
	s_nop 0
	global_load_lds_dwordx4 v131, s[4:5]
	s_waitcnt vmcnt(8)
	s_waitcnt lgkmcnt(0)
	s_barrier
	s_setprio 1
	s_waitcnt lgkmcnt(0)
	v_mfma_f32_16x16x32_bf16 v[126:129], v[136:139], v[168:171], v[126:129]
	v_mfma_f32_16x16x32_bf16 v[122:125], v[144:147], v[168:171], v[122:125]
	v_mfma_f32_16x16x32_bf16 v[110:113], v[136:139], v[176:179], v[110:113]
	v_mfma_f32_16x16x32_bf16 v[106:109], v[144:147], v[176:179], v[106:109]
	v_mfma_f32_16x16x32_bf16 v[94:97], v[136:139], v[184:187], v[94:97]
	v_mfma_f32_16x16x32_bf16 v[90:93], v[144:147], v[184:187], v[90:93]
	v_mfma_f32_16x16x32_bf16 v[78:81], v[136:139], v[192:195], v[78:81]
	v_mfma_f32_16x16x32_bf16 v[74:77], v[144:147], v[192:195], v[74:77]
	v_mfma_f32_16x16x32_bf16 v[126:129], v[140:143], v[172:175], v[126:129]
	v_mfma_f32_16x16x32_bf16 v[122:125], v[148:151], v[172:175], v[122:125]
	v_mfma_f32_16x16x32_bf16 v[110:113], v[140:143], v[180:183], v[110:113]
	v_mfma_f32_16x16x32_bf16 v[106:109], v[148:151], v[180:183], v[106:109]
	v_mfma_f32_16x16x32_bf16 v[94:97], v[140:143], v[188:191], v[94:97]
	v_mfma_f32_16x16x32_bf16 v[90:93], v[148:151], v[188:191], v[90:93]
	v_mfma_f32_16x16x32_bf16 v[78:81], v[140:143], v[198:201], v[78:81]
	v_mfma_f32_16x16x32_bf16 v[74:77], v[148:151], v[198:201], v[74:77]
	s_setprio 0
	s_setprio 1
	v_mfma_f32_16x16x32_bf16 v[118:121], v[152:155], v[168:171], v[118:121]
	v_mfma_f32_16x16x32_bf16 v[114:117], v[160:163], v[168:171], v[114:117]
	v_mfma_f32_16x16x32_bf16 v[102:105], v[152:155], v[176:179], v[102:105]
	v_mfma_f32_16x16x32_bf16 v[98:101], v[160:163], v[176:179], v[98:101]
	v_mfma_f32_16x16x32_bf16 v[86:89], v[152:155], v[184:187], v[86:89]
	v_mfma_f32_16x16x32_bf16 v[82:85], v[160:163], v[184:187], v[82:85]
	v_mfma_f32_16x16x32_bf16 v[70:73], v[152:155], v[192:195], v[70:73]
	v_mfma_f32_16x16x32_bf16 v[66:69], v[160:163], v[192:195], v[66:69]
	v_mfma_f32_16x16x32_bf16 v[118:121], v[156:159], v[172:175], v[118:121]
	v_mfma_f32_16x16x32_bf16 v[114:117], v[164:167], v[172:175], v[114:117]
	v_mfma_f32_16x16x32_bf16 v[102:105], v[156:159], v[180:183], v[102:105]
	v_mfma_f32_16x16x32_bf16 v[98:101], v[164:167], v[180:183], v[98:101]
	v_mfma_f32_16x16x32_bf16 v[86:89], v[156:159], v[188:191], v[86:89]
	v_mfma_f32_16x16x32_bf16 v[82:85], v[164:167], v[188:191], v[82:85]
	v_mfma_f32_16x16x32_bf16 v[70:73], v[156:159], v[198:201], v[70:73]
	v_mfma_f32_16x16x32_bf16 v[66:69], v[164:167], v[198:201], v[66:69]
	s_setprio 0
	s_barrier
	v_mov_b32_e32 v0, v132
	ds_read_b128 v[168:171], v135 offset:49152
	ds_read_b128 v[172:175], v135 offset:50176
	ds_read_b128 v[176:179], v135 offset:51200
	ds_read_b128 v[180:183], v135 offset:52224
	ds_read_b128 v[184:187], v135 offset:53248
	ds_read_b128 v[188:191], v135 offset:54272
	ds_read_b128 v[192:195], v135 offset:55296
	ds_read_b128 v[198:201], v135 offset:56320
	s_add_i32 s4, s85, s26
	v_lshl_add_u64 v[202:203], s[58:59], 0, v[0:1]
	v_lshl_add_u64 v[202:203], v[202:203], 0, s[38:39]
	s_mov_b32 m0, s4
	v_mov_b32_e32 v0, v133
	global_load_lds_dwordx4 v[202:203], off
	s_add_i32 m0, s4, 0x2000
	s_add_u32 s4, s58, 0xb0080
	v_lshl_add_u64 v[202:203], s[58:59], 0, v[0:1]
	v_lshl_add_u64 v[202:203], v[202:203], 0, s[38:39]
	s_addc_u32 s5, s59, 0
	s_add_i32 s58, s86, s26
	global_load_lds_dwordx4 v[202:203], off
	s_mov_b32 m0, s58
	s_nop 0
	global_load_lds_dwordx4 v132, s[4:5]
	s_add_i32 m0, s58, 0x2000
	s_nop 0
	global_load_lds_dwordx4 v133, s[4:5]
	v_mov_b32_e32 v0, v130
	s_mov_b32 m0, s75
	v_lshl_add_u64 v[202:203], s[46:47], 0, v[0:1]
	v_lshl_add_u64 v[202:203], v[202:203], 0, s[38:39]
	v_mov_b32_e32 v0, v131
	global_load_lds_dwordx4 v[202:203], off
	s_mov_b32 m0, s78
	v_lshl_add_u64 v[202:203], s[46:47], 0, v[0:1]
	v_lshl_add_u64 v[202:203], v[202:203], 0, s[38:39]
	global_load_lds_dwordx4 v[202:203], off
	s_waitcnt vmcnt(8)
	s_waitcnt lgkmcnt(0)
	s_barrier
	s_setprio 1
	s_waitcnt lgkmcnt(0)
	v_mfma_f32_16x16x32_bf16 v[62:65], v[136:139], v[168:171], v[62:65]
	v_mfma_f32_16x16x32_bf16 v[58:61], v[144:147], v[168:171], v[58:61]
	v_mfma_f32_16x16x32_bf16 v[46:49], v[136:139], v[176:179], v[46:49]
	v_mfma_f32_16x16x32_bf16 v[42:45], v[144:147], v[176:179], v[42:45]
	v_mfma_f32_16x16x32_bf16 v[30:33], v[136:139], v[184:187], v[30:33]
	v_mfma_f32_16x16x32_bf16 v[26:29], v[144:147], v[184:187], v[26:29]
	v_mfma_f32_16x16x32_bf16 v[14:17], v[136:139], v[192:195], v[14:17]
	v_mfma_f32_16x16x32_bf16 v[10:13], v[144:147], v[192:195], v[10:13]
	v_mfma_f32_16x16x32_bf16 v[62:65], v[140:143], v[172:175], v[62:65]
	v_mfma_f32_16x16x32_bf16 v[58:61], v[148:151], v[172:175], v[58:61]
	v_mfma_f32_16x16x32_bf16 v[46:49], v[140:143], v[180:183], v[46:49]
	v_mfma_f32_16x16x32_bf16 v[42:45], v[148:151], v[180:183], v[42:45]
	v_mfma_f32_16x16x32_bf16 v[30:33], v[140:143], v[188:191], v[30:33]
	v_mfma_f32_16x16x32_bf16 v[26:29], v[148:151], v[188:191], v[26:29]
	v_mfma_f32_16x16x32_bf16 v[14:17], v[140:143], v[198:201], v[14:17]
	v_mfma_f32_16x16x32_bf16 v[10:13], v[148:151], v[198:201], v[10:13]
	s_setprio 0
	s_setprio 1
	v_mfma_f32_16x16x32_bf16 v[54:57], v[152:155], v[168:171], v[54:57]
	v_mfma_f32_16x16x32_bf16 v[50:53], v[160:163], v[168:171], v[50:53]
	v_mfma_f32_16x16x32_bf16 v[38:41], v[152:155], v[176:179], v[38:41]
	v_mfma_f32_16x16x32_bf16 v[34:37], v[160:163], v[176:179], v[34:37]
	v_mfma_f32_16x16x32_bf16 v[22:25], v[152:155], v[184:187], v[22:25]
	v_mfma_f32_16x16x32_bf16 v[18:21], v[160:163], v[184:187], v[18:21]
	v_mfma_f32_16x16x32_bf16 v[6:9], v[152:155], v[192:195], v[6:9]
	v_mfma_f32_16x16x32_bf16 v[2:5], v[160:163], v[192:195], v[2:5]
	v_mfma_f32_16x16x32_bf16 v[54:57], v[156:159], v[172:175], v[54:57]
	v_mfma_f32_16x16x32_bf16 v[50:53], v[164:167], v[172:175], v[50:53]
	v_mfma_f32_16x16x32_bf16 v[38:41], v[156:159], v[180:183], v[38:41]
	v_mfma_f32_16x16x32_bf16 v[34:37], v[164:167], v[180:183], v[34:37]
	v_mfma_f32_16x16x32_bf16 v[22:25], v[156:159], v[188:191], v[22:25]
	v_mfma_f32_16x16x32_bf16 v[18:21], v[164:167], v[188:191], v[18:21]
	v_mfma_f32_16x16x32_bf16 v[6:9], v[156:159], v[198:201], v[6:9]
	v_mfma_f32_16x16x32_bf16 v[2:5], v[164:167], v[198:201], v[2:5]
	s_setprio 0
	s_barrier
	s_add_i32 s84, s84, 2
	s_add_u32 s50, s50, 0x100
	s_addc_u32 s51, s51, 0
	s_cmp_gt_u32 s84, 41
	s_cbranch_scc0 .LBB0_821
	s_cmpk_lt_u32 s24, 0x100
	s_cbranch_scc0 .LBB0_824
	s_barrier

.LBB0_869:
	s_add_u32 s4, s10, s2
	s_addc_u32 s5, s11, s3
	s_add_u32 s22, s4, 0x100
	s_addc_u32 s23, s5, 0
	s_add_u32 s46, s58, s2
	s_addc_u32 s47, s59, s3
	s_add_i32 s69, 0, 0x10000
	s_cmp_eq_u32 s68, 40
	s_cselect_b32 s23, s11, s23
	s_cselect_b32 s22, s10, s22
	v_add_u32_e32 v0, s69, v126
	s_cselect_b32 s47, s17, s47
	s_cselect_b32 s46, s16, s46
	s_add_i32 s70, 0, 0x14000
	ds_read_b128 v[128:131], v0
	ds_read_b128 v[142:145], v0 offset:1024
	ds_read_b128 v[146:149], v0 offset:2048
	ds_read_b128 v[150:153], v0 offset:3072
	v_add_u32_e32 v0, s70, v126
	ds_read_b128 v[154:157], v0
	ds_read_b128 v[160:163], v0 offset:1024
	ds_read_b128 v[164:167], v0 offset:2048
	ds_read_b128 v[168:171], v0 offset:3072
	v_mov_b32_e32 v0, v122
	ds_read_b128 v[172:175], v127
	ds_read_b128 v[176:179], v127 offset:1024
	ds_read_b128 v[180:183], v127 offset:2048
	ds_read_b128 v[184:187], v127 offset:3072
	ds_read_b128 v[188:191], v127 offset:4096
	ds_read_b128 v[192:195], v127 offset:5120
	ds_read_b128 v[196:199], v127 offset:6144
	ds_read_b128 v[200:203], v127 offset:7168
	s_add_i32 m0, s41, 0xc000
	v_lshl_add_u64 v[132:133], s[4:5], 0, v[0:1]
	v_lshl_add_u64 v[132:133], v[132:133], 0, s[62:63]
	v_mov_b32_e32 v0, v123
	global_load_lds_dwordx4 v[132:133], off
	s_add_i32 m0, s41, 0xe000
	v_lshl_add_u64 v[132:133], s[4:5], 0, v[0:1]
	v_lshl_add_u64 v[132:133], v[132:133], 0, s[62:63]
	global_load_lds_dwordx4 v[132:133], off
	s_waitcnt vmcnt(8)
	s_waitcnt lgkmcnt(0)
	s_barrier
	s_setprio 1
	s_waitcnt lgkmcnt(0)
	v_mfma_f32_16x16x32_bf16 v[138:141], v[128:131], v[172:175], v[138:141]
	v_mfma_f32_16x16x32_bf16 v[132:135], v[146:149], v[172:175], v[134:137]
	v_mfma_f32_16x16x32_bf16 v[110:113], v[128:131], v[180:183], v[110:113]
	v_mfma_f32_16x16x32_bf16 v[106:109], v[146:149], v[180:183], v[106:109]
	v_mfma_f32_16x16x32_bf16 v[94:97], v[128:131], v[188:191], v[94:97]
	v_mfma_f32_16x16x32_bf16 v[90:93], v[146:149], v[188:191], v[90:93]
	v_mfma_f32_16x16x32_bf16 v[78:81], v[128:131], v[196:199], v[78:81]
	v_mfma_f32_16x16x32_bf16 v[74:77], v[146:149], v[196:199], v[74:77]
	v_mfma_f32_16x16x32_bf16 v[138:141], v[142:145], v[176:179], v[138:141]
	v_mfma_f32_16x16x32_bf16 v[132:135], v[150:153], v[176:179], v[132:135]
	v_mfma_f32_16x16x32_bf16 v[110:113], v[142:145], v[184:187], v[110:113]
	v_mfma_f32_16x16x32_bf16 v[106:109], v[150:153], v[184:187], v[106:109]
	v_mfma_f32_16x16x32_bf16 v[94:97], v[142:145], v[192:195], v[94:97]
	v_mfma_f32_16x16x32_bf16 v[90:93], v[150:153], v[192:195], v[90:93]
	v_mfma_f32_16x16x32_bf16 v[78:81], v[142:145], v[200:203], v[78:81]
	v_mfma_f32_16x16x32_bf16 v[74:77], v[150:153], v[200:203], v[74:77]
	s_setprio 0
	s_setprio 1
	v_mfma_f32_16x16x32_bf16 v[118:121], v[154:157], v[172:175], v[118:121]
	v_mfma_f32_16x16x32_bf16 v[114:117], v[164:167], v[172:175], v[114:117]
	v_mfma_f32_16x16x32_bf16 v[102:105], v[154:157], v[180:183], v[102:105]
	v_mfma_f32_16x16x32_bf16 v[98:101], v[164:167], v[180:183], v[98:101]
	v_mfma_f32_16x16x32_bf16 v[86:89], v[154:157], v[188:191], v[86:89]
	v_mfma_f32_16x16x32_bf16 v[82:85], v[164:167], v[188:191], v[82:85]
	v_mfma_f32_16x16x32_bf16 v[70:73], v[154:157], v[196:199], v[70:73]
	v_mfma_f32_16x16x32_bf16 v[66:69], v[164:167], v[196:199], v[66:69]
	v_mfma_f32_16x16x32_bf16 v[118:121], v[160:163], v[176:179], v[118:121]
	v_mfma_f32_16x16x32_bf16 v[114:117], v[168:171], v[176:179], v[114:117]
	v_mfma_f32_16x16x32_bf16 v[102:105], v[160:163], v[184:187], v[102:105]
	v_mfma_f32_16x16x32_bf16 v[98:101], v[168:171], v[184:187], v[98:101]
	v_mfma_f32_16x16x32_bf16 v[86:89], v[160:163], v[192:195], v[86:89]
	v_mfma_f32_16x16x32_bf16 v[82:85], v[168:171], v[192:195], v[82:85]
	v_mfma_f32_16x16x32_bf16 v[70:73], v[160:163], v[200:203], v[70:73]
	v_mfma_f32_16x16x32_bf16 v[66:69], v[168:171], v[200:203], v[66:69]
	s_setprio 0
	s_barrier
	s_add_i32 s4, s69, s26
	ds_read_b128 v[172:175], v127 offset:16384
	ds_read_b128 v[176:179], v127 offset:17408
	ds_read_b128 v[180:183], v127 offset:18432
	ds_read_b128 v[184:187], v127 offset:19456
	ds_read_b128 v[188:191], v127 offset:20480
	ds_read_b128 v[192:195], v127 offset:21504
	ds_read_b128 v[196:199], v127 offset:22528
	ds_read_b128 v[200:203], v127 offset:23552
	s_mov_b32 m0, s4
	s_nop 0
	global_load_lds_dwordx4 v124, s[46:47]
	s_add_i32 m0, s4, 0x2000
	s_add_u32 s4, s46, 0xb0000
	global_load_lds_dwordx4 v125, s[46:47]
	s_addc_u32 s5, s47, 0
	s_add_i32 s69, s70, s26
	s_mov_b32 m0, s69
	s_nop 0
	global_load_lds_dwordx4 v124, s[4:5]
	s_add_i32 m0, s69, 0x2000
	s_nop 0
	global_load_lds_dwordx4 v125, s[4:5]
	s_mov_b32 m0, s41
	s_nop 0
	global_load_lds_dwordx4 v122, s[22:23]
	s_mov_b32 m0, s48
	s_nop 0
	global_load_lds_dwordx4 v123, s[22:23]
	s_waitcnt vmcnt(8)
	s_waitcnt lgkmcnt(0)
	s_barrier
	s_setprio 1
	s_waitcnt lgkmcnt(0)
	v_mfma_f32_16x16x32_bf16 v[62:65], v[128:131], v[172:175], v[62:65]
	v_mfma_f32_16x16x32_bf16 v[58:61], v[146:149], v[172:175], v[58:61]
	v_mfma_f32_16x16x32_bf16 v[46:49], v[128:131], v[180:183], v[46:49]
	v_mfma_f32_16x16x32_bf16 v[42:45], v[146:149], v[180:183], v[42:45]
	v_mfma_f32_16x16x32_bf16 v[30:33], v[128:131], v[188:191], v[30:33]
	v_mfma_f32_16x16x32_bf16 v[26:29], v[146:149], v[188:191], v[26:29]
	v_mfma_f32_16x16x32_bf16 v[14:17], v[128:131], v[196:199], v[14:17]
	v_mfma_f32_16x16x32_bf16 v[10:13], v[146:149], v[196:199], v[10:13]
	v_mfma_f32_16x16x32_bf16 v[62:65], v[142:145], v[176:179], v[62:65]
	v_mfma_f32_16x16x32_bf16 v[58:61], v[150:153], v[176:179], v[58:61]
	v_mfma_f32_16x16x32_bf16 v[46:49], v[142:145], v[184:187], v[46:49]
	v_mfma_f32_16x16x32_bf16 v[42:45], v[150:153], v[184:187], v[42:45]
	v_mfma_f32_16x16x32_bf16 v[30:33], v[142:145], v[192:195], v[30:33]
	v_mfma_f32_16x16x32_bf16 v[26:29], v[150:153], v[192:195], v[26:29]
	v_mfma_f32_16x16x32_bf16 v[14:17], v[142:145], v[200:203], v[14:17]
	v_mfma_f32_16x16x32_bf16 v[10:13], v[150:153], v[200:203], v[10:13]
	s_setprio 0
	s_setprio 1
	v_mfma_f32_16x16x32_bf16 v[54:57], v[154:157], v[172:175], v[54:57]
	v_mfma_f32_16x16x32_bf16 v[50:53], v[164:167], v[172:175], v[50:53]
	v_mfma_f32_16x16x32_bf16 v[38:41], v[154:157], v[180:183], v[38:41]
	v_mfma_f32_16x16x32_bf16 v[34:37], v[164:167], v[180:183], v[34:37]
	v_mfma_f32_16x16x32_bf16 v[22:25], v[154:157], v[188:191], v[22:25]
	v_mfma_f32_16x16x32_bf16 v[18:21], v[164:167], v[188:191], v[18:21]
	v_mfma_f32_16x16x32_bf16 v[6:9], v[154:157], v[196:199], v[6:9]
	v_mfma_f32_16x16x32_bf16 v[2:5], v[164:167], v[196:199], v[2:5]
	v_mfma_f32_16x16x32_bf16 v[54:57], v[160:163], v[176:179], v[54:57]
	v_mfma_f32_16x16x32_bf16 v[50:53], v[168:171], v[176:179], v[50:53]
	v_mfma_f32_16x16x32_bf16 v[38:41], v[160:163], v[184:187], v[38:41]
	v_mfma_f32_16x16x32_bf16 v[34:37], v[168:171], v[184:187], v[34:37]
	v_mfma_f32_16x16x32_bf16 v[22:25], v[160:163], v[192:195], v[22:25]
	v_mfma_f32_16x16x32_bf16 v[18:21], v[168:171], v[192:195], v[18:21]
	v_mfma_f32_16x16x32_bf16 v[6:9], v[160:163], v[200:203], v[6:9]
	v_mfma_f32_16x16x32_bf16 v[2:5], v[168:171], v[200:203], v[2:5]
	s_setprio 0
	s_barrier
	s_add_i32 s69, 0, 0x18000
	v_add_u32_e32 v0, s69, v126
	s_add_i32 s70, 0, 0x1c000
	ds_read_b128 v[128:131], v0
	ds_read_b128 v[142:145], v0 offset:1024
	ds_read_b128 v[146:149], v0 offset:2048
	ds_read_b128 v[150:153], v0 offset:3072
	v_add_u32_e32 v0, s70, v126
	ds_read_b128 v[154:157], v0
	ds_read_b128 v[160:163], v0 offset:1024
	ds_read_b128 v[164:167], v0 offset:2048
	ds_read_b128 v[168:171], v0 offset:3072
	s_add_u32 s4, s22, 0xb0000
	s_mov_b32 m0, s49
	ds_read_b128 v[172:175], v127 offset:32768
	ds_read_b128 v[176:179], v127 offset:33792
	ds_read_b128 v[180:183], v127 offset:34816
	ds_read_b128 v[184:187], v127 offset:35840
	ds_read_b128 v[188:191], v127 offset:36864
	ds_read_b128 v[192:195], v127 offset:37888
	ds_read_b128 v[196:199], v127 offset:38912
	ds_read_b128 v[200:203], v127 offset:39936
	s_addc_u32 s5, s23, 0
	s_nop 0
	global_load_lds_dwordx4 v122, s[4:5]
	s_mov_b32 m0, s50
	s_nop 0
	global_load_lds_dwordx4 v123, s[4:5]
	s_waitcnt vmcnt(8)
	s_waitcnt lgkmcnt(0)
	s_barrier
	s_setprio 1
	s_waitcnt lgkmcnt(0)
	v_mfma_f32_16x16x32_bf16 v[136:139], v[128:131], v[172:175], v[138:141]
	v_mfma_f32_16x16x32_bf16 v[132:135], v[146:149], v[172:175], v[132:135]
	v_mfma_f32_16x16x32_bf16 v[110:113], v[128:131], v[180:183], v[110:113]
	v_mfma_f32_16x16x32_bf16 v[106:109], v[146:149], v[180:183], v[106:109]
	v_mfma_f32_16x16x32_bf16 v[94:97], v[128:131], v[188:191], v[94:97]
	v_mfma_f32_16x16x32_bf16 v[90:93], v[146:149], v[188:191], v[90:93]
	v_mfma_f32_16x16x32_bf16 v[78:81], v[128:131], v[196:199], v[78:81]
	v_mfma_f32_16x16x32_bf16 v[74:77], v[146:149], v[196:199], v[74:77]
	v_mfma_f32_16x16x32_bf16 v[138:141], v[142:145], v[176:179], v[136:139]
	v_mfma_f32_16x16x32_bf16 v[134:137], v[150:153], v[176:179], v[132:135]
	v_mfma_f32_16x16x32_bf16 v[110:113], v[142:145], v[184:187], v[110:113]
	v_mfma_f32_16x16x32_bf16 v[106:109], v[150:153], v[184:187], v[106:109]
	v_mfma_f32_16x16x32_bf16 v[94:97], v[142:145], v[192:195], v[94:97]
	v_mfma_f32_16x16x32_bf16 v[90:93], v[150:153], v[192:195], v[90:93]
	v_mfma_f32_16x16x32_bf16 v[78:81], v[142:145], v[200:203], v[78:81]
	v_mfma_f32_16x16x32_bf16 v[74:77], v[150:153], v[200:203], v[74:77]
	s_setprio 0
	s_setprio 1
	v_mfma_f32_16x16x32_bf16 v[118:121], v[154:157], v[172:175], v[118:121]
	v_mfma_f32_16x16x32_bf16 v[114:117], v[164:167], v[172:175], v[114:117]
	v_mfma_f32_16x16x32_bf16 v[102:105], v[154:157], v[180:183], v[102:105]
	v_mfma_f32_16x16x32_bf16 v[98:101], v[164:167], v[180:183], v[98:101]
	v_mfma_f32_16x16x32_bf16 v[86:89], v[154:157], v[188:191], v[86:89]
	v_mfma_f32_16x16x32_bf16 v[82:85], v[164:167], v[188:191], v[82:85]
	v_mfma_f32_16x16x32_bf16 v[70:73], v[154:157], v[196:199], v[70:73]
	v_mfma_f32_16x16x32_bf16 v[66:69], v[164:167], v[196:199], v[66:69]
	v_mfma_f32_16x16x32_bf16 v[118:121], v[160:163], v[176:179], v[118:121]
	v_mfma_f32_16x16x32_bf16 v[114:117], v[168:171], v[176:179], v[114:117]
	v_mfma_f32_16x16x32_bf16 v[102:105], v[160:163], v[184:187], v[102:105]
	v_mfma_f32_16x16x32_bf16 v[98:101], v[168:171], v[184:187], v[98:101]
	v_mfma_f32_16x16x32_bf16 v[86:89], v[160:163], v[192:195], v[86:89]
	v_mfma_f32_16x16x32_bf16 v[82:85], v[168:171], v[192:195], v[82:85]
	v_mfma_f32_16x16x32_bf16 v[70:73], v[160:163], v[200:203], v[70:73]
	v_mfma_f32_16x16x32_bf16 v[66:69], v[168:171], v[200:203], v[66:69]
	s_setprio 0
	s_barrier
	v_mov_b32_e32 v0, v124
	ds_read_b128 v[172:175], v127 offset:49152
	ds_read_b128 v[176:179], v127 offset:50176
	ds_read_b128 v[180:183], v127 offset:51200
	ds_read_b128 v[184:187], v127 offset:52224
	ds_read_b128 v[188:191], v127 offset:53248
	ds_read_b128 v[192:195], v127 offset:54272
	ds_read_b128 v[196:199], v127 offset:55296
	ds_read_b128 v[200:203], v127 offset:56320
	s_add_i32 s4, s69, s26
	v_lshl_add_u64 v[132:133], s[46:47], 0, v[0:1]
	v_lshl_add_u64 v[132:133], v[132:133], 0, s[38:39]
	s_mov_b32 m0, s4
	v_mov_b32_e32 v0, v125
	global_load_lds_dwordx4 v[132:133], off
	s_add_i32 m0, s4, 0x2000
	s_add_u32 s4, s46, 0xb0080
	v_lshl_add_u64 v[132:133], s[46:47], 0, v[0:1]
	v_lshl_add_u64 v[132:133], v[132:133], 0, s[38:39]
	s_addc_u32 s5, s47, 0
	s_add_i32 s46, s70, s26
	global_load_lds_dwordx4 v[132:133], off
	s_mov_b32 m0, s46
	s_nop 0
	global_load_lds_dwordx4 v124, s[4:5]
	s_add_i32 m0, s46, 0x2000
	s_nop 0
	global_load_lds_dwordx4 v125, s[4:5]
	v_mov_b32_e32 v0, v122
	s_mov_b32 m0, s64
	v_lshl_add_u64 v[132:133], s[22:23], 0, v[0:1]
	v_lshl_add_u64 v[132:133], v[132:133], 0, s[38:39]
	v_mov_b32_e32 v0, v123
	global_load_lds_dwordx4 v[132:133], off
	s_mov_b32 m0, s65
	v_lshl_add_u64 v[132:133], s[22:23], 0, v[0:1]
	v_lshl_add_u64 v[132:133], v[132:133], 0, s[38:39]
	global_load_lds_dwordx4 v[132:133], off
	s_waitcnt vmcnt(8)
	s_waitcnt lgkmcnt(0)
	s_barrier
	s_setprio 1
	s_waitcnt lgkmcnt(0)
	v_mfma_f32_16x16x32_bf16 v[62:65], v[128:131], v[172:175], v[62:65]
	v_mfma_f32_16x16x32_bf16 v[58:61], v[146:149], v[172:175], v[58:61]
	v_mfma_f32_16x16x32_bf16 v[46:49], v[128:131], v[180:183], v[46:49]
	v_mfma_f32_16x16x32_bf16 v[42:45], v[146:149], v[180:183], v[42:45]
	v_mfma_f32_16x16x32_bf16 v[30:33], v[128:131], v[188:191], v[30:33]
	v_mfma_f32_16x16x32_bf16 v[26:29], v[146:149], v[188:191], v[26:29]
	v_mfma_f32_16x16x32_bf16 v[14:17], v[128:131], v[196:199], v[14:17]
	v_mfma_f32_16x16x32_bf16 v[10:13], v[146:149], v[196:199], v[10:13]
	v_mfma_f32_16x16x32_bf16 v[62:65], v[142:145], v[176:179], v[62:65]
	v_mfma_f32_16x16x32_bf16 v[58:61], v[150:153], v[176:179], v[58:61]
	v_mfma_f32_16x16x32_bf16 v[46:49], v[142:145], v[184:187], v[46:49]
	v_mfma_f32_16x16x32_bf16 v[42:45], v[150:153], v[184:187], v[42:45]
	v_mfma_f32_16x16x32_bf16 v[30:33], v[142:145], v[192:195], v[30:33]
	v_mfma_f32_16x16x32_bf16 v[26:29], v[150:153], v[192:195], v[26:29]
	v_mfma_f32_16x16x32_bf16 v[14:17], v[142:145], v[200:203], v[14:17]
	v_mfma_f32_16x16x32_bf16 v[10:13], v[150:153], v[200:203], v[10:13]
	s_setprio 0
	s_setprio 1
	v_mfma_f32_16x16x32_bf16 v[54:57], v[154:157], v[172:175], v[54:57]
	v_mfma_f32_16x16x32_bf16 v[50:53], v[164:167], v[172:175], v[50:53]
	v_mfma_f32_16x16x32_bf16 v[38:41], v[154:157], v[180:183], v[38:41]
	v_mfma_f32_16x16x32_bf16 v[34:37], v[164:167], v[180:183], v[34:37]
	v_mfma_f32_16x16x32_bf16 v[22:25], v[154:157], v[188:191], v[22:25]
	v_mfma_f32_16x16x32_bf16 v[18:21], v[164:167], v[188:191], v[18:21]
	v_mfma_f32_16x16x32_bf16 v[6:9], v[154:157], v[196:199], v[6:9]
	v_mfma_f32_16x16x32_bf16 v[2:5], v[164:167], v[196:199], v[2:5]
	v_mfma_f32_16x16x32_bf16 v[54:57], v[160:163], v[176:179], v[54:57]
	v_mfma_f32_16x16x32_bf16 v[50:53], v[168:171], v[176:179], v[50:53]
	v_mfma_f32_16x16x32_bf16 v[38:41], v[160:163], v[184:187], v[38:41]
	v_mfma_f32_16x16x32_bf16 v[34:37], v[168:171], v[184:187], v[34:37]
	v_mfma_f32_16x16x32_bf16 v[22:25], v[160:163], v[192:195], v[22:25]
	v_mfma_f32_16x16x32_bf16 v[18:21], v[168:171], v[192:195], v[18:21]
	v_mfma_f32_16x16x32_bf16 v[6:9], v[160:163], v[200:203], v[6:9]
	v_mfma_f32_16x16x32_bf16 v[2:5], v[168:171], v[200:203], v[2:5]
	s_setprio 0
	s_barrier
	s_add_i32 s68, s68, 2
	s_add_u32 s2, s2, 0x100
	s_addc_u32 s3, s3, 0
	s_cmp_gt_u32 s68, 41
	s_cbranch_scc0 .LBB0_869
	s_cmpk_lt_u32 s25, 0x100
	s_cbranch_scc0 .LBB0_872
	s_barrier

.LBB0_953:
	s_add_u32 s58, s4, s2
	s_addc_u32 s59, s5, s3
	s_add_u32 s14, s58, 0x100
	s_addc_u32 s15, s59, 0
	s_add_u32 s16, s43, s2
	s_addc_u32 s17, s46, s3
	s_add_i32 s51, 0, 0x10000
	s_cmp_eq_u32 s50, 40
	s_cselect_b32 s15, s5, s15
	s_cselect_b32 s14, s4, s14
	v_add_u32_e32 v0, s51, v135
	s_cselect_b32 s17, s7, s17
	s_cselect_b32 s16, s6, s16
	s_add_i32 s60, 0, 0x14000
	ds_read_b128 v[138:141], v0
	ds_read_b128 v[142:145], v0 offset:1024
	ds_read_b128 v[146:149], v0 offset:2048
	ds_read_b128 v[150:153], v0 offset:3072
	v_add_u32_e32 v0, s60, v135
	ds_read_b128 v[154:157], v0
	ds_read_b128 v[158:161], v0 offset:1024
	ds_read_b128 v[162:165], v0 offset:2048
	ds_read_b128 v[166:169], v0 offset:3072
	v_mov_b32_e32 v0, v130
	ds_read_b128 v[170:173], v136
	ds_read_b128 v[174:177], v136 offset:1024
	ds_read_b128 v[178:181], v136 offset:2048
	ds_read_b128 v[182:185], v136 offset:3072
	ds_read_b128 v[186:189], v136 offset:4096
	ds_read_b128 v[190:193], v136 offset:5120
	ds_read_b128 v[194:197], v136 offset:6144
	ds_read_b128 v[198:201], v136 offset:7168
	s_add_i32 m0, s37, 0xc000
	v_lshl_add_u64 v[202:203], s[58:59], 0, v[0:1]
	v_lshl_add_u64 v[202:203], v[202:203], 0, s[62:63]
	v_mov_b32_e32 v0, v131
	global_load_lds_dwordx4 v[202:203], off
	s_add_i32 m0, s37, 0xe000
	v_lshl_add_u64 v[202:203], s[58:59], 0, v[0:1]
	v_lshl_add_u64 v[202:203], v[202:203], 0, s[62:63]
	global_load_lds_dwordx4 v[202:203], off
	s_waitcnt vmcnt(8)
	s_waitcnt lgkmcnt(0)
	s_barrier
	s_setprio 1
	s_waitcnt lgkmcnt(0)
	v_mfma_f32_16x16x32_bf16 v[126:129], v[138:141], v[170:173], v[126:129]
	v_mfma_f32_16x16x32_bf16 v[122:125], v[146:149], v[170:173], v[122:125]
	v_mfma_f32_16x16x32_bf16 v[110:113], v[138:141], v[178:181], v[110:113]
	v_mfma_f32_16x16x32_bf16 v[106:109], v[146:149], v[178:181], v[106:109]
	v_mfma_f32_16x16x32_bf16 v[94:97], v[138:141], v[186:189], v[94:97]
	v_mfma_f32_16x16x32_bf16 v[90:93], v[146:149], v[186:189], v[90:93]
	v_mfma_f32_16x16x32_bf16 v[78:81], v[138:141], v[194:197], v[78:81]
	v_mfma_f32_16x16x32_bf16 v[74:77], v[146:149], v[194:197], v[74:77]
	v_mfma_f32_16x16x32_bf16 v[126:129], v[142:145], v[174:177], v[126:129]
	v_mfma_f32_16x16x32_bf16 v[122:125], v[150:153], v[174:177], v[122:125]
	v_mfma_f32_16x16x32_bf16 v[110:113], v[142:145], v[182:185], v[110:113]
	v_mfma_f32_16x16x32_bf16 v[106:109], v[150:153], v[182:185], v[106:109]
	v_mfma_f32_16x16x32_bf16 v[94:97], v[142:145], v[190:193], v[94:97]
	v_mfma_f32_16x16x32_bf16 v[90:93], v[150:153], v[190:193], v[90:93]
	v_mfma_f32_16x16x32_bf16 v[78:81], v[142:145], v[198:201], v[78:81]
	v_mfma_f32_16x16x32_bf16 v[74:77], v[150:153], v[198:201], v[74:77]
	s_setprio 0
	s_setprio 1
	v_mfma_f32_16x16x32_bf16 v[118:121], v[154:157], v[170:173], v[118:121]
	v_mfma_f32_16x16x32_bf16 v[114:117], v[162:165], v[170:173], v[114:117]
	v_mfma_f32_16x16x32_bf16 v[102:105], v[154:157], v[178:181], v[102:105]
	v_mfma_f32_16x16x32_bf16 v[98:101], v[162:165], v[178:181], v[98:101]
	v_mfma_f32_16x16x32_bf16 v[86:89], v[154:157], v[186:189], v[86:89]
	v_mfma_f32_16x16x32_bf16 v[82:85], v[162:165], v[186:189], v[82:85]
	v_mfma_f32_16x16x32_bf16 v[70:73], v[154:157], v[194:197], v[70:73]
	v_mfma_f32_16x16x32_bf16 v[66:69], v[162:165], v[194:197], v[66:69]
	v_mfma_f32_16x16x32_bf16 v[118:121], v[158:161], v[174:177], v[118:121]
	v_mfma_f32_16x16x32_bf16 v[114:117], v[166:169], v[174:177], v[114:117]
	v_mfma_f32_16x16x32_bf16 v[102:105], v[158:161], v[182:185], v[102:105]
	v_mfma_f32_16x16x32_bf16 v[98:101], v[166:169], v[182:185], v[98:101]
	v_mfma_f32_16x16x32_bf16 v[86:89], v[158:161], v[190:193], v[86:89]
	v_mfma_f32_16x16x32_bf16 v[82:85], v[166:169], v[190:193], v[82:85]
	v_mfma_f32_16x16x32_bf16 v[70:73], v[158:161], v[198:201], v[70:73]
	v_mfma_f32_16x16x32_bf16 v[66:69], v[166:169], v[198:201], v[66:69]
	s_setprio 0
	s_barrier
	s_add_i32 s51, s51, s26
	ds_read_b128 v[170:173], v136 offset:16384
	ds_read_b128 v[174:177], v136 offset:17408
	ds_read_b128 v[178:181], v136 offset:18432
	ds_read_b128 v[182:185], v136 offset:19456
	ds_read_b128 v[186:189], v136 offset:20480
	ds_read_b128 v[190:193], v136 offset:21504
	ds_read_b128 v[194:197], v136 offset:22528
	ds_read_b128 v[198:201], v136 offset:23552
	s_mov_b32 m0, s51
	s_nop 0
	global_load_lds_dwordx4 v133, s[16:17]
	s_add_i32 m0, s51, 0x2000
	s_add_u32 s58, s16, 0xb0000
	global_load_lds_dwordx4 v134, s[16:17]
	s_addc_u32 s59, s17, 0
	s_add_i32 s51, s60, s26
	s_mov_b32 m0, s51
	s_nop 0
	global_load_lds_dwordx4 v133, s[58:59]
	s_add_i32 m0, s51, 0x2000
	s_nop 0
	global_load_lds_dwordx4 v134, s[58:59]
	s_mov_b32 m0, s37
	s_nop 0
	global_load_lds_dwordx4 v130, s[14:15]
	s_mov_b32 m0, s40
	s_nop 0
	global_load_lds_dwordx4 v131, s[14:15]
	s_waitcnt vmcnt(8)
	s_waitcnt lgkmcnt(0)
	s_barrier
	s_setprio 1
	s_waitcnt lgkmcnt(0)
	v_mfma_f32_16x16x32_bf16 v[62:65], v[138:141], v[170:173], v[62:65]
	v_mfma_f32_16x16x32_bf16 v[58:61], v[146:149], v[170:173], v[58:61]
	v_mfma_f32_16x16x32_bf16 v[46:49], v[138:141], v[178:181], v[46:49]
	v_mfma_f32_16x16x32_bf16 v[42:45], v[146:149], v[178:181], v[42:45]
	v_mfma_f32_16x16x32_bf16 v[30:33], v[138:141], v[186:189], v[30:33]
	v_mfma_f32_16x16x32_bf16 v[26:29], v[146:149], v[186:189], v[26:29]
	v_mfma_f32_16x16x32_bf16 v[14:17], v[138:141], v[194:197], v[14:17]
	v_mfma_f32_16x16x32_bf16 v[10:13], v[146:149], v[194:197], v[10:13]
	v_mfma_f32_16x16x32_bf16 v[62:65], v[142:145], v[174:177], v[62:65]
	v_mfma_f32_16x16x32_bf16 v[58:61], v[150:153], v[174:177], v[58:61]
	v_mfma_f32_16x16x32_bf16 v[46:49], v[142:145], v[182:185], v[46:49]
	v_mfma_f32_16x16x32_bf16 v[42:45], v[150:153], v[182:185], v[42:45]
	v_mfma_f32_16x16x32_bf16 v[30:33], v[142:145], v[190:193], v[30:33]
	v_mfma_f32_16x16x32_bf16 v[26:29], v[150:153], v[190:193], v[26:29]
	v_mfma_f32_16x16x32_bf16 v[14:17], v[142:145], v[198:201], v[14:17]
	v_mfma_f32_16x16x32_bf16 v[10:13], v[150:153], v[198:201], v[10:13]
	s_setprio 0
	s_setprio 1
	v_mfma_f32_16x16x32_bf16 v[54:57], v[154:157], v[170:173], v[54:57]
	v_mfma_f32_16x16x32_bf16 v[50:53], v[162:165], v[170:173], v[50:53]
	v_mfma_f32_16x16x32_bf16 v[38:41], v[154:157], v[178:181], v[38:41]
	v_mfma_f32_16x16x32_bf16 v[34:37], v[162:165], v[178:181], v[34:37]
	v_mfma_f32_16x16x32_bf16 v[22:25], v[154:157], v[186:189], v[22:25]
	v_mfma_f32_16x16x32_bf16 v[18:21], v[162:165], v[186:189], v[18:21]
	v_mfma_f32_16x16x32_bf16 v[6:9], v[154:157], v[194:197], v[6:9]
	v_mfma_f32_16x16x32_bf16 v[2:5], v[162:165], v[194:197], v[2:5]
	v_mfma_f32_16x16x32_bf16 v[54:57], v[158:161], v[174:177], v[54:57]
	v_mfma_f32_16x16x32_bf16 v[50:53], v[166:169], v[174:177], v[50:53]
	v_mfma_f32_16x16x32_bf16 v[38:41], v[158:161], v[182:185], v[38:41]
	v_mfma_f32_16x16x32_bf16 v[34:37], v[166:169], v[182:185], v[34:37]
	v_mfma_f32_16x16x32_bf16 v[22:25], v[158:161], v[190:193], v[22:25]
	v_mfma_f32_16x16x32_bf16 v[18:21], v[166:169], v[190:193], v[18:21]
	v_mfma_f32_16x16x32_bf16 v[6:9], v[158:161], v[198:201], v[6:9]
	v_mfma_f32_16x16x32_bf16 v[2:5], v[166:169], v[198:201], v[2:5]
	s_setprio 0
	s_barrier
	s_add_i32 s51, 0, 0x18000
	v_add_u32_e32 v0, s51, v135
	s_add_i32 s60, 0, 0x1c000
	ds_read_b128 v[138:141], v0
	ds_read_b128 v[142:145], v0 offset:1024
	ds_read_b128 v[146:149], v0 offset:2048
	ds_read_b128 v[150:153], v0 offset:3072
	v_add_u32_e32 v0, s60, v135
	ds_read_b128 v[154:157], v0
	ds_read_b128 v[158:161], v0 offset:1024
	ds_read_b128 v[162:165], v0 offset:2048
	ds_read_b128 v[166:169], v0 offset:3072
	s_add_u32 s58, s14, 0xb0000
	s_mov_b32 m0, s41
	ds_read_b128 v[170:173], v136 offset:32768
	ds_read_b128 v[174:177], v136 offset:33792
	ds_read_b128 v[178:181], v136 offset:34816
	ds_read_b128 v[182:185], v136 offset:35840
	ds_read_b128 v[186:189], v136 offset:36864
	ds_read_b128 v[190:193], v136 offset:37888
	ds_read_b128 v[194:197], v136 offset:38912
	ds_read_b128 v[198:201], v136 offset:39936
	s_addc_u32 s59, s15, 0
	s_nop 0
	global_load_lds_dwordx4 v130, s[58:59]
	s_mov_b32 m0, s42
	s_nop 0
	global_load_lds_dwordx4 v131, s[58:59]
	s_waitcnt vmcnt(8)
	s_waitcnt lgkmcnt(0)
	s_barrier
	s_setprio 1
	s_waitcnt lgkmcnt(0)
	v_mfma_f32_16x16x32_bf16 v[126:129], v[138:141], v[170:173], v[126:129]
	v_mfma_f32_16x16x32_bf16 v[122:125], v[146:149], v[170:173], v[122:125]
	v_mfma_f32_16x16x32_bf16 v[110:113], v[138:141], v[178:181], v[110:113]
	v_mfma_f32_16x16x32_bf16 v[106:109], v[146:149], v[178:181], v[106:109]
	v_mfma_f32_16x16x32_bf16 v[94:97], v[138:141], v[186:189], v[94:97]
	v_mfma_f32_16x16x32_bf16 v[90:93], v[146:149], v[186:189], v[90:93]
	v_mfma_f32_16x16x32_bf16 v[78:81], v[138:141], v[194:197], v[78:81]
	v_mfma_f32_16x16x32_bf16 v[74:77], v[146:149], v[194:197], v[74:77]
	v_mfma_f32_16x16x32_bf16 v[126:129], v[142:145], v[174:177], v[126:129]
	v_mfma_f32_16x16x32_bf16 v[122:125], v[150:153], v[174:177], v[122:125]
	v_mfma_f32_16x16x32_bf16 v[110:113], v[142:145], v[182:185], v[110:113]
	v_mfma_f32_16x16x32_bf16 v[106:109], v[150:153], v[182:185], v[106:109]
	v_mfma_f32_16x16x32_bf16 v[94:97], v[142:145], v[190:193], v[94:97]
	v_mfma_f32_16x16x32_bf16 v[90:93], v[150:153], v[190:193], v[90:93]
	v_mfma_f32_16x16x32_bf16 v[78:81], v[142:145], v[198:201], v[78:81]
	v_mfma_f32_16x16x32_bf16 v[74:77], v[150:153], v[198:201], v[74:77]
	s_setprio 0
	s_setprio 1
	v_mfma_f32_16x16x32_bf16 v[118:121], v[154:157], v[170:173], v[118:121]
	v_mfma_f32_16x16x32_bf16 v[114:117], v[162:165], v[170:173], v[114:117]
	v_mfma_f32_16x16x32_bf16 v[102:105], v[154:157], v[178:181], v[102:105]
	v_mfma_f32_16x16x32_bf16 v[98:101], v[162:165], v[178:181], v[98:101]
	v_mfma_f32_16x16x32_bf16 v[86:89], v[154:157], v[186:189], v[86:89]
	v_mfma_f32_16x16x32_bf16 v[82:85], v[162:165], v[186:189], v[82:85]
	v_mfma_f32_16x16x32_bf16 v[70:73], v[154:157], v[194:197], v[70:73]
	v_mfma_f32_16x16x32_bf16 v[66:69], v[162:165], v[194:197], v[66:69]
	v_mfma_f32_16x16x32_bf16 v[118:121], v[158:161], v[174:177], v[118:121]
	v_mfma_f32_16x16x32_bf16 v[114:117], v[166:169], v[174:177], v[114:117]
	v_mfma_f32_16x16x32_bf16 v[102:105], v[158:161], v[182:185], v[102:105]
	v_mfma_f32_16x16x32_bf16 v[98:101], v[166:169], v[182:185], v[98:101]
	v_mfma_f32_16x16x32_bf16 v[86:89], v[158:161], v[190:193], v[86:89]
	v_mfma_f32_16x16x32_bf16 v[82:85], v[166:169], v[190:193], v[82:85]
	v_mfma_f32_16x16x32_bf16 v[70:73], v[158:161], v[198:201], v[70:73]
	v_mfma_f32_16x16x32_bf16 v[66:69], v[166:169], v[198:201], v[66:69]
	s_setprio 0
	s_barrier
	v_mov_b32_e32 v0, v133
	ds_read_b128 v[170:173], v136 offset:49152
	ds_read_b128 v[174:177], v136 offset:50176
	ds_read_b128 v[178:181], v136 offset:51200
	ds_read_b128 v[182:185], v136 offset:52224
	ds_read_b128 v[186:189], v136 offset:53248
	ds_read_b128 v[190:193], v136 offset:54272
	ds_read_b128 v[194:197], v136 offset:55296
	ds_read_b128 v[198:201], v136 offset:56320
	s_add_i32 s51, s51, s26
	v_lshl_add_u64 v[202:203], s[16:17], 0, v[0:1]
	v_lshl_add_u64 v[202:203], v[202:203], 0, s[38:39]
	s_mov_b32 m0, s51
	v_mov_b32_e32 v0, v134
	global_load_lds_dwordx4 v[202:203], off
	s_add_i32 m0, s51, 0x2000
	s_nop 0
	v_lshl_add_u64 v[202:203], s[16:17], 0, v[0:1]
	s_add_u32 s16, s16, 0xb0080
	v_lshl_add_u64 v[202:203], v[202:203], 0, s[38:39]
	s_addc_u32 s17, s17, 0
	s_add_i32 s51, s60, s26
	global_load_lds_dwordx4 v[202:203], off
	s_mov_b32 m0, s51
	s_nop 0
	global_load_lds_dwordx4 v133, s[16:17]
	s_add_i32 m0, s51, 0x2000
	s_nop 0
	global_load_lds_dwordx4 v134, s[16:17]
	v_mov_b32_e32 v0, v130
	s_mov_b32 m0, s48
	v_lshl_add_u64 v[202:203], s[14:15], 0, v[0:1]
	v_lshl_add_u64 v[202:203], v[202:203], 0, s[38:39]
	v_mov_b32_e32 v0, v131
	global_load_lds_dwordx4 v[202:203], off
	s_mov_b32 m0, s49
	v_lshl_add_u64 v[202:203], s[14:15], 0, v[0:1]
	v_lshl_add_u64 v[202:203], v[202:203], 0, s[38:39]
	global_load_lds_dwordx4 v[202:203], off
	s_waitcnt vmcnt(8)
	s_waitcnt lgkmcnt(0)
	s_barrier
	s_setprio 1
	s_waitcnt lgkmcnt(0)
	v_mfma_f32_16x16x32_bf16 v[62:65], v[138:141], v[170:173], v[62:65]
	v_mfma_f32_16x16x32_bf16 v[58:61], v[146:149], v[170:173], v[58:61]
	v_mfma_f32_16x16x32_bf16 v[46:49], v[138:141], v[178:181], v[46:49]
	v_mfma_f32_16x16x32_bf16 v[42:45], v[146:149], v[178:181], v[42:45]
	v_mfma_f32_16x16x32_bf16 v[30:33], v[138:141], v[186:189], v[30:33]
	v_mfma_f32_16x16x32_bf16 v[26:29], v[146:149], v[186:189], v[26:29]
	v_mfma_f32_16x16x32_bf16 v[14:17], v[138:141], v[194:197], v[14:17]
	v_mfma_f32_16x16x32_bf16 v[10:13], v[146:149], v[194:197], v[10:13]
	v_mfma_f32_16x16x32_bf16 v[62:65], v[142:145], v[174:177], v[62:65]
	v_mfma_f32_16x16x32_bf16 v[58:61], v[150:153], v[174:177], v[58:61]
	v_mfma_f32_16x16x32_bf16 v[46:49], v[142:145], v[182:185], v[46:49]
	v_mfma_f32_16x16x32_bf16 v[42:45], v[150:153], v[182:185], v[42:45]
	v_mfma_f32_16x16x32_bf16 v[30:33], v[142:145], v[190:193], v[30:33]
	v_mfma_f32_16x16x32_bf16 v[26:29], v[150:153], v[190:193], v[26:29]
	v_mfma_f32_16x16x32_bf16 v[14:17], v[142:145], v[198:201], v[14:17]
	v_mfma_f32_16x16x32_bf16 v[10:13], v[150:153], v[198:201], v[10:13]
	s_setprio 0
	s_setprio 1
	v_mfma_f32_16x16x32_bf16 v[54:57], v[154:157], v[170:173], v[54:57]
	v_mfma_f32_16x16x32_bf16 v[50:53], v[162:165], v[170:173], v[50:53]
	v_mfma_f32_16x16x32_bf16 v[38:41], v[154:157], v[178:181], v[38:41]
	v_mfma_f32_16x16x32_bf16 v[34:37], v[162:165], v[178:181], v[34:37]
	v_mfma_f32_16x16x32_bf16 v[22:25], v[154:157], v[186:189], v[22:25]
	v_mfma_f32_16x16x32_bf16 v[18:21], v[162:165], v[186:189], v[18:21]
	v_mfma_f32_16x16x32_bf16 v[6:9], v[154:157], v[194:197], v[6:9]
	v_mfma_f32_16x16x32_bf16 v[2:5], v[162:165], v[194:197], v[2:5]
	v_mfma_f32_16x16x32_bf16 v[54:57], v[158:161], v[174:177], v[54:57]
	v_mfma_f32_16x16x32_bf16 v[50:53], v[166:169], v[174:177], v[50:53]
	v_mfma_f32_16x16x32_bf16 v[38:41], v[158:161], v[182:185], v[38:41]
	v_mfma_f32_16x16x32_bf16 v[34:37], v[166:169], v[182:185], v[34:37]
	v_mfma_f32_16x16x32_bf16 v[22:25], v[158:161], v[190:193], v[22:25]
	v_mfma_f32_16x16x32_bf16 v[18:21], v[166:169], v[190:193], v[18:21]
	v_mfma_f32_16x16x32_bf16 v[6:9], v[158:161], v[198:201], v[6:9]
	v_mfma_f32_16x16x32_bf16 v[2:5], v[166:169], v[198:201], v[2:5]
	s_setprio 0
	s_barrier
	s_add_i32 s50, s50, 2
	s_add_u32 s2, s2, 0x100
	s_addc_u32 s3, s3, 0
	s_cmp_gt_u32 s50, 41
	s_cbranch_scc0 .LBB0_953
	s_cmpk_lt_u32 s25, 0x100
	s_cbranch_scc0 .LBB0_956
	s_barrier

.LBB0_1087:
	s_add_u32 s2, s6, 0x40080
	s_addc_u32 s3, s7, 0
	s_add_u32 s8, s8, 0x100
	s_addc_u32 s9, s9, 0
	s_mov_b32 s22, -2
	s_add_u32 s4, s2, 0xfffc0080
	s_addc_u32 s5, s3, -1
	s_add_i32 s23, 0, 0x10000
	s_cmp_eq_u32 s22, 12
	s_cselect_b32 s5, s49, s5
	s_cselect_b32 s4, s48, s4
	s_waitcnt vmcnt(0)
	v_add_u32_e32 v0, s23, v145
	s_cselect_b32 s7, s97, s9
	s_cselect_b32 s6, s96, s8
	s_add_i32 s25, 0, 0x14000
	ds_read_b128 v[146:149], v0
	ds_read_b128 v[152:155], v0 offset:1024
	ds_read_b128 v[156:159], v0 offset:2048
	ds_read_b128 v[160:163], v0 offset:3072
	v_add_u32_e32 v0, s25, v145
	ds_read_b128 v[164:167], v0
	ds_read_b128 v[168:171], v0 offset:1024
	ds_read_b128 v[172:175], v0 offset:2048
	ds_read_b128 v[176:179], v0 offset:3072
	ds_read_b128 v[180:183], v150
	ds_read_b128 v[184:187], v150 offset:1024
	ds_read_b128 v[188:191], v150 offset:2048
	ds_read_b128 v[192:195], v150 offset:3072
	ds_read_b128 v[196:199], v150 offset:4096
	ds_read_b128 v[200:203], v150 offset:5120
	ds_read_b128 v[204:207], v150 offset:6144
	ds_read_b128 v[208:211], v150 offset:7168
	s_add_i32 m0, s60, 0xc000
	s_nop 0
	global_load_lds_dwordx4 v131, s[2:3]
	s_add_i32 m0, s60, 0xe000
	s_nop 0
	global_load_lds_dwordx4 v133, s[2:3]
	s_waitcnt vmcnt(8)
	s_waitcnt lgkmcnt(0)
	s_barrier
	s_setprio 1
	s_waitcnt lgkmcnt(0)
	v_mfma_f32_16x16x32_bf16 v[126:129], v[146:149], v[180:183], 0
	v_mfma_f32_16x16x32_bf16 v[122:125], v[156:159], v[180:183], 0
	v_mfma_f32_16x16x32_bf16 v[110:113], v[146:149], v[188:191], 0
	v_mfma_f32_16x16x32_bf16 v[106:109], v[156:159], v[188:191], 0
	v_mfma_f32_16x16x32_bf16 v[94:97], v[146:149], v[196:199], 0
	v_mfma_f32_16x16x32_bf16 v[90:93], v[156:159], v[196:199], 0
	v_mfma_f32_16x16x32_bf16 v[78:81], v[146:149], v[204:207], 0
	v_mfma_f32_16x16x32_bf16 v[74:77], v[156:159], v[204:207], 0
	v_mfma_f32_16x16x32_bf16 v[126:129], v[152:155], v[184:187], v[126:129]
	v_mfma_f32_16x16x32_bf16 v[122:125], v[160:163], v[184:187], v[122:125]
	v_mfma_f32_16x16x32_bf16 v[110:113], v[152:155], v[192:195], v[110:113]
	v_mfma_f32_16x16x32_bf16 v[106:109], v[160:163], v[192:195], v[106:109]
	v_mfma_f32_16x16x32_bf16 v[94:97], v[152:155], v[200:203], v[94:97]
	v_mfma_f32_16x16x32_bf16 v[90:93], v[160:163], v[200:203], v[90:93]
	v_mfma_f32_16x16x32_bf16 v[78:81], v[152:155], v[208:211], v[78:81]
	v_mfma_f32_16x16x32_bf16 v[74:77], v[160:163], v[208:211], v[74:77]
	s_setprio 0
	s_setprio 1
	v_mfma_f32_16x16x32_bf16 v[118:121], v[164:167], v[180:183], 0
	v_mfma_f32_16x16x32_bf16 v[114:117], v[172:175], v[180:183], 0
	v_mfma_f32_16x16x32_bf16 v[102:105], v[164:167], v[188:191], 0
	v_mfma_f32_16x16x32_bf16 v[98:101], v[172:175], v[188:191], 0
	v_mfma_f32_16x16x32_bf16 v[86:89], v[164:167], v[196:199], 0
	v_mfma_f32_16x16x32_bf16 v[82:85], v[172:175], v[196:199], 0
	v_mfma_f32_16x16x32_bf16 v[70:73], v[164:167], v[204:207], 0
	v_mfma_f32_16x16x32_bf16 v[66:69], v[172:175], v[204:207], 0
	v_mfma_f32_16x16x32_bf16 v[118:121], v[168:171], v[184:187], v[118:121]
	v_mfma_f32_16x16x32_bf16 v[114:117], v[176:179], v[184:187], v[114:117]
	v_mfma_f32_16x16x32_bf16 v[102:105], v[168:171], v[192:195], v[102:105]
	v_mfma_f32_16x16x32_bf16 v[98:101], v[176:179], v[192:195], v[98:101]
	v_mfma_f32_16x16x32_bf16 v[86:89], v[168:171], v[200:203], v[86:89]
	v_mfma_f32_16x16x32_bf16 v[82:85], v[176:179], v[200:203], v[82:85]
	v_mfma_f32_16x16x32_bf16 v[70:73], v[168:171], v[208:211], v[70:73]
	v_mfma_f32_16x16x32_bf16 v[66:69], v[176:179], v[208:211], v[66:69]
	s_setprio 0
	s_barrier
	s_add_i32 s23, s23, s42
	ds_read_b128 v[180:183], v150 offset:16384
	ds_read_b128 v[184:187], v150 offset:17408
	ds_read_b128 v[188:191], v150 offset:18432
	ds_read_b128 v[192:195], v150 offset:19456
	ds_read_b128 v[196:199], v150 offset:20480
	ds_read_b128 v[200:203], v150 offset:21504
	ds_read_b128 v[204:207], v150 offset:22528
	ds_read_b128 v[208:211], v150 offset:23552
	s_mov_b32 m0, s23
	s_nop 0
	global_load_lds_dwordx4 v137, s[6:7]
	s_add_i32 m0, s23, 0x2000
	s_add_u32 s46, s6, 0x40000
	global_load_lds_dwordx4 v139, s[6:7]
	s_addc_u32 s47, s7, 0
	s_add_i32 s23, s25, s42
	s_mov_b32 m0, s23
	s_nop 0
	global_load_lds_dwordx4 v137, s[46:47]
	s_add_i32 m0, s23, 0x2000
	s_nop 0
	global_load_lds_dwordx4 v139, s[46:47]
	s_mov_b32 m0, s60
	s_nop 0
	global_load_lds_dwordx4 v131, s[4:5]
	s_mov_b32 m0, s61
	s_nop 0
	global_load_lds_dwordx4 v133, s[4:5]
	s_waitcnt vmcnt(8)
	s_waitcnt lgkmcnt(0)
	s_barrier
	s_setprio 1
	s_waitcnt lgkmcnt(0)
	v_mfma_f32_16x16x32_bf16 v[62:65], v[146:149], v[180:183], 0
	v_mfma_f32_16x16x32_bf16 v[58:61], v[156:159], v[180:183], 0
	v_mfma_f32_16x16x32_bf16 v[46:49], v[146:149], v[188:191], 0
	v_mfma_f32_16x16x32_bf16 v[42:45], v[156:159], v[188:191], 0
	v_mfma_f32_16x16x32_bf16 v[30:33], v[146:149], v[196:199], 0
	v_mfma_f32_16x16x32_bf16 v[26:29], v[156:159], v[196:199], 0
	v_mfma_f32_16x16x32_bf16 v[14:17], v[146:149], v[204:207], 0
	v_mfma_f32_16x16x32_bf16 v[10:13], v[156:159], v[204:207], 0
	v_mfma_f32_16x16x32_bf16 v[62:65], v[152:155], v[184:187], v[62:65]
	v_mfma_f32_16x16x32_bf16 v[58:61], v[160:163], v[184:187], v[58:61]
	v_mfma_f32_16x16x32_bf16 v[46:49], v[152:155], v[192:195], v[46:49]
	v_mfma_f32_16x16x32_bf16 v[42:45], v[160:163], v[192:195], v[42:45]
	v_mfma_f32_16x16x32_bf16 v[30:33], v[152:155], v[200:203], v[30:33]
	v_mfma_f32_16x16x32_bf16 v[26:29], v[160:163], v[200:203], v[26:29]
	v_mfma_f32_16x16x32_bf16 v[14:17], v[152:155], v[208:211], v[14:17]
	v_mfma_f32_16x16x32_bf16 v[10:13], v[160:163], v[208:211], v[10:13]
	s_setprio 0
	s_setprio 1
	v_mfma_f32_16x16x32_bf16 v[54:57], v[164:167], v[180:183], 0
	v_mfma_f32_16x16x32_bf16 v[50:53], v[172:175], v[180:183], 0
	v_mfma_f32_16x16x32_bf16 v[38:41], v[164:167], v[188:191], 0
	v_mfma_f32_16x16x32_bf16 v[34:37], v[172:175], v[188:191], 0
	v_mfma_f32_16x16x32_bf16 v[22:25], v[164:167], v[196:199], 0
	v_mfma_f32_16x16x32_bf16 v[18:21], v[172:175], v[196:199], 0
	v_mfma_f32_16x16x32_bf16 v[6:9], v[164:167], v[204:207], 0
	v_mfma_f32_16x16x32_bf16 v[2:5], v[172:175], v[204:207], 0
	v_mfma_f32_16x16x32_bf16 v[54:57], v[168:171], v[184:187], v[54:57]
	v_mfma_f32_16x16x32_bf16 v[50:53], v[176:179], v[184:187], v[50:53]
	v_mfma_f32_16x16x32_bf16 v[38:41], v[168:171], v[192:195], v[38:41]
	v_mfma_f32_16x16x32_bf16 v[34:37], v[176:179], v[192:195], v[34:37]
	v_mfma_f32_16x16x32_bf16 v[22:25], v[168:171], v[200:203], v[22:25]
	v_mfma_f32_16x16x32_bf16 v[18:21], v[176:179], v[200:203], v[18:21]
	v_mfma_f32_16x16x32_bf16 v[6:9], v[168:171], v[208:211], v[6:9]
	v_mfma_f32_16x16x32_bf16 v[2:5], v[176:179], v[208:211], v[2:5]
	s_setprio 0
	s_barrier
	s_add_i32 s23, 0, 0x18000
	v_add_u32_e32 v0, s23, v145
	s_add_i32 s25, 0, 0x1c000
	ds_read_b128 v[146:149], v0
	ds_read_b128 v[152:155], v0 offset:1024
	ds_read_b128 v[156:159], v0 offset:2048
	ds_read_b128 v[160:163], v0 offset:3072
	v_add_u32_e32 v0, s25, v145
	ds_read_b128 v[164:167], v0
	ds_read_b128 v[168:171], v0 offset:1024
	ds_read_b128 v[172:175], v0 offset:2048
	ds_read_b128 v[176:179], v0 offset:3072
	s_add_u32 s46, s4, 0x40000
	s_mov_b32 m0, s66
	ds_read_b128 v[180:183], v150 offset:32768
	ds_read_b128 v[184:187], v150 offset:33792
	ds_read_b128 v[188:191], v150 offset:34816
	ds_read_b128 v[192:195], v150 offset:35840
	ds_read_b128 v[196:199], v150 offset:36864
	ds_read_b128 v[200:203], v150 offset:37888
	ds_read_b128 v[204:207], v150 offset:38912
	ds_read_b128 v[208:211], v150 offset:39936
	s_addc_u32 s47, s5, 0
	s_nop 0
	global_load_lds_dwordx4 v131, s[46:47]
	s_mov_b32 m0, s67
	s_nop 0
	global_load_lds_dwordx4 v133, s[46:47]
	s_waitcnt vmcnt(8)
	s_waitcnt lgkmcnt(0)
	s_barrier
	s_setprio 1
	s_waitcnt lgkmcnt(0)
	v_mfma_f32_16x16x32_bf16 v[126:129], v[146:149], v[180:183], v[126:129]
	v_mfma_f32_16x16x32_bf16 v[122:125], v[156:159], v[180:183], v[122:125]
	v_mfma_f32_16x16x32_bf16 v[110:113], v[146:149], v[188:191], v[110:113]
	v_mfma_f32_16x16x32_bf16 v[106:109], v[156:159], v[188:191], v[106:109]
	v_mfma_f32_16x16x32_bf16 v[94:97], v[146:149], v[196:199], v[94:97]
	v_mfma_f32_16x16x32_bf16 v[90:93], v[156:159], v[196:199], v[90:93]
	v_mfma_f32_16x16x32_bf16 v[78:81], v[146:149], v[204:207], v[78:81]
	v_mfma_f32_16x16x32_bf16 v[74:77], v[156:159], v[204:207], v[74:77]
	v_mfma_f32_16x16x32_bf16 v[126:129], v[152:155], v[184:187], v[126:129]
	v_mfma_f32_16x16x32_bf16 v[122:125], v[160:163], v[184:187], v[122:125]
	v_mfma_f32_16x16x32_bf16 v[110:113], v[152:155], v[192:195], v[110:113]
	v_mfma_f32_16x16x32_bf16 v[106:109], v[160:163], v[192:195], v[106:109]
	v_mfma_f32_16x16x32_bf16 v[94:97], v[152:155], v[200:203], v[94:97]
	v_mfma_f32_16x16x32_bf16 v[90:93], v[160:163], v[200:203], v[90:93]
	v_mfma_f32_16x16x32_bf16 v[78:81], v[152:155], v[208:211], v[78:81]
	v_mfma_f32_16x16x32_bf16 v[74:77], v[160:163], v[208:211], v[74:77]
	s_setprio 0
	s_setprio 1
	v_mfma_f32_16x16x32_bf16 v[118:121], v[164:167], v[180:183], v[118:121]
	v_mfma_f32_16x16x32_bf16 v[114:117], v[172:175], v[180:183], v[114:117]
	v_mfma_f32_16x16x32_bf16 v[102:105], v[164:167], v[188:191], v[102:105]
	v_mfma_f32_16x16x32_bf16 v[98:101], v[172:175], v[188:191], v[98:101]
	v_mfma_f32_16x16x32_bf16 v[86:89], v[164:167], v[196:199], v[86:89]
	v_mfma_f32_16x16x32_bf16 v[82:85], v[172:175], v[196:199], v[82:85]
	v_mfma_f32_16x16x32_bf16 v[70:73], v[164:167], v[204:207], v[70:73]
	v_mfma_f32_16x16x32_bf16 v[66:69], v[172:175], v[204:207], v[66:69]
	v_mfma_f32_16x16x32_bf16 v[118:121], v[168:171], v[184:187], v[118:121]
	v_mfma_f32_16x16x32_bf16 v[114:117], v[176:179], v[184:187], v[114:117]
	v_mfma_f32_16x16x32_bf16 v[102:105], v[168:171], v[192:195], v[102:105]
	v_mfma_f32_16x16x32_bf16 v[98:101], v[176:179], v[192:195], v[98:101]
	v_mfma_f32_16x16x32_bf16 v[86:89], v[168:171], v[200:203], v[86:89]
	v_mfma_f32_16x16x32_bf16 v[82:85], v[176:179], v[200:203], v[82:85]
	v_mfma_f32_16x16x32_bf16 v[70:73], v[168:171], v[208:211], v[70:73]
	v_mfma_f32_16x16x32_bf16 v[66:69], v[176:179], v[208:211], v[66:69]
	s_setprio 0
	s_barrier
	v_mov_b32_e32 v0, v137
	ds_read_b128 v[180:183], v150 offset:49152
	ds_read_b128 v[184:187], v150 offset:50176
	ds_read_b128 v[188:191], v150 offset:51200
	ds_read_b128 v[192:195], v150 offset:52224
	ds_read_b128 v[196:199], v150 offset:53248
	ds_read_b128 v[200:203], v150 offset:54272
	ds_read_b128 v[204:207], v150 offset:55296
	ds_read_b128 v[208:211], v150 offset:56320
	s_add_i32 s23, s23, s42
	v_lshl_add_u64 v[212:213], s[6:7], 0, v[0:1]
	v_lshl_add_u64 v[212:213], v[212:213], 0, s[38:39]
	s_mov_b32 m0, s23
	v_mov_b32_e32 v0, v139
	global_load_lds_dwordx4 v[212:213], off
	s_add_i32 m0, s23, 0x2000
	s_nop 0
	v_lshl_add_u64 v[212:213], s[6:7], 0, v[0:1]
	s_add_u32 s6, s6, 0x40080
	v_lshl_add_u64 v[212:213], v[212:213], 0, s[38:39]
	s_addc_u32 s7, s7, 0
	s_add_i32 s23, s25, s42
	global_load_lds_dwordx4 v[212:213], off
	s_mov_b32 m0, s23
	s_nop 0
	global_load_lds_dwordx4 v137, s[6:7]
	s_add_i32 m0, s23, 0x2000
	s_nop 0
	global_load_lds_dwordx4 v139, s[6:7]
	v_mov_b32_e32 v0, v131
	s_mov_b32 m0, s70
	v_lshl_add_u64 v[212:213], s[4:5], 0, v[0:1]
	v_lshl_add_u64 v[212:213], v[212:213], 0, s[38:39]
	v_mov_b32_e32 v0, v133
	global_load_lds_dwordx4 v[212:213], off
	s_mov_b32 m0, s71
	v_lshl_add_u64 v[212:213], s[4:5], 0, v[0:1]
	v_lshl_add_u64 v[212:213], v[212:213], 0, s[38:39]
	global_load_lds_dwordx4 v[212:213], off
	s_waitcnt vmcnt(8)
	s_waitcnt lgkmcnt(0)
	s_barrier
	s_setprio 1
	s_waitcnt lgkmcnt(0)
	v_mfma_f32_16x16x32_bf16 v[62:65], v[146:149], v[180:183], v[62:65]
	v_mfma_f32_16x16x32_bf16 v[58:61], v[156:159], v[180:183], v[58:61]
	v_mfma_f32_16x16x32_bf16 v[46:49], v[146:149], v[188:191], v[46:49]
	v_mfma_f32_16x16x32_bf16 v[42:45], v[156:159], v[188:191], v[42:45]
	v_mfma_f32_16x16x32_bf16 v[30:33], v[146:149], v[196:199], v[30:33]
	v_mfma_f32_16x16x32_bf16 v[26:29], v[156:159], v[196:199], v[26:29]
	v_mfma_f32_16x16x32_bf16 v[14:17], v[146:149], v[204:207], v[14:17]
	v_mfma_f32_16x16x32_bf16 v[10:13], v[156:159], v[204:207], v[10:13]
	v_mfma_f32_16x16x32_bf16 v[62:65], v[152:155], v[184:187], v[62:65]
	v_mfma_f32_16x16x32_bf16 v[58:61], v[160:163], v[184:187], v[58:61]
	v_mfma_f32_16x16x32_bf16 v[46:49], v[152:155], v[192:195], v[46:49]
	v_mfma_f32_16x16x32_bf16 v[42:45], v[160:163], v[192:195], v[42:45]
	v_mfma_f32_16x16x32_bf16 v[30:33], v[152:155], v[200:203], v[30:33]
	v_mfma_f32_16x16x32_bf16 v[26:29], v[160:163], v[200:203], v[26:29]
	v_mfma_f32_16x16x32_bf16 v[14:17], v[152:155], v[208:211], v[14:17]
	v_mfma_f32_16x16x32_bf16 v[10:13], v[160:163], v[208:211], v[10:13]
	s_setprio 0
	s_setprio 1
	v_mfma_f32_16x16x32_bf16 v[54:57], v[164:167], v[180:183], v[54:57]
	v_mfma_f32_16x16x32_bf16 v[50:53], v[172:175], v[180:183], v[50:53]
	v_mfma_f32_16x16x32_bf16 v[38:41], v[164:167], v[188:191], v[38:41]
	v_mfma_f32_16x16x32_bf16 v[34:37], v[172:175], v[188:191], v[34:37]
	v_mfma_f32_16x16x32_bf16 v[22:25], v[164:167], v[196:199], v[22:25]
	v_mfma_f32_16x16x32_bf16 v[18:21], v[172:175], v[196:199], v[18:21]
	v_mfma_f32_16x16x32_bf16 v[6:9], v[164:167], v[204:207], v[6:9]
	v_mfma_f32_16x16x32_bf16 v[2:5], v[172:175], v[204:207], v[2:5]
	v_mfma_f32_16x16x32_bf16 v[54:57], v[168:171], v[184:187], v[54:57]
	v_mfma_f32_16x16x32_bf16 v[50:53], v[176:179], v[184:187], v[50:53]
	v_mfma_f32_16x16x32_bf16 v[38:41], v[168:171], v[192:195], v[38:41]
	v_mfma_f32_16x16x32_bf16 v[34:37], v[176:179], v[192:195], v[34:37]
	v_mfma_f32_16x16x32_bf16 v[22:25], v[168:171], v[200:203], v[22:25]
	v_mfma_f32_16x16x32_bf16 v[18:21], v[176:179], v[200:203], v[18:21]
	v_mfma_f32_16x16x32_bf16 v[6:9], v[168:171], v[208:211], v[6:9]
	v_mfma_f32_16x16x32_bf16 v[2:5], v[176:179], v[208:211], v[2:5]
	s_setprio 0
	s_barrier
	s_add_i32 s22, s22, 2
	s_add_u32 s2, s2, 0x100
	s_addc_u32 s3, s3, 0
	s_add_u32 s8, s8, 0x100
	s_addc_u32 s9, s9, 0
	s_cmp_gt_u32 s22, 13
	s_cbranch_scc0 .LBB0_1088
	s_branch .Lpeel_exit_1088
.LBB0_1088:
	s_add_u32 s4, s2, 0xfffc0080
	s_addc_u32 s5, s3, -1
	s_add_i32 s23, 0, 0x10000
	s_cmp_eq_u32 s22, 12
	s_cselect_b32 s5, s49, s5
	s_cselect_b32 s4, s48, s4
	v_add_u32_e32 v0, s23, v145
	s_cselect_b32 s7, s97, s9
	s_cselect_b32 s6, s96, s8
	s_add_i32 s25, 0, 0x14000
	ds_read_b128 v[146:149], v0
	ds_read_b128 v[152:155], v0 offset:1024
	ds_read_b128 v[156:159], v0 offset:2048
	ds_read_b128 v[160:163], v0 offset:3072
	v_add_u32_e32 v0, s25, v145
	ds_read_b128 v[164:167], v0
	ds_read_b128 v[168:171], v0 offset:1024
	ds_read_b128 v[172:175], v0 offset:2048
	ds_read_b128 v[176:179], v0 offset:3072
	ds_read_b128 v[180:183], v150
	ds_read_b128 v[184:187], v150 offset:1024
	ds_read_b128 v[188:191], v150 offset:2048
	ds_read_b128 v[192:195], v150 offset:3072
	ds_read_b128 v[196:199], v150 offset:4096
	ds_read_b128 v[200:203], v150 offset:5120
	ds_read_b128 v[204:207], v150 offset:6144
	ds_read_b128 v[208:211], v150 offset:7168
	s_add_i32 m0, s60, 0xc000
	s_nop 0
	global_load_lds_dwordx4 v131, s[2:3]
	s_add_i32 m0, s60, 0xe000
	s_nop 0
	global_load_lds_dwordx4 v133, s[2:3]
	s_waitcnt vmcnt(8)
	s_waitcnt lgkmcnt(0)
	s_barrier
	s_setprio 1
	s_waitcnt lgkmcnt(0)
	v_mfma_f32_16x16x32_bf16 v[126:129], v[146:149], v[180:183], v[126:129]
	v_mfma_f32_16x16x32_bf16 v[122:125], v[156:159], v[180:183], v[122:125]
	v_mfma_f32_16x16x32_bf16 v[110:113], v[146:149], v[188:191], v[110:113]
	v_mfma_f32_16x16x32_bf16 v[106:109], v[156:159], v[188:191], v[106:109]
	v_mfma_f32_16x16x32_bf16 v[94:97], v[146:149], v[196:199], v[94:97]
	v_mfma_f32_16x16x32_bf16 v[90:93], v[156:159], v[196:199], v[90:93]
	v_mfma_f32_16x16x32_bf16 v[78:81], v[146:149], v[204:207], v[78:81]
	v_mfma_f32_16x16x32_bf16 v[74:77], v[156:159], v[204:207], v[74:77]
	v_mfma_f32_16x16x32_bf16 v[126:129], v[152:155], v[184:187], v[126:129]
	v_mfma_f32_16x16x32_bf16 v[122:125], v[160:163], v[184:187], v[122:125]
	v_mfma_f32_16x16x32_bf16 v[110:113], v[152:155], v[192:195], v[110:113]
	v_mfma_f32_16x16x32_bf16 v[106:109], v[160:163], v[192:195], v[106:109]
	v_mfma_f32_16x16x32_bf16 v[94:97], v[152:155], v[200:203], v[94:97]
	v_mfma_f32_16x16x32_bf16 v[90:93], v[160:163], v[200:203], v[90:93]
	v_mfma_f32_16x16x32_bf16 v[78:81], v[152:155], v[208:211], v[78:81]
	v_mfma_f32_16x16x32_bf16 v[74:77], v[160:163], v[208:211], v[74:77]
	s_setprio 0
	s_setprio 1
	v_mfma_f32_16x16x32_bf16 v[118:121], v[164:167], v[180:183], v[118:121]
	v_mfma_f32_16x16x32_bf16 v[114:117], v[172:175], v[180:183], v[114:117]
	v_mfma_f32_16x16x32_bf16 v[102:105], v[164:167], v[188:191], v[102:105]
	v_mfma_f32_16x16x32_bf16 v[98:101], v[172:175], v[188:191], v[98:101]
	v_mfma_f32_16x16x32_bf16 v[86:89], v[164:167], v[196:199], v[86:89]
	v_mfma_f32_16x16x32_bf16 v[82:85], v[172:175], v[196:199], v[82:85]
	v_mfma_f32_16x16x32_bf16 v[70:73], v[164:167], v[204:207], v[70:73]
	v_mfma_f32_16x16x32_bf16 v[66:69], v[172:175], v[204:207], v[66:69]
	v_mfma_f32_16x16x32_bf16 v[118:121], v[168:171], v[184:187], v[118:121]
	v_mfma_f32_16x16x32_bf16 v[114:117], v[176:179], v[184:187], v[114:117]
	v_mfma_f32_16x16x32_bf16 v[102:105], v[168:171], v[192:195], v[102:105]
	v_mfma_f32_16x16x32_bf16 v[98:101], v[176:179], v[192:195], v[98:101]
	v_mfma_f32_16x16x32_bf16 v[86:89], v[168:171], v[200:203], v[86:89]
	v_mfma_f32_16x16x32_bf16 v[82:85], v[176:179], v[200:203], v[82:85]
	v_mfma_f32_16x16x32_bf16 v[70:73], v[168:171], v[208:211], v[70:73]
	v_mfma_f32_16x16x32_bf16 v[66:69], v[176:179], v[208:211], v[66:69]
	s_setprio 0
	s_barrier
	s_add_i32 s23, s23, s42
	ds_read_b128 v[180:183], v150 offset:16384
	ds_read_b128 v[184:187], v150 offset:17408
	ds_read_b128 v[188:191], v150 offset:18432
	ds_read_b128 v[192:195], v150 offset:19456
	ds_read_b128 v[196:199], v150 offset:20480
	ds_read_b128 v[200:203], v150 offset:21504
	ds_read_b128 v[204:207], v150 offset:22528
	ds_read_b128 v[208:211], v150 offset:23552
	s_mov_b32 m0, s23
	s_nop 0
	global_load_lds_dwordx4 v137, s[6:7]
	s_add_i32 m0, s23, 0x2000
	s_add_u32 s46, s6, 0x40000
	global_load_lds_dwordx4 v139, s[6:7]
	s_addc_u32 s47, s7, 0
	s_add_i32 s23, s25, s42
	s_mov_b32 m0, s23
	s_nop 0
	global_load_lds_dwordx4 v137, s[46:47]
	s_add_i32 m0, s23, 0x2000
	s_nop 0
	global_load_lds_dwordx4 v139, s[46:47]
	s_mov_b32 m0, s60
	s_nop 0
	global_load_lds_dwordx4 v131, s[4:5]
	s_mov_b32 m0, s61
	s_nop 0
	global_load_lds_dwordx4 v133, s[4:5]
	s_waitcnt vmcnt(8)
	s_waitcnt lgkmcnt(0)
	s_barrier
	s_setprio 1
	s_waitcnt lgkmcnt(0)
	v_mfma_f32_16x16x32_bf16 v[62:65], v[146:149], v[180:183], v[62:65]
	v_mfma_f32_16x16x32_bf16 v[58:61], v[156:159], v[180:183], v[58:61]
	v_mfma_f32_16x16x32_bf16 v[46:49], v[146:149], v[188:191], v[46:49]
	v_mfma_f32_16x16x32_bf16 v[42:45], v[156:159], v[188:191], v[42:45]
	v_mfma_f32_16x16x32_bf16 v[30:33], v[146:149], v[196:199], v[30:33]
	v_mfma_f32_16x16x32_bf16 v[26:29], v[156:159], v[196:199], v[26:29]
	v_mfma_f32_16x16x32_bf16 v[14:17], v[146:149], v[204:207], v[14:17]
	v_mfma_f32_16x16x32_bf16 v[10:13], v[156:159], v[204:207], v[10:13]
	v_mfma_f32_16x16x32_bf16 v[62:65], v[152:155], v[184:187], v[62:65]
	v_mfma_f32_16x16x32_bf16 v[58:61], v[160:163], v[184:187], v[58:61]
	v_mfma_f32_16x16x32_bf16 v[46:49], v[152:155], v[192:195], v[46:49]
	v_mfma_f32_16x16x32_bf16 v[42:45], v[160:163], v[192:195], v[42:45]
	v_mfma_f32_16x16x32_bf16 v[30:33], v[152:155], v[200:203], v[30:33]
	v_mfma_f32_16x16x32_bf16 v[26:29], v[160:163], v[200:203], v[26:29]
	v_mfma_f32_16x16x32_bf16 v[14:17], v[152:155], v[208:211], v[14:17]
	v_mfma_f32_16x16x32_bf16 v[10:13], v[160:163], v[208:211], v[10:13]
	s_setprio 0
	s_setprio 1
	v_mfma_f32_16x16x32_bf16 v[54:57], v[164:167], v[180:183], v[54:57]
	v_mfma_f32_16x16x32_bf16 v[50:53], v[172:175], v[180:183], v[50:53]
	v_mfma_f32_16x16x32_bf16 v[38:41], v[164:167], v[188:191], v[38:41]
	v_mfma_f32_16x16x32_bf16 v[34:37], v[172:175], v[188:191], v[34:37]
	v_mfma_f32_16x16x32_bf16 v[22:25], v[164:167], v[196:199], v[22:25]
	v_mfma_f32_16x16x32_bf16 v[18:21], v[172:175], v[196:199], v[18:21]
	v_mfma_f32_16x16x32_bf16 v[6:9], v[164:167], v[204:207], v[6:9]
	v_mfma_f32_16x16x32_bf16 v[2:5], v[172:175], v[204:207], v[2:5]
	v_mfma_f32_16x16x32_bf16 v[54:57], v[168:171], v[184:187], v[54:57]
	v_mfma_f32_16x16x32_bf16 v[50:53], v[176:179], v[184:187], v[50:53]
	v_mfma_f32_16x16x32_bf16 v[38:41], v[168:171], v[192:195], v[38:41]
	v_mfma_f32_16x16x32_bf16 v[34:37], v[176:179], v[192:195], v[34:37]
	v_mfma_f32_16x16x32_bf16 v[22:25], v[168:171], v[200:203], v[22:25]
	v_mfma_f32_16x16x32_bf16 v[18:21], v[176:179], v[200:203], v[18:21]
	v_mfma_f32_16x16x32_bf16 v[6:9], v[168:171], v[208:211], v[6:9]
	v_mfma_f32_16x16x32_bf16 v[2:5], v[176:179], v[208:211], v[2:5]
	s_setprio 0
	s_barrier
	s_add_i32 s23, 0, 0x18000
	v_add_u32_e32 v0, s23, v145
	s_add_i32 s25, 0, 0x1c000
	ds_read_b128 v[146:149], v0
	ds_read_b128 v[152:155], v0 offset:1024
	ds_read_b128 v[156:159], v0 offset:2048
	ds_read_b128 v[160:163], v0 offset:3072
	v_add_u32_e32 v0, s25, v145
	ds_read_b128 v[164:167], v0
	ds_read_b128 v[168:171], v0 offset:1024
	ds_read_b128 v[172:175], v0 offset:2048
	ds_read_b128 v[176:179], v0 offset:3072
	s_add_u32 s46, s4, 0x40000
	s_mov_b32 m0, s66
	ds_read_b128 v[180:183], v150 offset:32768
	ds_read_b128 v[184:187], v150 offset:33792
	ds_read_b128 v[188:191], v150 offset:34816
	ds_read_b128 v[192:195], v150 offset:35840
	ds_read_b128 v[196:199], v150 offset:36864
	ds_read_b128 v[200:203], v150 offset:37888
	ds_read_b128 v[204:207], v150 offset:38912
	ds_read_b128 v[208:211], v150 offset:39936
	s_addc_u32 s47, s5, 0
	s_nop 0
	global_load_lds_dwordx4 v131, s[46:47]
	s_mov_b32 m0, s67
	s_nop 0
	global_load_lds_dwordx4 v133, s[46:47]
	s_waitcnt vmcnt(8)
	s_waitcnt lgkmcnt(0)
	s_barrier
	s_setprio 1
	s_waitcnt lgkmcnt(0)
	v_mfma_f32_16x16x32_bf16 v[126:129], v[146:149], v[180:183], v[126:129]
	v_mfma_f32_16x16x32_bf16 v[122:125], v[156:159], v[180:183], v[122:125]
	v_mfma_f32_16x16x32_bf16 v[110:113], v[146:149], v[188:191], v[110:113]
	v_mfma_f32_16x16x32_bf16 v[106:109], v[156:159], v[188:191], v[106:109]
	v_mfma_f32_16x16x32_bf16 v[94:97], v[146:149], v[196:199], v[94:97]
	v_mfma_f32_16x16x32_bf16 v[90:93], v[156:159], v[196:199], v[90:93]
	v_mfma_f32_16x16x32_bf16 v[78:81], v[146:149], v[204:207], v[78:81]
	v_mfma_f32_16x16x32_bf16 v[74:77], v[156:159], v[204:207], v[74:77]
	v_mfma_f32_16x16x32_bf16 v[126:129], v[152:155], v[184:187], v[126:129]
	v_mfma_f32_16x16x32_bf16 v[122:125], v[160:163], v[184:187], v[122:125]
	v_mfma_f32_16x16x32_bf16 v[110:113], v[152:155], v[192:195], v[110:113]
	v_mfma_f32_16x16x32_bf16 v[106:109], v[160:163], v[192:195], v[106:109]
	v_mfma_f32_16x16x32_bf16 v[94:97], v[152:155], v[200:203], v[94:97]
	v_mfma_f32_16x16x32_bf16 v[90:93], v[160:163], v[200:203], v[90:93]
	v_mfma_f32_16x16x32_bf16 v[78:81], v[152:155], v[208:211], v[78:81]
	v_mfma_f32_16x16x32_bf16 v[74:77], v[160:163], v[208:211], v[74:77]
	s_setprio 0
	s_setprio 1
	v_mfma_f32_16x16x32_bf16 v[118:121], v[164:167], v[180:183], v[118:121]
	v_mfma_f32_16x16x32_bf16 v[114:117], v[172:175], v[180:183], v[114:117]
	v_mfma_f32_16x16x32_bf16 v[102:105], v[164:167], v[188:191], v[102:105]
	v_mfma_f32_16x16x32_bf16 v[98:101], v[172:175], v[188:191], v[98:101]
	v_mfma_f32_16x16x32_bf16 v[86:89], v[164:167], v[196:199], v[86:89]
	v_mfma_f32_16x16x32_bf16 v[82:85], v[172:175], v[196:199], v[82:85]
	v_mfma_f32_16x16x32_bf16 v[70:73], v[164:167], v[204:207], v[70:73]
	v_mfma_f32_16x16x32_bf16 v[66:69], v[172:175], v[204:207], v[66:69]
	v_mfma_f32_16x16x32_bf16 v[118:121], v[168:171], v[184:187], v[118:121]
	v_mfma_f32_16x16x32_bf16 v[114:117], v[176:179], v[184:187], v[114:117]
	v_mfma_f32_16x16x32_bf16 v[102:105], v[168:171], v[192:195], v[102:105]
	v_mfma_f32_16x16x32_bf16 v[98:101], v[176:179], v[192:195], v[98:101]
	v_mfma_f32_16x16x32_bf16 v[86:89], v[168:171], v[200:203], v[86:89]
	v_mfma_f32_16x16x32_bf16 v[82:85], v[176:179], v[200:203], v[82:85]
	v_mfma_f32_16x16x32_bf16 v[70:73], v[168:171], v[208:211], v[70:73]
	v_mfma_f32_16x16x32_bf16 v[66:69], v[176:179], v[208:211], v[66:69]
	s_setprio 0
	s_barrier
	v_mov_b32_e32 v0, v137
	ds_read_b128 v[180:183], v150 offset:49152
	ds_read_b128 v[184:187], v150 offset:50176
	ds_read_b128 v[188:191], v150 offset:51200
	ds_read_b128 v[192:195], v150 offset:52224
	ds_read_b128 v[196:199], v150 offset:53248
	ds_read_b128 v[200:203], v150 offset:54272
	ds_read_b128 v[204:207], v150 offset:55296
	ds_read_b128 v[208:211], v150 offset:56320
	s_add_i32 s23, s23, s42
	v_lshl_add_u64 v[212:213], s[6:7], 0, v[0:1]
	v_lshl_add_u64 v[212:213], v[212:213], 0, s[38:39]
	s_mov_b32 m0, s23
	v_mov_b32_e32 v0, v139
	global_load_lds_dwordx4 v[212:213], off
	s_add_i32 m0, s23, 0x2000
	s_nop 0
	v_lshl_add_u64 v[212:213], s[6:7], 0, v[0:1]
	s_add_u32 s6, s6, 0x40080
	v_lshl_add_u64 v[212:213], v[212:213], 0, s[38:39]
	s_addc_u32 s7, s7, 0
	s_add_i32 s23, s25, s42
	global_load_lds_dwordx4 v[212:213], off
	s_mov_b32 m0, s23
	s_nop 0
	global_load_lds_dwordx4 v137, s[6:7]
	s_add_i32 m0, s23, 0x2000
	s_nop 0
	global_load_lds_dwordx4 v139, s[6:7]
	v_mov_b32_e32 v0, v131
	s_mov_b32 m0, s70
	v_lshl_add_u64 v[212:213], s[4:5], 0, v[0:1]
	v_lshl_add_u64 v[212:213], v[212:213], 0, s[38:39]
	v_mov_b32_e32 v0, v133
	global_load_lds_dwordx4 v[212:213], off
	s_mov_b32 m0, s71
	v_lshl_add_u64 v[212:213], s[4:5], 0, v[0:1]
	v_lshl_add_u64 v[212:213], v[212:213], 0, s[38:39]
	global_load_lds_dwordx4 v[212:213], off
	s_waitcnt vmcnt(8)
	s_waitcnt lgkmcnt(0)
	s_barrier
	s_setprio 1
	s_waitcnt lgkmcnt(0)
	v_mfma_f32_16x16x32_bf16 v[62:65], v[146:149], v[180:183], v[62:65]
	v_mfma_f32_16x16x32_bf16 v[58:61], v[156:159], v[180:183], v[58:61]
	v_mfma_f32_16x16x32_bf16 v[46:49], v[146:149], v[188:191], v[46:49]
	v_mfma_f32_16x16x32_bf16 v[42:45], v[156:159], v[188:191], v[42:45]
	v_mfma_f32_16x16x32_bf16 v[30:33], v[146:149], v[196:199], v[30:33]
	v_mfma_f32_16x16x32_bf16 v[26:29], v[156:159], v[196:199], v[26:29]
	v_mfma_f32_16x16x32_bf16 v[14:17], v[146:149], v[204:207], v[14:17]
	v_mfma_f32_16x16x32_bf16 v[10:13], v[156:159], v[204:207], v[10:13]
	v_mfma_f32_16x16x32_bf16 v[62:65], v[152:155], v[184:187], v[62:65]
	v_mfma_f32_16x16x32_bf16 v[58:61], v[160:163], v[184:187], v[58:61]
	v_mfma_f32_16x16x32_bf16 v[46:49], v[152:155], v[192:195], v[46:49]
	v_mfma_f32_16x16x32_bf16 v[42:45], v[160:163], v[192:195], v[42:45]
	v_mfma_f32_16x16x32_bf16 v[30:33], v[152:155], v[200:203], v[30:33]
	v_mfma_f32_16x16x32_bf16 v[26:29], v[160:163], v[200:203], v[26:29]
	v_mfma_f32_16x16x32_bf16 v[14:17], v[152:155], v[208:211], v[14:17]
	v_mfma_f32_16x16x32_bf16 v[10:13], v[160:163], v[208:211], v[10:13]
	s_setprio 0
	s_setprio 1
	v_mfma_f32_16x16x32_bf16 v[54:57], v[164:167], v[180:183], v[54:57]
	v_mfma_f32_16x16x32_bf16 v[50:53], v[172:175], v[180:183], v[50:53]
	v_mfma_f32_16x16x32_bf16 v[38:41], v[164:167], v[188:191], v[38:41]
	v_mfma_f32_16x16x32_bf16 v[34:37], v[172:175], v[188:191], v[34:37]
	v_mfma_f32_16x16x32_bf16 v[22:25], v[164:167], v[196:199], v[22:25]
	v_mfma_f32_16x16x32_bf16 v[18:21], v[172:175], v[196:199], v[18:21]
	v_mfma_f32_16x16x32_bf16 v[6:9], v[164:167], v[204:207], v[6:9]
	v_mfma_f32_16x16x32_bf16 v[2:5], v[172:175], v[204:207], v[2:5]
	v_mfma_f32_16x16x32_bf16 v[54:57], v[168:171], v[184:187], v[54:57]
	v_mfma_f32_16x16x32_bf16 v[50:53], v[176:179], v[184:187], v[50:53]
	v_mfma_f32_16x16x32_bf16 v[38:41], v[168:171], v[192:195], v[38:41]
	v_mfma_f32_16x16x32_bf16 v[34:37], v[176:179], v[192:195], v[34:37]
	v_mfma_f32_16x16x32_bf16 v[22:25], v[168:171], v[200:203], v[22:25]
	v_mfma_f32_16x16x32_bf16 v[18:21], v[176:179], v[200:203], v[18:21]
	v_mfma_f32_16x16x32_bf16 v[6:9], v[168:171], v[208:211], v[6:9]
	v_mfma_f32_16x16x32_bf16 v[2:5], v[176:179], v[208:211], v[2:5]
	s_setprio 0
	s_barrier
	s_add_i32 s22, s22, 2
	s_add_u32 s2, s2, 0x100
	s_addc_u32 s3, s3, 0
	s_add_u32 s8, s8, 0x100
	s_addc_u32 s9, s9, 0
	s_cmp_gt_u32 s22, 13
	s_cbranch_scc0 .LBB0_1088

.LBB0_1681:
	s_add_u32 s48, s6, s2
	s_addc_u32 s49, s7, s3
	s_add_u32 s10, s48, 0x100
	s_addc_u32 s11, s49, 0
	s_add_u32 s12, s37, s2
	s_addc_u32 s13, s40, s3
	s_add_i32 s47, 0, 0x10000
	s_cmp_eq_u32 s46, 12
	s_cselect_b32 s11, s7, s11
	s_cselect_b32 s10, s6, s10
	v_add_u32_e32 v0, s47, v136
	s_cselect_b32 s13, s9, s13
	s_cselect_b32 s12, s8, s12
	s_add_i32 s50, 0, 0x14000
	ds_read_b128 v[138:141], v0
	ds_read_b128 v[142:145], v0 offset:1024
	ds_read_b128 v[146:149], v0 offset:2048
	ds_read_b128 v[150:153], v0 offset:3072
	v_add_u32_e32 v0, s50, v136
	ds_read_b128 v[154:157], v0
	ds_read_b128 v[158:161], v0 offset:1024
	ds_read_b128 v[162:165], v0 offset:2048
	ds_read_b128 v[166:169], v0 offset:3072
	v_mov_b32_e32 v0, v130
	ds_read_b128 v[170:173], v137
	ds_read_b128 v[174:177], v137 offset:1024
	ds_read_b128 v[178:181], v137 offset:2048
	ds_read_b128 v[182:185], v137 offset:3072
	ds_read_b128 v[186:189], v137 offset:4096
	ds_read_b128 v[190:193], v137 offset:5120
	ds_read_b128 v[194:197], v137 offset:6144
	ds_read_b128 v[198:201], v137 offset:7168
	s_add_i32 m0, s23, 0xc000
	v_lshl_add_u64 v[202:203], s[48:49], 0, v[0:1]
	v_lshl_add_u64 v[202:203], v[202:203], 0, s[56:57]
	v_mov_b32_e32 v0, v132
	global_load_lds_dwordx4 v[202:203], off
	s_add_i32 m0, s23, 0xe000
	v_lshl_add_u64 v[202:203], s[48:49], 0, v[0:1]
	v_lshl_add_u64 v[202:203], v[202:203], 0, s[56:57]
	global_load_lds_dwordx4 v[202:203], off
	s_waitcnt vmcnt(8)
	s_waitcnt lgkmcnt(0)
	s_barrier
	s_setprio 1
	s_waitcnt lgkmcnt(0)
	v_mfma_f32_16x16x32_bf16 v[126:129], v[138:141], v[170:173], v[126:129]
	v_mfma_f32_16x16x32_bf16 v[122:125], v[146:149], v[170:173], v[122:125]
	v_mfma_f32_16x16x32_bf16 v[110:113], v[138:141], v[178:181], v[110:113]
	v_mfma_f32_16x16x32_bf16 v[106:109], v[146:149], v[178:181], v[106:109]
	v_mfma_f32_16x16x32_bf16 v[94:97], v[138:141], v[186:189], v[94:97]
	v_mfma_f32_16x16x32_bf16 v[90:93], v[146:149], v[186:189], v[90:93]
	v_mfma_f32_16x16x32_bf16 v[78:81], v[138:141], v[194:197], v[78:81]
	v_mfma_f32_16x16x32_bf16 v[74:77], v[146:149], v[194:197], v[74:77]
	v_mfma_f32_16x16x32_bf16 v[126:129], v[142:145], v[174:177], v[126:129]
	v_mfma_f32_16x16x32_bf16 v[122:125], v[150:153], v[174:177], v[122:125]
	v_mfma_f32_16x16x32_bf16 v[110:113], v[142:145], v[182:185], v[110:113]
	v_mfma_f32_16x16x32_bf16 v[106:109], v[150:153], v[182:185], v[106:109]
	v_mfma_f32_16x16x32_bf16 v[94:97], v[142:145], v[190:193], v[94:97]
	v_mfma_f32_16x16x32_bf16 v[90:93], v[150:153], v[190:193], v[90:93]
	v_mfma_f32_16x16x32_bf16 v[78:81], v[142:145], v[198:201], v[78:81]
	v_mfma_f32_16x16x32_bf16 v[74:77], v[150:153], v[198:201], v[74:77]
	s_setprio 0
	s_setprio 1
	v_mfma_f32_16x16x32_bf16 v[118:121], v[154:157], v[170:173], v[118:121]
	v_mfma_f32_16x16x32_bf16 v[114:117], v[162:165], v[170:173], v[114:117]
	v_mfma_f32_16x16x32_bf16 v[102:105], v[154:157], v[178:181], v[102:105]
	v_mfma_f32_16x16x32_bf16 v[98:101], v[162:165], v[178:181], v[98:101]
	v_mfma_f32_16x16x32_bf16 v[86:89], v[154:157], v[186:189], v[86:89]
	v_mfma_f32_16x16x32_bf16 v[82:85], v[162:165], v[186:189], v[82:85]
	v_mfma_f32_16x16x32_bf16 v[70:73], v[154:157], v[194:197], v[70:73]
	v_mfma_f32_16x16x32_bf16 v[66:69], v[162:165], v[194:197], v[66:69]
	v_mfma_f32_16x16x32_bf16 v[118:121], v[158:161], v[174:177], v[118:121]
	v_mfma_f32_16x16x32_bf16 v[114:117], v[166:169], v[174:177], v[114:117]
	v_mfma_f32_16x16x32_bf16 v[102:105], v[158:161], v[182:185], v[102:105]
	v_mfma_f32_16x16x32_bf16 v[98:101], v[166:169], v[182:185], v[98:101]
	v_mfma_f32_16x16x32_bf16 v[86:89], v[158:161], v[190:193], v[86:89]
	v_mfma_f32_16x16x32_bf16 v[82:85], v[166:169], v[190:193], v[82:85]
	v_mfma_f32_16x16x32_bf16 v[70:73], v[158:161], v[198:201], v[70:73]
	v_mfma_f32_16x16x32_bf16 v[66:69], v[166:169], v[198:201], v[66:69]
	s_setprio 0
	s_barrier
	s_add_i32 s47, s47, s22
	ds_read_b128 v[170:173], v137 offset:16384
	ds_read_b128 v[174:177], v137 offset:17408
	ds_read_b128 v[178:181], v137 offset:18432
	ds_read_b128 v[182:185], v137 offset:19456
	ds_read_b128 v[186:189], v137 offset:20480
	ds_read_b128 v[190:193], v137 offset:21504
	ds_read_b128 v[194:197], v137 offset:22528
	ds_read_b128 v[198:201], v137 offset:23552
	s_mov_b32 m0, s47
	s_nop 0
	global_load_lds_dwordx4 v134, s[12:13]
	s_add_i32 m0, s47, 0x2000
	s_add_u32 s48, s12, 0x40000
	global_load_lds_dwordx4 v135, s[12:13]
	s_addc_u32 s49, s13, 0
	s_add_i32 s47, s50, s22
	s_mov_b32 m0, s47
	s_nop 0
	global_load_lds_dwordx4 v134, s[48:49]
	s_add_i32 m0, s47, 0x2000
	s_nop 0
	global_load_lds_dwordx4 v135, s[48:49]
	s_mov_b32 m0, s23
	s_nop 0
	global_load_lds_dwordx4 v130, s[10:11]
	s_mov_b32 m0, s24
	s_nop 0
	global_load_lds_dwordx4 v132, s[10:11]
	s_waitcnt vmcnt(8)
	s_waitcnt lgkmcnt(0)
	s_barrier
	s_setprio 1
	s_waitcnt lgkmcnt(0)
	v_mfma_f32_16x16x32_bf16 v[62:65], v[138:141], v[170:173], v[62:65]
	v_mfma_f32_16x16x32_bf16 v[58:61], v[146:149], v[170:173], v[58:61]
	v_mfma_f32_16x16x32_bf16 v[46:49], v[138:141], v[178:181], v[46:49]
	v_mfma_f32_16x16x32_bf16 v[42:45], v[146:149], v[178:181], v[42:45]
	v_mfma_f32_16x16x32_bf16 v[30:33], v[138:141], v[186:189], v[30:33]
	v_mfma_f32_16x16x32_bf16 v[26:29], v[146:149], v[186:189], v[26:29]
	v_mfma_f32_16x16x32_bf16 v[14:17], v[138:141], v[194:197], v[14:17]
	v_mfma_f32_16x16x32_bf16 v[10:13], v[146:149], v[194:197], v[10:13]
	v_mfma_f32_16x16x32_bf16 v[62:65], v[142:145], v[174:177], v[62:65]
	v_mfma_f32_16x16x32_bf16 v[58:61], v[150:153], v[174:177], v[58:61]
	v_mfma_f32_16x16x32_bf16 v[46:49], v[142:145], v[182:185], v[46:49]
	v_mfma_f32_16x16x32_bf16 v[42:45], v[150:153], v[182:185], v[42:45]
	v_mfma_f32_16x16x32_bf16 v[30:33], v[142:145], v[190:193], v[30:33]
	v_mfma_f32_16x16x32_bf16 v[26:29], v[150:153], v[190:193], v[26:29]
	v_mfma_f32_16x16x32_bf16 v[14:17], v[142:145], v[198:201], v[14:17]
	v_mfma_f32_16x16x32_bf16 v[10:13], v[150:153], v[198:201], v[10:13]
	s_setprio 0
	s_setprio 1
	v_mfma_f32_16x16x32_bf16 v[54:57], v[154:157], v[170:173], v[54:57]
	v_mfma_f32_16x16x32_bf16 v[50:53], v[162:165], v[170:173], v[50:53]
	v_mfma_f32_16x16x32_bf16 v[38:41], v[154:157], v[178:181], v[38:41]
	v_mfma_f32_16x16x32_bf16 v[34:37], v[162:165], v[178:181], v[34:37]
	v_mfma_f32_16x16x32_bf16 v[22:25], v[154:157], v[186:189], v[22:25]
	v_mfma_f32_16x16x32_bf16 v[18:21], v[162:165], v[186:189], v[18:21]
	v_mfma_f32_16x16x32_bf16 v[6:9], v[154:157], v[194:197], v[6:9]
	v_mfma_f32_16x16x32_bf16 v[2:5], v[162:165], v[194:197], v[2:5]
	v_mfma_f32_16x16x32_bf16 v[54:57], v[158:161], v[174:177], v[54:57]
	v_mfma_f32_16x16x32_bf16 v[50:53], v[166:169], v[174:177], v[50:53]
	v_mfma_f32_16x16x32_bf16 v[38:41], v[158:161], v[182:185], v[38:41]
	v_mfma_f32_16x16x32_bf16 v[34:37], v[166:169], v[182:185], v[34:37]
	v_mfma_f32_16x16x32_bf16 v[22:25], v[158:161], v[190:193], v[22:25]
	v_mfma_f32_16x16x32_bf16 v[18:21], v[166:169], v[190:193], v[18:21]
	v_mfma_f32_16x16x32_bf16 v[6:9], v[158:161], v[198:201], v[6:9]
	v_mfma_f32_16x16x32_bf16 v[2:5], v[166:169], v[198:201], v[2:5]
	s_setprio 0
	s_barrier
	s_add_i32 s47, 0, 0x18000
	v_add_u32_e32 v0, s47, v136
	s_add_i32 s50, 0, 0x1c000
	ds_read_b128 v[138:141], v0
	ds_read_b128 v[142:145], v0 offset:1024
	ds_read_b128 v[146:149], v0 offset:2048
	ds_read_b128 v[150:153], v0 offset:3072
	v_add_u32_e32 v0, s50, v136
	ds_read_b128 v[154:157], v0
	ds_read_b128 v[158:161], v0 offset:1024
	ds_read_b128 v[162:165], v0 offset:2048
	ds_read_b128 v[166:169], v0 offset:3072
	s_add_u32 s48, s10, 0x40000
	s_mov_b32 m0, s25
	ds_read_b128 v[170:173], v137 offset:32768
	ds_read_b128 v[174:177], v137 offset:33792
	ds_read_b128 v[178:181], v137 offset:34816
	ds_read_b128 v[182:185], v137 offset:35840
	ds_read_b128 v[186:189], v137 offset:36864
	ds_read_b128 v[190:193], v137 offset:37888
	ds_read_b128 v[194:197], v137 offset:38912
	ds_read_b128 v[198:201], v137 offset:39936
	s_addc_u32 s49, s11, 0
	s_nop 0
	global_load_lds_dwordx4 v130, s[48:49]
	s_mov_b32 m0, s26
	s_nop 0
	global_load_lds_dwordx4 v132, s[48:49]
	s_waitcnt vmcnt(8)
	s_waitcnt lgkmcnt(0)
	s_barrier
	s_setprio 1
	s_waitcnt lgkmcnt(0)
	v_mfma_f32_16x16x32_bf16 v[126:129], v[138:141], v[170:173], v[126:129]
	v_mfma_f32_16x16x32_bf16 v[122:125], v[146:149], v[170:173], v[122:125]
	v_mfma_f32_16x16x32_bf16 v[110:113], v[138:141], v[178:181], v[110:113]
	v_mfma_f32_16x16x32_bf16 v[106:109], v[146:149], v[178:181], v[106:109]
	v_mfma_f32_16x16x32_bf16 v[94:97], v[138:141], v[186:189], v[94:97]
	v_mfma_f32_16x16x32_bf16 v[90:93], v[146:149], v[186:189], v[90:93]
	v_mfma_f32_16x16x32_bf16 v[78:81], v[138:141], v[194:197], v[78:81]
	v_mfma_f32_16x16x32_bf16 v[74:77], v[146:149], v[194:197], v[74:77]
	v_mfma_f32_16x16x32_bf16 v[126:129], v[142:145], v[174:177], v[126:129]
	v_mfma_f32_16x16x32_bf16 v[122:125], v[150:153], v[174:177], v[122:125]
	v_mfma_f32_16x16x32_bf16 v[110:113], v[142:145], v[182:185], v[110:113]
	v_mfma_f32_16x16x32_bf16 v[106:109], v[150:153], v[182:185], v[106:109]
	v_mfma_f32_16x16x32_bf16 v[94:97], v[142:145], v[190:193], v[94:97]
	v_mfma_f32_16x16x32_bf16 v[90:93], v[150:153], v[190:193], v[90:93]
	v_mfma_f32_16x16x32_bf16 v[78:81], v[142:145], v[198:201], v[78:81]
	v_mfma_f32_16x16x32_bf16 v[74:77], v[150:153], v[198:201], v[74:77]
	s_setprio 0
	s_setprio 1
	v_mfma_f32_16x16x32_bf16 v[118:121], v[154:157], v[170:173], v[118:121]
	v_mfma_f32_16x16x32_bf16 v[114:117], v[162:165], v[170:173], v[114:117]
	v_mfma_f32_16x16x32_bf16 v[102:105], v[154:157], v[178:181], v[102:105]
	v_mfma_f32_16x16x32_bf16 v[98:101], v[162:165], v[178:181], v[98:101]
	v_mfma_f32_16x16x32_bf16 v[86:89], v[154:157], v[186:189], v[86:89]
	v_mfma_f32_16x16x32_bf16 v[82:85], v[162:165], v[186:189], v[82:85]
	v_mfma_f32_16x16x32_bf16 v[70:73], v[154:157], v[194:197], v[70:73]
	v_mfma_f32_16x16x32_bf16 v[66:69], v[162:165], v[194:197], v[66:69]
	v_mfma_f32_16x16x32_bf16 v[118:121], v[158:161], v[174:177], v[118:121]
	v_mfma_f32_16x16x32_bf16 v[114:117], v[166:169], v[174:177], v[114:117]
	v_mfma_f32_16x16x32_bf16 v[102:105], v[158:161], v[182:185], v[102:105]
	v_mfma_f32_16x16x32_bf16 v[98:101], v[166:169], v[182:185], v[98:101]
	v_mfma_f32_16x16x32_bf16 v[86:89], v[158:161], v[190:193], v[86:89]
	v_mfma_f32_16x16x32_bf16 v[82:85], v[166:169], v[190:193], v[82:85]
	v_mfma_f32_16x16x32_bf16 v[70:73], v[158:161], v[198:201], v[70:73]
	v_mfma_f32_16x16x32_bf16 v[66:69], v[166:169], v[198:201], v[66:69]
	s_setprio 0
	s_barrier
	v_mov_b32_e32 v0, v134
	ds_read_b128 v[170:173], v137 offset:49152
	ds_read_b128 v[174:177], v137 offset:50176
	ds_read_b128 v[178:181], v137 offset:51200
	ds_read_b128 v[182:185], v137 offset:52224
	ds_read_b128 v[186:189], v137 offset:53248
	ds_read_b128 v[190:193], v137 offset:54272
	ds_read_b128 v[194:197], v137 offset:55296
	ds_read_b128 v[198:201], v137 offset:56320
	s_add_i32 s47, s47, s22
	v_lshl_add_u64 v[202:203], s[12:13], 0, v[0:1]
	v_lshl_add_u64 v[202:203], v[202:203], 0, s[38:39]
	s_mov_b32 m0, s47
	v_mov_b32_e32 v0, v135
	global_load_lds_dwordx4 v[202:203], off
	s_add_i32 m0, s47, 0x2000
	s_nop 0
	v_lshl_add_u64 v[202:203], s[12:13], 0, v[0:1]
	s_add_u32 s12, s12, 0x40080
	v_lshl_add_u64 v[202:203], v[202:203], 0, s[38:39]
	s_addc_u32 s13, s13, 0
	s_add_i32 s47, s50, s22
	global_load_lds_dwordx4 v[202:203], off
	s_mov_b32 m0, s47
	s_nop 0
	global_load_lds_dwordx4 v134, s[12:13]
	s_add_i32 m0, s47, 0x2000
	s_nop 0
	global_load_lds_dwordx4 v135, s[12:13]
	v_mov_b32_e32 v0, v130
	s_mov_b32 m0, s42
	v_lshl_add_u64 v[202:203], s[10:11], 0, v[0:1]
	v_lshl_add_u64 v[202:203], v[202:203], 0, s[38:39]
	v_mov_b32_e32 v0, v132
	global_load_lds_dwordx4 v[202:203], off
	s_mov_b32 m0, s43
	v_lshl_add_u64 v[202:203], s[10:11], 0, v[0:1]
	v_lshl_add_u64 v[202:203], v[202:203], 0, s[38:39]
	global_load_lds_dwordx4 v[202:203], off
	s_waitcnt vmcnt(8)
	s_waitcnt lgkmcnt(0)
	s_barrier
	s_setprio 1
	s_waitcnt lgkmcnt(0)
	v_mfma_f32_16x16x32_bf16 v[62:65], v[138:141], v[170:173], v[62:65]
	v_mfma_f32_16x16x32_bf16 v[58:61], v[146:149], v[170:173], v[58:61]
	v_mfma_f32_16x16x32_bf16 v[46:49], v[138:141], v[178:181], v[46:49]
	v_mfma_f32_16x16x32_bf16 v[42:45], v[146:149], v[178:181], v[42:45]
	v_mfma_f32_16x16x32_bf16 v[30:33], v[138:141], v[186:189], v[30:33]
	v_mfma_f32_16x16x32_bf16 v[26:29], v[146:149], v[186:189], v[26:29]
	v_mfma_f32_16x16x32_bf16 v[14:17], v[138:141], v[194:197], v[14:17]
	v_mfma_f32_16x16x32_bf16 v[10:13], v[146:149], v[194:197], v[10:13]
	v_mfma_f32_16x16x32_bf16 v[62:65], v[142:145], v[174:177], v[62:65]
	v_mfma_f32_16x16x32_bf16 v[58:61], v[150:153], v[174:177], v[58:61]
	v_mfma_f32_16x16x32_bf16 v[46:49], v[142:145], v[182:185], v[46:49]
	v_mfma_f32_16x16x32_bf16 v[42:45], v[150:153], v[182:185], v[42:45]
	v_mfma_f32_16x16x32_bf16 v[30:33], v[142:145], v[190:193], v[30:33]
	v_mfma_f32_16x16x32_bf16 v[26:29], v[150:153], v[190:193], v[26:29]
	v_mfma_f32_16x16x32_bf16 v[14:17], v[142:145], v[198:201], v[14:17]
	v_mfma_f32_16x16x32_bf16 v[10:13], v[150:153], v[198:201], v[10:13]
	s_setprio 0
	s_setprio 1
	v_mfma_f32_16x16x32_bf16 v[54:57], v[154:157], v[170:173], v[54:57]
	v_mfma_f32_16x16x32_bf16 v[50:53], v[162:165], v[170:173], v[50:53]
	v_mfma_f32_16x16x32_bf16 v[38:41], v[154:157], v[178:181], v[38:41]
	v_mfma_f32_16x16x32_bf16 v[34:37], v[162:165], v[178:181], v[34:37]
	v_mfma_f32_16x16x32_bf16 v[22:25], v[154:157], v[186:189], v[22:25]
	v_mfma_f32_16x16x32_bf16 v[18:21], v[162:165], v[186:189], v[18:21]
	v_mfma_f32_16x16x32_bf16 v[6:9], v[154:157], v[194:197], v[6:9]
	v_mfma_f32_16x16x32_bf16 v[2:5], v[162:165], v[194:197], v[2:5]
	v_mfma_f32_16x16x32_bf16 v[54:57], v[158:161], v[174:177], v[54:57]
	v_mfma_f32_16x16x32_bf16 v[50:53], v[166:169], v[174:177], v[50:53]
	v_mfma_f32_16x16x32_bf16 v[38:41], v[158:161], v[182:185], v[38:41]
	v_mfma_f32_16x16x32_bf16 v[34:37], v[166:169], v[182:185], v[34:37]
	v_mfma_f32_16x16x32_bf16 v[22:25], v[158:161], v[190:193], v[22:25]
	v_mfma_f32_16x16x32_bf16 v[18:21], v[166:169], v[190:193], v[18:21]
	v_mfma_f32_16x16x32_bf16 v[6:9], v[158:161], v[198:201], v[6:9]
	v_mfma_f32_16x16x32_bf16 v[2:5], v[166:169], v[198:201], v[2:5]
	s_setprio 0
	s_barrier
	s_add_i32 s46, s46, 2
	s_add_u32 s2, s2, 0x100
	s_addc_u32 s3, s3, 0
	s_cmp_gt_u32 s46, 13
	s_cbranch_scc0 .LBB0_1681
	s_cmpk_lt_u32 s17, 0x100
	s_cbranch_scc0 .LBB0_1684
	s_barrier

.LBB0_1807:
	s_add_u32 s68, s4, s14
	s_addc_u32 s69, s5, s15
	s_add_u32 s16, s68, 0x100
	s_addc_u32 s17, s69, 0
	s_add_u32 s22, s50, s14
	s_addc_u32 s23, s51, s15
	s_add_i32 s67, 0, 0x10000
	s_cmp_eq_u32 s66, 12
	s_cselect_b32 s17, s5, s17
	s_cselect_b32 s16, s4, s16
	v_add_u32_e32 v0, s67, v126
	s_cselect_b32 s23, s13, s23
	s_cselect_b32 s22, s12, s22
	s_add_i32 s70, 0, 0x14000
	ds_read_b128 v[128:131], v0
	ds_read_b128 v[142:145], v0 offset:1024
	ds_read_b128 v[146:149], v0 offset:2048
	ds_read_b128 v[150:153], v0 offset:3072
	v_add_u32_e32 v0, s70, v126
	ds_read_b128 v[154:157], v0
	ds_read_b128 v[160:163], v0 offset:1024
	ds_read_b128 v[164:167], v0 offset:2048
	ds_read_b128 v[168:171], v0 offset:3072
	v_mov_b32_e32 v0, v122
	ds_read_b128 v[172:175], v127
	ds_read_b128 v[176:179], v127 offset:1024
	ds_read_b128 v[180:183], v127 offset:2048
	ds_read_b128 v[184:187], v127 offset:3072
	ds_read_b128 v[188:191], v127 offset:4096
	ds_read_b128 v[192:195], v127 offset:5120
	ds_read_b128 v[196:199], v127 offset:6144
	ds_read_b128 v[200:203], v127 offset:7168
	s_add_i32 m0, s43, 0xc000
	v_lshl_add_u64 v[132:133], s[68:69], 0, v[0:1]
	v_lshl_add_u64 v[132:133], v[132:133], 0, s[56:57]
	v_mov_b32_e32 v0, v123
	global_load_lds_dwordx4 v[132:133], off
	s_add_i32 m0, s43, 0xe000
	v_lshl_add_u64 v[132:133], s[68:69], 0, v[0:1]
	v_lshl_add_u64 v[132:133], v[132:133], 0, s[56:57]
	global_load_lds_dwordx4 v[132:133], off
	s_waitcnt vmcnt(8)
	s_waitcnt lgkmcnt(0)
	s_barrier
	s_setprio 1
	s_waitcnt lgkmcnt(0)
	v_mfma_f32_16x16x32_bf16 v[138:141], v[128:131], v[172:175], v[138:141]
	v_mfma_f32_16x16x32_bf16 v[132:135], v[146:149], v[172:175], v[134:137]
	v_mfma_f32_16x16x32_bf16 v[110:113], v[128:131], v[180:183], v[110:113]
	v_mfma_f32_16x16x32_bf16 v[106:109], v[146:149], v[180:183], v[106:109]
	v_mfma_f32_16x16x32_bf16 v[94:97], v[128:131], v[188:191], v[94:97]
	v_mfma_f32_16x16x32_bf16 v[90:93], v[146:149], v[188:191], v[90:93]
	v_mfma_f32_16x16x32_bf16 v[78:81], v[128:131], v[196:199], v[78:81]
	v_mfma_f32_16x16x32_bf16 v[74:77], v[146:149], v[196:199], v[74:77]
	v_mfma_f32_16x16x32_bf16 v[138:141], v[142:145], v[176:179], v[138:141]
	v_mfma_f32_16x16x32_bf16 v[132:135], v[150:153], v[176:179], v[132:135]
	v_mfma_f32_16x16x32_bf16 v[110:113], v[142:145], v[184:187], v[110:113]
	v_mfma_f32_16x16x32_bf16 v[106:109], v[150:153], v[184:187], v[106:109]
	v_mfma_f32_16x16x32_bf16 v[94:97], v[142:145], v[192:195], v[94:97]
	v_mfma_f32_16x16x32_bf16 v[90:93], v[150:153], v[192:195], v[90:93]
	v_mfma_f32_16x16x32_bf16 v[78:81], v[142:145], v[200:203], v[78:81]
	v_mfma_f32_16x16x32_bf16 v[74:77], v[150:153], v[200:203], v[74:77]
	s_setprio 0
	s_setprio 1
	v_mfma_f32_16x16x32_bf16 v[118:121], v[154:157], v[172:175], v[118:121]
	v_mfma_f32_16x16x32_bf16 v[114:117], v[164:167], v[172:175], v[114:117]
	v_mfma_f32_16x16x32_bf16 v[102:105], v[154:157], v[180:183], v[102:105]
	v_mfma_f32_16x16x32_bf16 v[98:101], v[164:167], v[180:183], v[98:101]
	v_mfma_f32_16x16x32_bf16 v[86:89], v[154:157], v[188:191], v[86:89]
	v_mfma_f32_16x16x32_bf16 v[82:85], v[164:167], v[188:191], v[82:85]
	v_mfma_f32_16x16x32_bf16 v[70:73], v[154:157], v[196:199], v[70:73]
	v_mfma_f32_16x16x32_bf16 v[66:69], v[164:167], v[196:199], v[66:69]
	v_mfma_f32_16x16x32_bf16 v[118:121], v[160:163], v[176:179], v[118:121]
	v_mfma_f32_16x16x32_bf16 v[114:117], v[168:171], v[176:179], v[114:117]
	v_mfma_f32_16x16x32_bf16 v[102:105], v[160:163], v[184:187], v[102:105]
	v_mfma_f32_16x16x32_bf16 v[98:101], v[168:171], v[184:187], v[98:101]
	v_mfma_f32_16x16x32_bf16 v[86:89], v[160:163], v[192:195], v[86:89]
	v_mfma_f32_16x16x32_bf16 v[82:85], v[168:171], v[192:195], v[82:85]
	v_mfma_f32_16x16x32_bf16 v[70:73], v[160:163], v[200:203], v[70:73]
	v_mfma_f32_16x16x32_bf16 v[66:69], v[168:171], v[200:203], v[66:69]
	s_setprio 0
	s_barrier
	s_add_i32 s67, s67, s42
	ds_read_b128 v[172:175], v127 offset:16384
	ds_read_b128 v[176:179], v127 offset:17408
	ds_read_b128 v[180:183], v127 offset:18432
	ds_read_b128 v[184:187], v127 offset:19456
	ds_read_b128 v[188:191], v127 offset:20480
	ds_read_b128 v[192:195], v127 offset:21504
	ds_read_b128 v[196:199], v127 offset:22528
	ds_read_b128 v[200:203], v127 offset:23552
	s_mov_b32 m0, s67
	s_nop 0
	global_load_lds_dwordx4 v124, s[22:23]
	s_add_i32 m0, s67, 0x2000
	s_add_u32 s68, s22, 0x40000
	global_load_lds_dwordx4 v125, s[22:23]
	s_addc_u32 s69, s23, 0
	s_add_i32 s67, s70, s42
	s_mov_b32 m0, s67
	s_nop 0
	global_load_lds_dwordx4 v124, s[68:69]
	s_add_i32 m0, s67, 0x2000
	s_nop 0
	global_load_lds_dwordx4 v125, s[68:69]
	s_mov_b32 m0, s43
	s_nop 0
	global_load_lds_dwordx4 v122, s[16:17]
	s_mov_b32 m0, s46
	s_nop 0
	global_load_lds_dwordx4 v123, s[16:17]
	s_waitcnt vmcnt(8)
	s_waitcnt lgkmcnt(0)
	s_barrier
	s_setprio 1
	s_waitcnt lgkmcnt(0)
	v_mfma_f32_16x16x32_bf16 v[62:65], v[128:131], v[172:175], v[62:65]
	v_mfma_f32_16x16x32_bf16 v[58:61], v[146:149], v[172:175], v[58:61]
	v_mfma_f32_16x16x32_bf16 v[46:49], v[128:131], v[180:183], v[46:49]
	v_mfma_f32_16x16x32_bf16 v[42:45], v[146:149], v[180:183], v[42:45]
	v_mfma_f32_16x16x32_bf16 v[30:33], v[128:131], v[188:191], v[30:33]
	v_mfma_f32_16x16x32_bf16 v[26:29], v[146:149], v[188:191], v[26:29]
	v_mfma_f32_16x16x32_bf16 v[14:17], v[128:131], v[196:199], v[14:17]
	v_mfma_f32_16x16x32_bf16 v[10:13], v[146:149], v[196:199], v[10:13]
	v_mfma_f32_16x16x32_bf16 v[62:65], v[142:145], v[176:179], v[62:65]
	v_mfma_f32_16x16x32_bf16 v[58:61], v[150:153], v[176:179], v[58:61]
	v_mfma_f32_16x16x32_bf16 v[46:49], v[142:145], v[184:187], v[46:49]
	v_mfma_f32_16x16x32_bf16 v[42:45], v[150:153], v[184:187], v[42:45]
	v_mfma_f32_16x16x32_bf16 v[30:33], v[142:145], v[192:195], v[30:33]
	v_mfma_f32_16x16x32_bf16 v[26:29], v[150:153], v[192:195], v[26:29]
	v_mfma_f32_16x16x32_bf16 v[14:17], v[142:145], v[200:203], v[14:17]
	v_mfma_f32_16x16x32_bf16 v[10:13], v[150:153], v[200:203], v[10:13]
	s_setprio 0
	s_setprio 1
	v_mfma_f32_16x16x32_bf16 v[54:57], v[154:157], v[172:175], v[54:57]
	v_mfma_f32_16x16x32_bf16 v[50:53], v[164:167], v[172:175], v[50:53]
	v_mfma_f32_16x16x32_bf16 v[38:41], v[154:157], v[180:183], v[38:41]
	v_mfma_f32_16x16x32_bf16 v[34:37], v[164:167], v[180:183], v[34:37]
	v_mfma_f32_16x16x32_bf16 v[22:25], v[154:157], v[188:191], v[22:25]
	v_mfma_f32_16x16x32_bf16 v[18:21], v[164:167], v[188:191], v[18:21]
	v_mfma_f32_16x16x32_bf16 v[6:9], v[154:157], v[196:199], v[6:9]
	v_mfma_f32_16x16x32_bf16 v[2:5], v[164:167], v[196:199], v[2:5]
	v_mfma_f32_16x16x32_bf16 v[54:57], v[160:163], v[176:179], v[54:57]
	v_mfma_f32_16x16x32_bf16 v[50:53], v[168:171], v[176:179], v[50:53]
	v_mfma_f32_16x16x32_bf16 v[38:41], v[160:163], v[184:187], v[38:41]
	v_mfma_f32_16x16x32_bf16 v[34:37], v[168:171], v[184:187], v[34:37]
	v_mfma_f32_16x16x32_bf16 v[22:25], v[160:163], v[192:195], v[22:25]
	v_mfma_f32_16x16x32_bf16 v[18:21], v[168:171], v[192:195], v[18:21]
	v_mfma_f32_16x16x32_bf16 v[6:9], v[160:163], v[200:203], v[6:9]
	v_mfma_f32_16x16x32_bf16 v[2:5], v[168:171], v[200:203], v[2:5]
	s_setprio 0
	s_barrier
	s_add_i32 s67, 0, 0x18000
	v_add_u32_e32 v0, s67, v126
	s_add_i32 s70, 0, 0x1c000
	ds_read_b128 v[128:131], v0
	ds_read_b128 v[142:145], v0 offset:1024
	ds_read_b128 v[146:149], v0 offset:2048
	ds_read_b128 v[150:153], v0 offset:3072
	v_add_u32_e32 v0, s70, v126
	ds_read_b128 v[154:157], v0
	ds_read_b128 v[160:163], v0 offset:1024
	ds_read_b128 v[164:167], v0 offset:2048
	ds_read_b128 v[168:171], v0 offset:3072
	s_add_u32 s68, s16, 0x40000
	s_mov_b32 m0, s47
	ds_read_b128 v[172:175], v127 offset:32768
	ds_read_b128 v[176:179], v127 offset:33792
	ds_read_b128 v[180:183], v127 offset:34816
	ds_read_b128 v[184:187], v127 offset:35840
	ds_read_b128 v[188:191], v127 offset:36864
	ds_read_b128 v[192:195], v127 offset:37888
	ds_read_b128 v[196:199], v127 offset:38912
	ds_read_b128 v[200:203], v127 offset:39936
	s_addc_u32 s69, s17, 0
	s_nop 0
	global_load_lds_dwordx4 v122, s[68:69]
	s_mov_b32 m0, s48
	s_nop 0
	global_load_lds_dwordx4 v123, s[68:69]
	s_waitcnt vmcnt(8)
	s_waitcnt lgkmcnt(0)
	s_barrier
	s_setprio 1
	s_waitcnt lgkmcnt(0)
	v_mfma_f32_16x16x32_bf16 v[136:139], v[128:131], v[172:175], v[138:141]
	v_mfma_f32_16x16x32_bf16 v[132:135], v[146:149], v[172:175], v[132:135]
	v_mfma_f32_16x16x32_bf16 v[110:113], v[128:131], v[180:183], v[110:113]
	v_mfma_f32_16x16x32_bf16 v[106:109], v[146:149], v[180:183], v[106:109]
	v_mfma_f32_16x16x32_bf16 v[94:97], v[128:131], v[188:191], v[94:97]
	v_mfma_f32_16x16x32_bf16 v[90:93], v[146:149], v[188:191], v[90:93]
	v_mfma_f32_16x16x32_bf16 v[78:81], v[128:131], v[196:199], v[78:81]
	v_mfma_f32_16x16x32_bf16 v[74:77], v[146:149], v[196:199], v[74:77]
	v_mfma_f32_16x16x32_bf16 v[138:141], v[142:145], v[176:179], v[136:139]
	v_mfma_f32_16x16x32_bf16 v[134:137], v[150:153], v[176:179], v[132:135]
	v_mfma_f32_16x16x32_bf16 v[110:113], v[142:145], v[184:187], v[110:113]
	v_mfma_f32_16x16x32_bf16 v[106:109], v[150:153], v[184:187], v[106:109]
	v_mfma_f32_16x16x32_bf16 v[94:97], v[142:145], v[192:195], v[94:97]
	v_mfma_f32_16x16x32_bf16 v[90:93], v[150:153], v[192:195], v[90:93]
	v_mfma_f32_16x16x32_bf16 v[78:81], v[142:145], v[200:203], v[78:81]
	v_mfma_f32_16x16x32_bf16 v[74:77], v[150:153], v[200:203], v[74:77]
	s_setprio 0
	s_setprio 1
	v_mfma_f32_16x16x32_bf16 v[118:121], v[154:157], v[172:175], v[118:121]
	v_mfma_f32_16x16x32_bf16 v[114:117], v[164:167], v[172:175], v[114:117]
	v_mfma_f32_16x16x32_bf16 v[102:105], v[154:157], v[180:183], v[102:105]
	v_mfma_f32_16x16x32_bf16 v[98:101], v[164:167], v[180:183], v[98:101]
	v_mfma_f32_16x16x32_bf16 v[86:89], v[154:157], v[188:191], v[86:89]
	v_mfma_f32_16x16x32_bf16 v[82:85], v[164:167], v[188:191], v[82:85]
	v_mfma_f32_16x16x32_bf16 v[70:73], v[154:157], v[196:199], v[70:73]
	v_mfma_f32_16x16x32_bf16 v[66:69], v[164:167], v[196:199], v[66:69]
	v_mfma_f32_16x16x32_bf16 v[118:121], v[160:163], v[176:179], v[118:121]
	v_mfma_f32_16x16x32_bf16 v[114:117], v[168:171], v[176:179], v[114:117]
	v_mfma_f32_16x16x32_bf16 v[102:105], v[160:163], v[184:187], v[102:105]
	v_mfma_f32_16x16x32_bf16 v[98:101], v[168:171], v[184:187], v[98:101]
	v_mfma_f32_16x16x32_bf16 v[86:89], v[160:163], v[192:195], v[86:89]
	v_mfma_f32_16x16x32_bf16 v[82:85], v[168:171], v[192:195], v[82:85]
	v_mfma_f32_16x16x32_bf16 v[70:73], v[160:163], v[200:203], v[70:73]
	v_mfma_f32_16x16x32_bf16 v[66:69], v[168:171], v[200:203], v[66:69]
	s_setprio 0
	s_barrier
	v_mov_b32_e32 v0, v124
	ds_read_b128 v[172:175], v127 offset:49152
	ds_read_b128 v[176:179], v127 offset:50176
	ds_read_b128 v[180:183], v127 offset:51200
	ds_read_b128 v[184:187], v127 offset:52224
	ds_read_b128 v[188:191], v127 offset:53248
	ds_read_b128 v[192:195], v127 offset:54272
	ds_read_b128 v[196:199], v127 offset:55296
	ds_read_b128 v[200:203], v127 offset:56320
	s_add_i32 s67, s67, s42
	v_lshl_add_u64 v[132:133], s[22:23], 0, v[0:1]
	v_lshl_add_u64 v[132:133], v[132:133], 0, s[38:39]
	s_mov_b32 m0, s67
	v_mov_b32_e32 v0, v125
	global_load_lds_dwordx4 v[132:133], off
	s_add_i32 m0, s67, 0x2000
	s_nop 0
	v_lshl_add_u64 v[132:133], s[22:23], 0, v[0:1]
	s_add_u32 s22, s22, 0x40080
	v_lshl_add_u64 v[132:133], v[132:133], 0, s[38:39]
	s_addc_u32 s23, s23, 0
	s_add_i32 s67, s70, s42
	global_load_lds_dwordx4 v[132:133], off
	s_mov_b32 m0, s67
	s_nop 0
	global_load_lds_dwordx4 v124, s[22:23]
	s_add_i32 m0, s67, 0x2000
	s_nop 0
	global_load_lds_dwordx4 v125, s[22:23]
	v_mov_b32_e32 v0, v122
	s_mov_b32 m0, s64
	v_lshl_add_u64 v[132:133], s[16:17], 0, v[0:1]
	v_lshl_add_u64 v[132:133], v[132:133], 0, s[38:39]
	v_mov_b32_e32 v0, v123
	global_load_lds_dwordx4 v[132:133], off
	s_mov_b32 m0, s65
	v_lshl_add_u64 v[132:133], s[16:17], 0, v[0:1]
	v_lshl_add_u64 v[132:133], v[132:133], 0, s[38:39]
	global_load_lds_dwordx4 v[132:133], off
	s_waitcnt vmcnt(8)
	s_waitcnt lgkmcnt(0)
	s_barrier
	s_setprio 1
	s_waitcnt lgkmcnt(0)
	v_mfma_f32_16x16x32_bf16 v[62:65], v[128:131], v[172:175], v[62:65]
	v_mfma_f32_16x16x32_bf16 v[58:61], v[146:149], v[172:175], v[58:61]
	v_mfma_f32_16x16x32_bf16 v[46:49], v[128:131], v[180:183], v[46:49]
	v_mfma_f32_16x16x32_bf16 v[42:45], v[146:149], v[180:183], v[42:45]
	v_mfma_f32_16x16x32_bf16 v[30:33], v[128:131], v[188:191], v[30:33]
	v_mfma_f32_16x16x32_bf16 v[26:29], v[146:149], v[188:191], v[26:29]
	v_mfma_f32_16x16x32_bf16 v[14:17], v[128:131], v[196:199], v[14:17]
	v_mfma_f32_16x16x32_bf16 v[10:13], v[146:149], v[196:199], v[10:13]
	v_mfma_f32_16x16x32_bf16 v[62:65], v[142:145], v[176:179], v[62:65]
	v_mfma_f32_16x16x32_bf16 v[58:61], v[150:153], v[176:179], v[58:61]
	v_mfma_f32_16x16x32_bf16 v[46:49], v[142:145], v[184:187], v[46:49]
	v_mfma_f32_16x16x32_bf16 v[42:45], v[150:153], v[184:187], v[42:45]
	v_mfma_f32_16x16x32_bf16 v[30:33], v[142:145], v[192:195], v[30:33]
	v_mfma_f32_16x16x32_bf16 v[26:29], v[150:153], v[192:195], v[26:29]
	v_mfma_f32_16x16x32_bf16 v[14:17], v[142:145], v[200:203], v[14:17]
	v_mfma_f32_16x16x32_bf16 v[10:13], v[150:153], v[200:203], v[10:13]
	s_setprio 0
	s_setprio 1
	v_mfma_f32_16x16x32_bf16 v[54:57], v[154:157], v[172:175], v[54:57]
	v_mfma_f32_16x16x32_bf16 v[50:53], v[164:167], v[172:175], v[50:53]
	v_mfma_f32_16x16x32_bf16 v[38:41], v[154:157], v[180:183], v[38:41]
	v_mfma_f32_16x16x32_bf16 v[34:37], v[164:167], v[180:183], v[34:37]
	v_mfma_f32_16x16x32_bf16 v[22:25], v[154:157], v[188:191], v[22:25]
	v_mfma_f32_16x16x32_bf16 v[18:21], v[164:167], v[188:191], v[18:21]
	v_mfma_f32_16x16x32_bf16 v[6:9], v[154:157], v[196:199], v[6:9]
	v_mfma_f32_16x16x32_bf16 v[2:5], v[164:167], v[196:199], v[2:5]
	v_mfma_f32_16x16x32_bf16 v[54:57], v[160:163], v[176:179], v[54:57]
	v_mfma_f32_16x16x32_bf16 v[50:53], v[168:171], v[176:179], v[50:53]
	v_mfma_f32_16x16x32_bf16 v[38:41], v[160:163], v[184:187], v[38:41]
	v_mfma_f32_16x16x32_bf16 v[34:37], v[168:171], v[184:187], v[34:37]
	v_mfma_f32_16x16x32_bf16 v[22:25], v[160:163], v[192:195], v[22:25]
	v_mfma_f32_16x16x32_bf16 v[18:21], v[168:171], v[192:195], v[18:21]
	v_mfma_f32_16x16x32_bf16 v[6:9], v[160:163], v[200:203], v[6:9]
	v_mfma_f32_16x16x32_bf16 v[2:5], v[168:171], v[200:203], v[2:5]
	s_setprio 0
	s_barrier
	s_add_i32 s66, s66, 2
	s_add_u32 s14, s14, 0x100
	s_addc_u32 s15, s15, 0
	s_cmp_gt_u32 s66, 13
	s_cbranch_scc0 .LBB0_1807
	s_cmpk_lt_u32 s26, 0x100
	s_cbranch_scc0 .LBB0_1810
	s_barrier

.LBB0_1886:
	s_add_u32 s6, s4, 0xfffc0080
	s_addc_u32 s7, s5, -1
	s_add_i32 s47, 0, 0x10000
	s_cmp_eq_u32 s46, 12
	s_cselect_b32 s7, s3, s7
	s_cselect_b32 s6, s2, s6
	v_add_u32_e32 v0, s47, v127
	s_cselect_b32 s11, s40, s43
	s_cselect_b32 s10, s26, s37
	s_add_i32 s50, 0, 0x14000
	ds_read_b128 v[130:133], v0
	ds_read_b128 v[134:137], v0 offset:1024
	ds_read_b128 v[138:141], v0 offset:2048
	ds_read_b128 v[142:145], v0 offset:3072
	v_add_u32_e32 v0, s50, v127
	ds_read_b128 v[146:149], v0
	ds_read_b128 v[158:161], v0 offset:1024
	ds_read_b128 v[162:165], v0 offset:2048
	ds_read_b128 v[166:169], v0 offset:3072
	ds_read_b128 v[170:173], v128
	ds_read_b128 v[174:177], v128 offset:1024
	ds_read_b128 v[178:181], v128 offset:2048
	ds_read_b128 v[182:185], v128 offset:3072
	ds_read_b128 v[186:189], v128 offset:4096
	ds_read_b128 v[190:193], v128 offset:5120
	ds_read_b128 v[194:197], v128 offset:6144
	ds_read_b128 v[198:201], v128 offset:7168
	s_add_i32 m0, s17, 0xc000
	s_nop 0
	global_load_lds_dwordx4 v122, s[4:5]
	s_add_i32 m0, s17, 0xe000
	s_nop 0
	global_load_lds_dwordx4 v123, s[4:5]
	s_waitcnt vmcnt(8)
	s_waitcnt lgkmcnt(0)
	s_barrier
	s_setprio 1
	s_waitcnt lgkmcnt(0)
	v_mfma_f32_16x16x32_bf16 v[154:157], v[130:133], v[170:173], v[154:157]
	v_mfma_f32_16x16x32_bf16 v[150:153], v[138:141], v[170:173], v[150:153]
	v_mfma_f32_16x16x32_bf16 v[110:113], v[130:133], v[178:181], v[110:113]
	v_mfma_f32_16x16x32_bf16 v[106:109], v[138:141], v[178:181], v[106:109]
	v_mfma_f32_16x16x32_bf16 v[94:97], v[130:133], v[186:189], v[94:97]
	v_mfma_f32_16x16x32_bf16 v[90:93], v[138:141], v[186:189], v[90:93]
	v_mfma_f32_16x16x32_bf16 v[78:81], v[130:133], v[194:197], v[78:81]
	v_mfma_f32_16x16x32_bf16 v[74:77], v[138:141], v[194:197], v[74:77]
	v_mfma_f32_16x16x32_bf16 v[154:157], v[134:137], v[174:177], v[154:157]
	v_mfma_f32_16x16x32_bf16 v[150:153], v[142:145], v[174:177], v[150:153]
	v_mfma_f32_16x16x32_bf16 v[110:113], v[134:137], v[182:185], v[110:113]
	v_mfma_f32_16x16x32_bf16 v[106:109], v[142:145], v[182:185], v[106:109]
	v_mfma_f32_16x16x32_bf16 v[94:97], v[134:137], v[190:193], v[94:97]
	v_mfma_f32_16x16x32_bf16 v[90:93], v[142:145], v[190:193], v[90:93]
	v_mfma_f32_16x16x32_bf16 v[78:81], v[134:137], v[198:201], v[78:81]
	v_mfma_f32_16x16x32_bf16 v[74:77], v[142:145], v[198:201], v[74:77]
	s_setprio 0
	s_setprio 1
	v_mfma_f32_16x16x32_bf16 v[118:121], v[146:149], v[170:173], v[118:121]
	v_mfma_f32_16x16x32_bf16 v[114:117], v[162:165], v[170:173], v[114:117]
	v_mfma_f32_16x16x32_bf16 v[102:105], v[146:149], v[178:181], v[102:105]
	v_mfma_f32_16x16x32_bf16 v[98:101], v[162:165], v[178:181], v[98:101]
	v_mfma_f32_16x16x32_bf16 v[86:89], v[146:149], v[186:189], v[86:89]
	v_mfma_f32_16x16x32_bf16 v[82:85], v[162:165], v[186:189], v[82:85]
	v_mfma_f32_16x16x32_bf16 v[70:73], v[146:149], v[194:197], v[70:73]
	v_mfma_f32_16x16x32_bf16 v[66:69], v[162:165], v[194:197], v[66:69]
	v_mfma_f32_16x16x32_bf16 v[118:121], v[158:161], v[174:177], v[118:121]
	v_mfma_f32_16x16x32_bf16 v[114:117], v[166:169], v[174:177], v[114:117]
	v_mfma_f32_16x16x32_bf16 v[102:105], v[158:161], v[182:185], v[102:105]
	v_mfma_f32_16x16x32_bf16 v[98:101], v[166:169], v[182:185], v[98:101]
	v_mfma_f32_16x16x32_bf16 v[86:89], v[158:161], v[190:193], v[86:89]
	v_mfma_f32_16x16x32_bf16 v[82:85], v[166:169], v[190:193], v[82:85]
	v_mfma_f32_16x16x32_bf16 v[70:73], v[158:161], v[198:201], v[70:73]
	v_mfma_f32_16x16x32_bf16 v[66:69], v[166:169], v[198:201], v[66:69]
	s_setprio 0
	s_barrier
	s_add_i32 s47, s47, s16
	ds_read_b128 v[170:173], v128 offset:16384
	ds_read_b128 v[174:177], v128 offset:17408
	ds_read_b128 v[178:181], v128 offset:18432
	ds_read_b128 v[182:185], v128 offset:19456
	ds_read_b128 v[186:189], v128 offset:20480
	ds_read_b128 v[190:193], v128 offset:21504
	ds_read_b128 v[194:197], v128 offset:22528
	ds_read_b128 v[198:201], v128 offset:23552
	s_mov_b32 m0, s47
	s_nop 0
	global_load_lds_dwordx4 v125, s[10:11]
	s_add_i32 m0, s47, 0x2000
	s_add_u32 s48, s10, 0x40000
	global_load_lds_dwordx4 v126, s[10:11]
	s_addc_u32 s49, s11, 0
	s_add_i32 s47, s50, s16
	s_mov_b32 m0, s47
	s_nop 0
	global_load_lds_dwordx4 v125, s[48:49]
	s_add_i32 m0, s47, 0x2000
	s_nop 0
	global_load_lds_dwordx4 v126, s[48:49]
	s_mov_b32 m0, s17
	s_nop 0
	global_load_lds_dwordx4 v122, s[6:7]
	s_mov_b32 m0, s22
	s_nop 0
	global_load_lds_dwordx4 v123, s[6:7]
	s_waitcnt vmcnt(8)
	s_waitcnt lgkmcnt(0)
	s_barrier
	s_setprio 1
	s_waitcnt lgkmcnt(0)
	v_mfma_f32_16x16x32_bf16 v[62:65], v[130:133], v[170:173], v[62:65]
	v_mfma_f32_16x16x32_bf16 v[58:61], v[138:141], v[170:173], v[58:61]
	v_mfma_f32_16x16x32_bf16 v[46:49], v[130:133], v[178:181], v[46:49]
	v_mfma_f32_16x16x32_bf16 v[42:45], v[138:141], v[178:181], v[42:45]
	v_mfma_f32_16x16x32_bf16 v[30:33], v[130:133], v[186:189], v[30:33]
	v_mfma_f32_16x16x32_bf16 v[26:29], v[138:141], v[186:189], v[26:29]
	v_mfma_f32_16x16x32_bf16 v[14:17], v[130:133], v[194:197], v[14:17]
	v_mfma_f32_16x16x32_bf16 v[10:13], v[138:141], v[194:197], v[10:13]
	v_mfma_f32_16x16x32_bf16 v[62:65], v[134:137], v[174:177], v[62:65]
	v_mfma_f32_16x16x32_bf16 v[58:61], v[142:145], v[174:177], v[58:61]
	v_mfma_f32_16x16x32_bf16 v[46:49], v[134:137], v[182:185], v[46:49]
	v_mfma_f32_16x16x32_bf16 v[42:45], v[142:145], v[182:185], v[42:45]
	v_mfma_f32_16x16x32_bf16 v[30:33], v[134:137], v[190:193], v[30:33]
	v_mfma_f32_16x16x32_bf16 v[26:29], v[142:145], v[190:193], v[26:29]
	v_mfma_f32_16x16x32_bf16 v[14:17], v[134:137], v[198:201], v[14:17]
	v_mfma_f32_16x16x32_bf16 v[10:13], v[142:145], v[198:201], v[10:13]
	s_setprio 0
	s_setprio 1
	v_mfma_f32_16x16x32_bf16 v[54:57], v[146:149], v[170:173], v[54:57]
	v_mfma_f32_16x16x32_bf16 v[50:53], v[162:165], v[170:173], v[50:53]
	v_mfma_f32_16x16x32_bf16 v[38:41], v[146:149], v[178:181], v[38:41]
	v_mfma_f32_16x16x32_bf16 v[34:37], v[162:165], v[178:181], v[34:37]
	v_mfma_f32_16x16x32_bf16 v[22:25], v[146:149], v[186:189], v[22:25]
	v_mfma_f32_16x16x32_bf16 v[18:21], v[162:165], v[186:189], v[18:21]
	v_mfma_f32_16x16x32_bf16 v[6:9], v[146:149], v[194:197], v[6:9]
	v_mfma_f32_16x16x32_bf16 v[2:5], v[162:165], v[194:197], v[2:5]
	v_mfma_f32_16x16x32_bf16 v[54:57], v[158:161], v[174:177], v[54:57]
	v_mfma_f32_16x16x32_bf16 v[50:53], v[166:169], v[174:177], v[50:53]
	v_mfma_f32_16x16x32_bf16 v[38:41], v[158:161], v[182:185], v[38:41]
	v_mfma_f32_16x16x32_bf16 v[34:37], v[166:169], v[182:185], v[34:37]
	v_mfma_f32_16x16x32_bf16 v[22:25], v[158:161], v[190:193], v[22:25]
	v_mfma_f32_16x16x32_bf16 v[18:21], v[166:169], v[190:193], v[18:21]
	v_mfma_f32_16x16x32_bf16 v[6:9], v[158:161], v[198:201], v[6:9]
	v_mfma_f32_16x16x32_bf16 v[2:5], v[166:169], v[198:201], v[2:5]
	s_setprio 0
	s_barrier
	s_add_i32 s47, 0, 0x18000
	v_add_u32_e32 v0, s47, v127
	s_add_i32 s50, 0, 0x1c000
	ds_read_b128 v[130:133], v0
	ds_read_b128 v[134:137], v0 offset:1024
	ds_read_b128 v[138:141], v0 offset:2048
	ds_read_b128 v[142:145], v0 offset:3072
	v_add_u32_e32 v0, s50, v127
	ds_read_b128 v[146:149], v0
	ds_read_b128 v[158:161], v0 offset:1024
	ds_read_b128 v[162:165], v0 offset:2048
	ds_read_b128 v[166:169], v0 offset:3072
	s_add_u32 s48, s6, 0x40000
	s_mov_b32 m0, s23
	ds_read_b128 v[170:173], v128 offset:32768
	ds_read_b128 v[174:177], v128 offset:33792
	ds_read_b128 v[178:181], v128 offset:34816
	ds_read_b128 v[182:185], v128 offset:35840
	ds_read_b128 v[186:189], v128 offset:36864
	ds_read_b128 v[190:193], v128 offset:37888
	ds_read_b128 v[194:197], v128 offset:38912
	ds_read_b128 v[198:201], v128 offset:39936
	s_addc_u32 s49, s7, 0
	s_nop 0
	global_load_lds_dwordx4 v122, s[48:49]
	s_mov_b32 m0, s24
	s_nop 0
	global_load_lds_dwordx4 v123, s[48:49]
	s_waitcnt vmcnt(8)
	s_waitcnt lgkmcnt(0)
	s_barrier
	s_setprio 1
	s_waitcnt lgkmcnt(0)
	v_mfma_f32_16x16x32_bf16 v[154:157], v[130:133], v[170:173], v[154:157]
	v_mfma_f32_16x16x32_bf16 v[150:153], v[138:141], v[170:173], v[150:153]
	v_mfma_f32_16x16x32_bf16 v[110:113], v[130:133], v[178:181], v[110:113]
	v_mfma_f32_16x16x32_bf16 v[106:109], v[138:141], v[178:181], v[106:109]
	v_mfma_f32_16x16x32_bf16 v[94:97], v[130:133], v[186:189], v[94:97]
	v_mfma_f32_16x16x32_bf16 v[90:93], v[138:141], v[186:189], v[90:93]
	v_mfma_f32_16x16x32_bf16 v[78:81], v[130:133], v[194:197], v[78:81]
	v_mfma_f32_16x16x32_bf16 v[74:77], v[138:141], v[194:197], v[74:77]
	v_mfma_f32_16x16x32_bf16 v[154:157], v[134:137], v[174:177], v[154:157]
	v_mfma_f32_16x16x32_bf16 v[150:153], v[142:145], v[174:177], v[150:153]
	v_mfma_f32_16x16x32_bf16 v[110:113], v[134:137], v[182:185], v[110:113]
	v_mfma_f32_16x16x32_bf16 v[106:109], v[142:145], v[182:185], v[106:109]
	v_mfma_f32_16x16x32_bf16 v[94:97], v[134:137], v[190:193], v[94:97]
	v_mfma_f32_16x16x32_bf16 v[90:93], v[142:145], v[190:193], v[90:93]
	v_mfma_f32_16x16x32_bf16 v[78:81], v[134:137], v[198:201], v[78:81]
	v_mfma_f32_16x16x32_bf16 v[74:77], v[142:145], v[198:201], v[74:77]
	s_setprio 0
	s_setprio 1
	v_mfma_f32_16x16x32_bf16 v[118:121], v[146:149], v[170:173], v[118:121]
	v_mfma_f32_16x16x32_bf16 v[114:117], v[162:165], v[170:173], v[114:117]
	v_mfma_f32_16x16x32_bf16 v[102:105], v[146:149], v[178:181], v[102:105]
	v_mfma_f32_16x16x32_bf16 v[98:101], v[162:165], v[178:181], v[98:101]
	v_mfma_f32_16x16x32_bf16 v[86:89], v[146:149], v[186:189], v[86:89]
	v_mfma_f32_16x16x32_bf16 v[82:85], v[162:165], v[186:189], v[82:85]
	v_mfma_f32_16x16x32_bf16 v[70:73], v[146:149], v[194:197], v[70:73]
	v_mfma_f32_16x16x32_bf16 v[66:69], v[162:165], v[194:197], v[66:69]
	v_mfma_f32_16x16x32_bf16 v[118:121], v[158:161], v[174:177], v[118:121]
	v_mfma_f32_16x16x32_bf16 v[114:117], v[166:169], v[174:177], v[114:117]
	v_mfma_f32_16x16x32_bf16 v[102:105], v[158:161], v[182:185], v[102:105]
	v_mfma_f32_16x16x32_bf16 v[98:101], v[166:169], v[182:185], v[98:101]
	v_mfma_f32_16x16x32_bf16 v[86:89], v[158:161], v[190:193], v[86:89]
	v_mfma_f32_16x16x32_bf16 v[82:85], v[166:169], v[190:193], v[82:85]
	v_mfma_f32_16x16x32_bf16 v[70:73], v[158:161], v[198:201], v[70:73]
	v_mfma_f32_16x16x32_bf16 v[66:69], v[166:169], v[198:201], v[66:69]
	s_setprio 0
	s_barrier
	v_mov_b32_e32 v0, v125
	ds_read_b128 v[170:173], v128 offset:49152
	ds_read_b128 v[174:177], v128 offset:50176
	ds_read_b128 v[178:181], v128 offset:51200
	ds_read_b128 v[182:185], v128 offset:52224
	ds_read_b128 v[186:189], v128 offset:53248
	ds_read_b128 v[190:193], v128 offset:54272
	ds_read_b128 v[194:197], v128 offset:55296
	ds_read_b128 v[198:201], v128 offset:56320
	s_add_i32 s47, s47, s16
	v_lshl_add_u64 v[202:203], s[10:11], 0, v[0:1]
	v_lshl_add_u64 v[202:203], v[202:203], 0, s[38:39]
	s_mov_b32 m0, s47
	v_mov_b32_e32 v0, v126
	global_load_lds_dwordx4 v[202:203], off
	s_add_i32 m0, s47, 0x2000
	s_nop 0
	v_lshl_add_u64 v[202:203], s[10:11], 0, v[0:1]
	s_add_u32 s10, s10, 0x40080
	v_lshl_add_u64 v[202:203], v[202:203], 0, s[38:39]
	s_addc_u32 s11, s11, 0
	s_add_i32 s47, s50, s16
	global_load_lds_dwordx4 v[202:203], off
	s_mov_b32 m0, s47
	s_nop 0
	global_load_lds_dwordx4 v125, s[10:11]
	s_add_i32 m0, s47, 0x2000
	s_nop 0
	global_load_lds_dwordx4 v126, s[10:11]
	v_mov_b32_e32 v0, v122
	s_mov_b32 m0, s41
	v_lshl_add_u64 v[202:203], s[6:7], 0, v[0:1]
	v_lshl_add_u64 v[202:203], v[202:203], 0, s[38:39]
	v_mov_b32_e32 v0, v123
	global_load_lds_dwordx4 v[202:203], off
	s_mov_b32 m0, s42
	v_lshl_add_u64 v[202:203], s[6:7], 0, v[0:1]
	v_lshl_add_u64 v[202:203], v[202:203], 0, s[38:39]
	global_load_lds_dwordx4 v[202:203], off
	s_waitcnt vmcnt(8)
	s_waitcnt lgkmcnt(0)
	s_barrier
	s_setprio 1
	s_waitcnt lgkmcnt(0)
	v_mfma_f32_16x16x32_bf16 v[62:65], v[130:133], v[170:173], v[62:65]
	v_mfma_f32_16x16x32_bf16 v[58:61], v[138:141], v[170:173], v[58:61]
	v_mfma_f32_16x16x32_bf16 v[46:49], v[130:133], v[178:181], v[46:49]
	v_mfma_f32_16x16x32_bf16 v[42:45], v[138:141], v[178:181], v[42:45]
	v_mfma_f32_16x16x32_bf16 v[30:33], v[130:133], v[186:189], v[30:33]
	v_mfma_f32_16x16x32_bf16 v[26:29], v[138:141], v[186:189], v[26:29]
	v_mfma_f32_16x16x32_bf16 v[14:17], v[130:133], v[194:197], v[14:17]
	v_mfma_f32_16x16x32_bf16 v[10:13], v[138:141], v[194:197], v[10:13]
	v_mfma_f32_16x16x32_bf16 v[62:65], v[134:137], v[174:177], v[62:65]
	v_mfma_f32_16x16x32_bf16 v[58:61], v[142:145], v[174:177], v[58:61]
	v_mfma_f32_16x16x32_bf16 v[46:49], v[134:137], v[182:185], v[46:49]
	v_mfma_f32_16x16x32_bf16 v[42:45], v[142:145], v[182:185], v[42:45]
	v_mfma_f32_16x16x32_bf16 v[30:33], v[134:137], v[190:193], v[30:33]
	v_mfma_f32_16x16x32_bf16 v[26:29], v[142:145], v[190:193], v[26:29]
	v_mfma_f32_16x16x32_bf16 v[14:17], v[134:137], v[198:201], v[14:17]
	v_mfma_f32_16x16x32_bf16 v[10:13], v[142:145], v[198:201], v[10:13]
	s_setprio 0
	s_setprio 1
	v_mfma_f32_16x16x32_bf16 v[54:57], v[146:149], v[170:173], v[54:57]
	v_mfma_f32_16x16x32_bf16 v[50:53], v[162:165], v[170:173], v[50:53]
	v_mfma_f32_16x16x32_bf16 v[38:41], v[146:149], v[178:181], v[38:41]
	v_mfma_f32_16x16x32_bf16 v[34:37], v[162:165], v[178:181], v[34:37]
	v_mfma_f32_16x16x32_bf16 v[22:25], v[146:149], v[186:189], v[22:25]
	v_mfma_f32_16x16x32_bf16 v[18:21], v[162:165], v[186:189], v[18:21]
	v_mfma_f32_16x16x32_bf16 v[6:9], v[146:149], v[194:197], v[6:9]
	v_mfma_f32_16x16x32_bf16 v[2:5], v[162:165], v[194:197], v[2:5]
	v_mfma_f32_16x16x32_bf16 v[54:57], v[158:161], v[174:177], v[54:57]
	v_mfma_f32_16x16x32_bf16 v[50:53], v[166:169], v[174:177], v[50:53]
	v_mfma_f32_16x16x32_bf16 v[38:41], v[158:161], v[182:185], v[38:41]
	v_mfma_f32_16x16x32_bf16 v[34:37], v[166:169], v[182:185], v[34:37]
	v_mfma_f32_16x16x32_bf16 v[22:25], v[158:161], v[190:193], v[22:25]
	v_mfma_f32_16x16x32_bf16 v[18:21], v[166:169], v[190:193], v[18:21]
	v_mfma_f32_16x16x32_bf16 v[6:9], v[158:161], v[198:201], v[6:9]
	v_mfma_f32_16x16x32_bf16 v[2:5], v[166:169], v[198:201], v[2:5]
	s_setprio 0
	s_barrier
	s_add_i32 s46, s46, 2
	s_add_u32 s4, s4, 0x100
	s_addc_u32 s5, s5, 0
	s_add_u32 s37, s37, 0x100
	s_addc_u32 s43, s43, 0
	s_cmp_gt_u32 s46, 13
	s_cbranch_scc0 .LBB0_1886
	s_cmpk_lt_u32 s14, 0x100
	s_cbranch_scc0 .LBB0_1889
	s_barrier
